# cache-policy lever: residual loads of the three EpiResid epilogues marked nt (read-once streams), otherwise identical to v13
# speedup vs baseline: 1.0047x; 1.0047x over previous
;     __device__ __forceinline__ void operator()(const f32x4 (&acc)[2][2][4][2], const Unit& u, int wr, int wc, int fr, int fq) const {
;         const int row0 = u.pm * BM + wr * 64 + fr, col0 = u.pn * BM + wc * 32 + 4 * fq;
;         const float* rbase = (u.pm * BM < SEQ_P) ? resA : (resB - (size_t)SEQ_P * ldc);
;         f32x4 wv[2][2];
;         if (xn) {
; #pragma unroll
;             for (int bj = 0; bj < 2; ++bj)
; #pragma unroll
;                 for (int n = 0; n < 2; ++n) wv[bj][n] = *(const f32x4*)(wn + col0 + bj * HALF + n * 16);
;         }
; #pragma unroll
;         for (int ai = 0; ai < 2; ++ai)
; #pragma unroll
;             for (int m = 0; m < 4; ++m) {
;                 const int row = row0 + ai * HALF + m * 16;
;                 const size_t off = (size_t)row * ldc + col0;
;                 float q = 0.f;
; #pragma unroll
;                 for (int bj = 0; bj < 2; ++bj)
; #pragma unroll
;                     for (int n = 0; n < 2; ++n) {
;                         const f32x4 rv = *(const f32x4*)(rbase + off + bj * HALF + n * 16);
;                         const f32x4 v = rv + acc[ai][bj][m][n] * scale;
;                         if (out) *(f32x4*)(out + off + bj * HALF + n * 16) = v;
;                         if (xn) { q += (v.x * v.x + v.y * v.y) + (v.z * v.z + v.w * v.w); const f32x4 o = v * wv[bj][n];
;                             u32x2 p; p.x = pk2(o.x, o.y); p.y = pk2(o.z, o.w); *(u32x2*)(xn + off + bj * HALF + n * 16) = p; }
;                     }
;                 if (xn) { q += __shfl_xor(q, 16); q += __shfl_xor(q, 32); if (fq == 0) (void)__hip_atomic_fetch_add(ss + row, q, __ATOMIC_RELAXED, __HIP_MEMORY_SCOPE_AGENT); }
.LBB0_312:
	v_lshl_add_u32 v212, s62, 8, v168
	v_lshl_or_b32 v214, s61, 8, v170
	v_and_b32_e32 v243, 8, v174
	v_mov_b32_e32 v213, 0
	v_cmp_eq_u32_e64 s[34:35], 0, v243
	v_lshlrev_b32_e32 v175, 1, v243
	v_add_u32_e32 v216, v214, v175
	v_sub_u32_e32 v234, 16, v175
	v_add_u32_e32 v234, v214, v234
	v_mov_b32_e32 v214, v216
	v_mov_b32_e32 v216, v234
	v_mov_b32_e32 v215, 0
	v_mov_b32_e32 v217, 0
	v_sub_u32_e32 v210, v212, v243
	v_mov_b32_e32 v211, 0
	v_lshlrev_b64 v[208:209], 11, v[210:211]
	v_add_u32_e32 v210, 8, v210
	v_lshlrev_b64 v[210:211], 11, v[210:211]
	s_cmp_lt_i32 s62, 32
	s_cselect_b32 s31, s2, s54
	s_cselect_b32 s30, s33, s53
	v_lshl_add_u64 v[208:209], v[208:209], 0, v[214:215]
	v_lshl_add_u64 v[210:211], v[210:211], 0, v[216:217]
	v_lshl_add_u64 v[164:165], v[208:209], 2, s[30:31]
	v_lshl_add_u64 v[200:201], v[210:211], 2, s[30:31]
	v_lshl_add_u64 v[202:203], v[214:215], 2, s[10:11]
	v_lshl_add_u64 v[204:205], v[216:217], 2, s[10:11]
	global_load_dwordx4 v[64:67], v[202:203], off
	global_load_dwordx4 v[72:75], v[202:203], off offset:512
	global_load_dwordx4 v[80:83], v[204:205], off
	global_load_dwordx4 v[84:87], v[204:205], off offset:512
	global_load_dwordx4 v[156:159], v[164:165], off nt
	global_load_dwordx4 v[160:163], v[164:165], off offset:512 nt
	global_load_dwordx4 v[176:179], v[200:201], off nt
	global_load_dwordx4 v[180:183], v[200:201], off offset:512 nt
	s_mov_b64 vcc, 0x20000
	v_lshl_add_u64 v[164:165], v[164:165], 0, vcc
	v_lshl_add_u64 v[200:201], v[200:201], 0, vcc
	global_load_dwordx4 v[184:187], v[164:165], off nt
	global_load_dwordx4 v[188:191], v[164:165], off offset:512 nt
	global_load_dwordx4 v[192:195], v[200:201], off nt
	global_load_dwordx4 v[196:199], v[200:201], off offset:512 nt
	s_mov_b64 vcc, 0x20000
	v_lshl_add_u64 v[164:165], v[164:165], 0, vcc
	v_lshl_add_u64 v[200:201], v[200:201], 0, vcc
	v_lshl_add_u64 v[218:219], v[208:209], 2, s[8:9]
	v_lshl_add_u64 v[220:221], v[210:211], 2, s[8:9]
	v_lshl_add_u64 v[202:203], v[208:209], 1, s[14:15]
	v_lshl_add_u64 v[204:205], v[210:211], 1, s[14:15]
	v_lshl_add_u64 v[206:207], v[212:213], 2, s[18:19]
	v_xor_b32_e32 v235, 16, v174
	v_xor_b32_e32 v240, 32, v174
	v_lshlrev_b32_e32 v235, 2, v235
	v_lshlrev_b32_e32 v240, 2, v240
	v_mov_b32_dpp v236, v136 row_ror:8 row_mask:0xf bank_mask:0xf
	v_mov_b32_dpp v237, v137 row_ror:8 row_mask:0xf bank_mask:0xf
	v_mov_b32_dpp v238, v138 row_ror:8 row_mask:0xf bank_mask:0xf
	v_mov_b32_dpp v239, v139 row_ror:8 row_mask:0xf bank_mask:0xf
	v_cndmask_b32_e64 v136, v236, v140, s[34:35]
	v_cndmask_b32_e64 v137, v237, v141, s[34:35]
	v_cndmask_b32_e64 v138, v238, v142, s[34:35]
	v_cndmask_b32_e64 v139, v239, v143, s[34:35]
	v_cndmask_b32_e64 v140, v140, v236, s[34:35]
	v_cndmask_b32_e64 v141, v141, v237, s[34:35]
	v_cndmask_b32_e64 v142, v142, v238, s[34:35]
	v_cndmask_b32_e64 v143, v143, v239, s[34:35]
	v_mov_b32_dpp v236, v128 row_ror:8 row_mask:0xf bank_mask:0xf
	v_mov_b32_dpp v237, v129 row_ror:8 row_mask:0xf bank_mask:0xf
	v_mov_b32_dpp v238, v130 row_ror:8 row_mask:0xf bank_mask:0xf
	v_mov_b32_dpp v239, v131 row_ror:8 row_mask:0xf bank_mask:0xf
	v_cndmask_b32_e64 v128, v236, v132, s[34:35]
	v_cndmask_b32_e64 v129, v237, v133, s[34:35]
	v_cndmask_b32_e64 v130, v238, v134, s[34:35]
	v_cndmask_b32_e64 v131, v239, v135, s[34:35]
	v_cndmask_b32_e64 v132, v132, v236, s[34:35]
	v_cndmask_b32_e64 v133, v133, v237, s[34:35]
	v_cndmask_b32_e64 v134, v134, v238, s[34:35]
	v_cndmask_b32_e64 v135, v135, v239, s[34:35]
	s_waitcnt vmcnt(4)
	v_pk_fma_f32 v[138:139], v[138:139], 0.5, v[158:159] op_sel_hi:[1,0,1]
	v_pk_fma_f32 v[136:137], v[136:137], 0.5, v[156:157] op_sel_hi:[1,0,1]
	global_store_dwordx4 v[218:219], v[136:139], off
	v_pk_mul_f32 v[224:225], v[64:65], v[136:137]
	v_pk_mul_f32 v[226:227], v[66:67], v[138:139]
	v_mul_f32_e32 v175, v136, v136
	v_add_u32_e32 v224, 0x8000, v224
	v_add_u32_e32 v225, 0x8000, v225
	v_add_u32_e32 v226, 0x8000, v226
	v_add_u32_e32 v227, 0x8000, v227
	v_fmac_f32_e32 v175, v137, v137
	v_fmac_f32_e32 v175, v138, v138
	v_fmac_f32_e32 v175, v139, v139
	v_perm_b32 v222, v225, v224, s58
	v_perm_b32 v223, v227, v226, s58
	global_store_dwordx2 v[202:203], v[222:223], off
	v_pk_fma_f32 v[130:131], v[130:131], 0.5, v[162:163] op_sel_hi:[1,0,1]
	v_pk_fma_f32 v[128:129], v[128:129], 0.5, v[160:161] op_sel_hi:[1,0,1]
	global_store_dwordx4 v[218:219], v[128:131], off offset:512
	v_pk_mul_f32 v[228:229], v[72:73], v[128:129]
	v_pk_mul_f32 v[230:231], v[74:75], v[130:131]
	v_fmac_f32_e32 v175, v128, v128
	v_add_u32_e32 v228, 0x8000, v228
	v_add_u32_e32 v229, 0x8000, v229
	v_add_u32_e32 v230, 0x8000, v230
	v_add_u32_e32 v231, 0x8000, v231
	v_fmac_f32_e32 v175, v129, v129
	v_fmac_f32_e32 v175, v130, v130
	v_fmac_f32_e32 v175, v131, v131
	v_perm_b32 v232, v229, v228, s58
	v_perm_b32 v233, v231, v230, s58
	global_store_dwordx2 v[202:203], v[232:233], off offset:256
	v_pk_fma_f32 v[142:143], v[142:143], 0.5, v[178:179] op_sel_hi:[1,0,1]
	v_pk_fma_f32 v[140:141], v[140:141], 0.5, v[176:177] op_sel_hi:[1,0,1]
	global_store_dwordx4 v[220:221], v[140:143], off
	v_pk_mul_f32 v[224:225], v[80:81], v[140:141]
	v_pk_mul_f32 v[226:227], v[82:83], v[142:143]
	v_mul_f32_e32 v234, v140, v140
	v_add_u32_e32 v224, 0x8000, v224
	v_add_u32_e32 v225, 0x8000, v225
	v_add_u32_e32 v226, 0x8000, v226
	v_add_u32_e32 v227, 0x8000, v227
	v_fmac_f32_e32 v234, v141, v141
	v_fmac_f32_e32 v234, v142, v142
	v_fmac_f32_e32 v234, v143, v143
	v_perm_b32 v222, v225, v224, s58
	v_perm_b32 v223, v227, v226, s58
	global_store_dwordx2 v[204:205], v[222:223], off
	v_pk_fma_f32 v[134:135], v[134:135], 0.5, v[182:183] op_sel_hi:[1,0,1]
;     __device__ __forceinline__ void operator()(const f32x4 (&acc)[2][2][4][2], const Unit& u, int wr, int wc, int fr, int fq) const {
;     ...
; #pragma unroll
;         for (int ai = 0; ai < 2; ++ai)
; #pragma unroll
;             for (int m = 0; m < 4; ++m) {
;                 const int row = row0 + ai * HALF + m * 16;
;                 const size_t off = (size_t)row * ldc + col0;
;                 float q = 0.f;
; #pragma unroll
;                 for (int bj = 0; bj < 2; ++bj)
; #pragma unroll
;                     for (int n = 0; n < 2; ++n) {
;                         const f32x4 rv = *(const f32x4*)(rbase + off + bj * HALF + n * 16);
;                         const f32x4 v = rv + acc[ai][bj][m][n] * scale;
;                         if (out) *(f32x4*)(out + off + bj * HALF + n * 16) = v;
;                         if (xn) { q += (v.x * v.x + v.y * v.y) + (v.z * v.z + v.w * v.w); const f32x4 o = v * wv[bj][n];
;                             u32x2 p; p.x = pk2(o.x, o.y); p.y = pk2(o.z, o.w); *(u32x2*)(xn + off + bj * HALF + n * 16) = p; }
;                     }
;                 if (xn) { q += __shfl_xor(q, 16); q += __shfl_xor(q, 32); if (fq == 0) (void)__hip_atomic_fetch_add(ss + row, q, __ATOMIC_RELAXED, __HIP_MEMORY_SCOPE_AGENT); }
	v_pk_fma_f32 v[132:133], v[132:133], 0.5, v[180:181] op_sel_hi:[1,0,1]
	global_store_dwordx4 v[220:221], v[132:135], off offset:512
	v_pk_mul_f32 v[228:229], v[84:85], v[132:133]
	v_pk_mul_f32 v[230:231], v[86:87], v[134:135]
	v_fmac_f32_e32 v234, v132, v132
	v_add_u32_e32 v228, 0x8000, v228
	v_add_u32_e32 v229, 0x8000, v229
	v_add_u32_e32 v230, 0x8000, v230
	v_add_u32_e32 v231, 0x8000, v231
	v_fmac_f32_e32 v234, v133, v133
	v_fmac_f32_e32 v234, v134, v134
	v_fmac_f32_e32 v234, v135, v135
	v_perm_b32 v232, v229, v228, s58
	v_perm_b32 v233, v231, v230, s58
	global_store_dwordx2 v[204:205], v[232:233], off offset:256
	s_nop 1
	v_mov_b32_dpp v241, v175 row_ror:8 row_mask:0xf bank_mask:0xf
	v_mov_b32_dpp v242, v234 row_ror:8 row_mask:0xf bank_mask:0xf
	v_add_f32_e32 v175, v175, v241
	v_add_f32_e32 v234, v234, v242
	v_cndmask_b32_e64 v175, v234, v175, s[34:35]
	s_nop 0
	ds_bpermute_b32 v241, v235, v175
	global_load_dwordx4 v[156:159], v[164:165], off nt
	global_load_dwordx4 v[160:163], v[164:165], off offset:512 nt
	global_load_dwordx4 v[176:179], v[200:201], off nt
	global_load_dwordx4 v[180:183], v[200:201], off offset:512 nt
	s_mov_b64 vcc, 0x20000
	v_lshl_add_u64 v[164:165], v[164:165], 0, vcc
	v_lshl_add_u64 v[200:201], v[200:201], 0, vcc
	s_mov_b64 vcc, 0x20000
	v_lshl_add_u64 v[218:219], v[218:219], 0, vcc
	v_lshl_add_u64 v[220:221], v[220:221], 0, vcc
	s_mov_b64 vcc, 0x10000
	v_lshl_add_u64 v[202:203], v[202:203], 0, vcc
	v_lshl_add_u64 v[204:205], v[204:205], 0, vcc
	s_waitcnt lgkmcnt(0)
	v_add_f32_e32 v175, v175, v241
	s_nop 0
	ds_bpermute_b32 v242, v240, v175
	s_waitcnt lgkmcnt(0)
	v_add_f32_e32 v175, v175, v242
	s_mov_b64 exec, s[0:1]
	global_atomic_add_f32 v[206:207], v175, off
	s_mov_b64 exec, -1
	s_mov_b64 vcc, 64
	v_lshl_add_u64 v[206:207], v[206:207], 0, vcc
	v_mov_b32_dpp v236, v120 row_ror:8 row_mask:0xf bank_mask:0xf
	v_mov_b32_dpp v237, v121 row_ror:8 row_mask:0xf bank_mask:0xf
	v_mov_b32_dpp v238, v122 row_ror:8 row_mask:0xf bank_mask:0xf
	v_mov_b32_dpp v239, v123 row_ror:8 row_mask:0xf bank_mask:0xf
	v_cndmask_b32_e64 v120, v236, v124, s[34:35]
	v_cndmask_b32_e64 v121, v237, v125, s[34:35]
	v_cndmask_b32_e64 v122, v238, v126, s[34:35]
	v_cndmask_b32_e64 v123, v239, v127, s[34:35]
	v_cndmask_b32_e64 v124, v124, v236, s[34:35]
	v_cndmask_b32_e64 v125, v125, v237, s[34:35]
	v_cndmask_b32_e64 v126, v126, v238, s[34:35]
	v_cndmask_b32_e64 v127, v127, v239, s[34:35]
	v_mov_b32_dpp v236, v112 row_ror:8 row_mask:0xf bank_mask:0xf
	v_mov_b32_dpp v237, v113 row_ror:8 row_mask:0xf bank_mask:0xf
	v_mov_b32_dpp v238, v114 row_ror:8 row_mask:0xf bank_mask:0xf
	v_mov_b32_dpp v239, v115 row_ror:8 row_mask:0xf bank_mask:0xf
	v_cndmask_b32_e64 v112, v236, v116, s[34:35]
	v_cndmask_b32_e64 v113, v237, v117, s[34:35]
	v_cndmask_b32_e64 v114, v238, v118, s[34:35]
	v_cndmask_b32_e64 v115, v239, v119, s[34:35]
	v_cndmask_b32_e64 v116, v116, v236, s[34:35]
	v_cndmask_b32_e64 v117, v117, v237, s[34:35]
	v_cndmask_b32_e64 v118, v118, v238, s[34:35]
	v_cndmask_b32_e64 v119, v119, v239, s[34:35]
	s_waitcnt vmcnt(13)
	v_pk_fma_f32 v[122:123], v[122:123], 0.5, v[186:187] op_sel_hi:[1,0,1]
	v_pk_fma_f32 v[120:121], v[120:121], 0.5, v[184:185] op_sel_hi:[1,0,1]
	global_store_dwordx4 v[218:219], v[120:123], off
	v_pk_mul_f32 v[224:225], v[64:65], v[120:121]
	v_pk_mul_f32 v[226:227], v[66:67], v[122:123]
	v_mul_f32_e32 v175, v120, v120
	v_add_u32_e32 v224, 0x8000, v224
	v_add_u32_e32 v225, 0x8000, v225
	v_add_u32_e32 v226, 0x8000, v226
	v_add_u32_e32 v227, 0x8000, v227
	v_fmac_f32_e32 v175, v121, v121
	v_fmac_f32_e32 v175, v122, v122
	v_fmac_f32_e32 v175, v123, v123
	v_perm_b32 v222, v225, v224, s58
	v_perm_b32 v223, v227, v226, s58
	global_store_dwordx2 v[202:203], v[222:223], off
	v_pk_fma_f32 v[114:115], v[114:115], 0.5, v[190:191] op_sel_hi:[1,0,1]
	v_pk_fma_f32 v[112:113], v[112:113], 0.5, v[188:189] op_sel_hi:[1,0,1]
	global_store_dwordx4 v[218:219], v[112:115], off offset:512
	v_pk_mul_f32 v[228:229], v[72:73], v[112:113]
	v_pk_mul_f32 v[230:231], v[74:75], v[114:115]
	v_fmac_f32_e32 v175, v112, v112
	v_add_u32_e32 v228, 0x8000, v228
	v_add_u32_e32 v229, 0x8000, v229
	v_add_u32_e32 v230, 0x8000, v230
	v_add_u32_e32 v231, 0x8000, v231
	v_fmac_f32_e32 v175, v113, v113
	v_fmac_f32_e32 v175, v114, v114
	v_fmac_f32_e32 v175, v115, v115
	v_perm_b32 v232, v229, v228, s58
	v_perm_b32 v233, v231, v230, s58
	global_store_dwordx2 v[202:203], v[232:233], off offset:256
	v_pk_fma_f32 v[126:127], v[126:127], 0.5, v[194:195] op_sel_hi:[1,0,1]
	v_pk_fma_f32 v[124:125], v[124:125], 0.5, v[192:193] op_sel_hi:[1,0,1]
	global_store_dwordx4 v[220:221], v[124:127], off
	v_pk_mul_f32 v[224:225], v[80:81], v[124:125]
	v_pk_mul_f32 v[226:227], v[82:83], v[126:127]
	v_mul_f32_e32 v234, v124, v124
	v_add_u32_e32 v224, 0x8000, v224
	v_add_u32_e32 v225, 0x8000, v225
	v_add_u32_e32 v226, 0x8000, v226
	v_add_u32_e32 v227, 0x8000, v227
	v_fmac_f32_e32 v234, v125, v125
	v_fmac_f32_e32 v234, v126, v126
	v_fmac_f32_e32 v234, v127, v127
	v_perm_b32 v222, v225, v224, s58
	v_perm_b32 v223, v227, v226, s58
	global_store_dwordx2 v[204:205], v[222:223], off
	v_pk_fma_f32 v[118:119], v[118:119], 0.5, v[198:199] op_sel_hi:[1,0,1]
	v_pk_fma_f32 v[116:117], v[116:117], 0.5, v[196:197] op_sel_hi:[1,0,1]
	global_store_dwordx4 v[220:221], v[116:119], off offset:512
	v_pk_mul_f32 v[228:229], v[84:85], v[116:117]
	v_pk_mul_f32 v[230:231], v[86:87], v[118:119]
	v_fmac_f32_e32 v234, v116, v116
	v_add_u32_e32 v228, 0x8000, v228
	v_add_u32_e32 v229, 0x8000, v229
	v_add_u32_e32 v230, 0x8000, v230
	v_add_u32_e32 v231, 0x8000, v231
	v_fmac_f32_e32 v234, v117, v117
	v_fmac_f32_e32 v234, v118, v118
	v_fmac_f32_e32 v234, v119, v119
	v_perm_b32 v232, v229, v228, s58
	v_perm_b32 v233, v231, v230, s58
	global_store_dwordx2 v[204:205], v[232:233], off offset:256
	s_nop 1
	v_mov_b32_dpp v241, v175 row_ror:8 row_mask:0xf bank_mask:0xf
	v_mov_b32_dpp v242, v234 row_ror:8 row_mask:0xf bank_mask:0xf
	v_add_f32_e32 v175, v175, v241
	v_add_f32_e32 v234, v234, v242
	v_cndmask_b32_e64 v175, v234, v175, s[34:35]
	s_nop 0
	ds_bpermute_b32 v241, v235, v175
	global_load_dwordx4 v[184:187], v[164:165], off nt
	global_load_dwordx4 v[188:191], v[164:165], off offset:512 nt
	global_load_dwordx4 v[192:195], v[200:201], off nt
	global_load_dwordx4 v[196:199], v[200:201], off offset:512 nt
	s_mov_b64 vcc, 0xa0000
	v_lshl_add_u64 v[164:165], v[164:165], 0, vcc
	v_lshl_add_u64 v[200:201], v[200:201], 0, vcc
	s_mov_b64 vcc, 0x20000
	v_lshl_add_u64 v[218:219], v[218:219], 0, vcc
	v_lshl_add_u64 v[220:221], v[220:221], 0, vcc
	s_mov_b64 vcc, 0x10000
	v_lshl_add_u64 v[202:203], v[202:203], 0, vcc
	v_lshl_add_u64 v[204:205], v[204:205], 0, vcc
	s_waitcnt lgkmcnt(0)
;     __device__ __forceinline__ void operator()(const f32x4 (&acc)[2][2][4][2], const Unit& u, int wr, int wc, int fr, int fq) const {
;     ...
; #pragma unroll
;         for (int ai = 0; ai < 2; ++ai)
; #pragma unroll
;             for (int m = 0; m < 4; ++m) {
;                 const int row = row0 + ai * HALF + m * 16;
;                 const size_t off = (size_t)row * ldc + col0;
;                 float q = 0.f;
; #pragma unroll
;                 for (int bj = 0; bj < 2; ++bj)
; #pragma unroll
;                     for (int n = 0; n < 2; ++n) {
;                         const f32x4 rv = *(const f32x4*)(rbase + off + bj * HALF + n * 16);
;                         const f32x4 v = rv + acc[ai][bj][m][n] * scale;
;                         if (out) *(f32x4*)(out + off + bj * HALF + n * 16) = v;
;                         if (xn) { q += (v.x * v.x + v.y * v.y) + (v.z * v.z + v.w * v.w); const f32x4 o = v * wv[bj][n];
;                             u32x2 p; p.x = pk2(o.x, o.y); p.y = pk2(o.z, o.w); *(u32x2*)(xn + off + bj * HALF + n * 16) = p; }
;                     }
;                 if (xn) { q += __shfl_xor(q, 16); q += __shfl_xor(q, 32); if (fq == 0) (void)__hip_atomic_fetch_add(ss + row, q, __ATOMIC_RELAXED, __HIP_MEMORY_SCOPE_AGENT); }
	v_add_f32_e32 v175, v175, v241
	s_nop 0
	ds_bpermute_b32 v242, v240, v175
	s_waitcnt lgkmcnt(0)
	v_add_f32_e32 v175, v175, v242
	s_mov_b64 exec, s[0:1]
	global_atomic_add_f32 v[206:207], v175, off
	s_mov_b64 exec, -1
	s_mov_b64 vcc, 64
	v_lshl_add_u64 v[206:207], v[206:207], 0, vcc
	v_mov_b32_dpp v236, v104 row_ror:8 row_mask:0xf bank_mask:0xf
	v_mov_b32_dpp v237, v105 row_ror:8 row_mask:0xf bank_mask:0xf
	v_mov_b32_dpp v238, v106 row_ror:8 row_mask:0xf bank_mask:0xf
	v_mov_b32_dpp v239, v107 row_ror:8 row_mask:0xf bank_mask:0xf
	v_cndmask_b32_e64 v104, v236, v108, s[34:35]
	v_cndmask_b32_e64 v105, v237, v109, s[34:35]
	v_cndmask_b32_e64 v106, v238, v110, s[34:35]
	v_cndmask_b32_e64 v107, v239, v111, s[34:35]
	v_cndmask_b32_e64 v108, v108, v236, s[34:35]
	v_cndmask_b32_e64 v109, v109, v237, s[34:35]
	v_cndmask_b32_e64 v110, v110, v238, s[34:35]
	v_cndmask_b32_e64 v111, v111, v239, s[34:35]
	v_mov_b32_dpp v236, v96 row_ror:8 row_mask:0xf bank_mask:0xf
	v_mov_b32_dpp v237, v97 row_ror:8 row_mask:0xf bank_mask:0xf
	v_mov_b32_dpp v238, v98 row_ror:8 row_mask:0xf bank_mask:0xf
	v_mov_b32_dpp v239, v99 row_ror:8 row_mask:0xf bank_mask:0xf
	v_cndmask_b32_e64 v96, v236, v100, s[34:35]
	v_cndmask_b32_e64 v97, v237, v101, s[34:35]
	v_cndmask_b32_e64 v98, v238, v102, s[34:35]
	v_cndmask_b32_e64 v99, v239, v103, s[34:35]
	v_cndmask_b32_e64 v100, v100, v236, s[34:35]
	v_cndmask_b32_e64 v101, v101, v237, s[34:35]
	v_cndmask_b32_e64 v102, v102, v238, s[34:35]
	v_cndmask_b32_e64 v103, v103, v239, s[34:35]
	s_waitcnt vmcnt(14)
	v_pk_fma_f32 v[106:107], v[106:107], 0.5, v[158:159] op_sel_hi:[1,0,1]
	v_pk_fma_f32 v[104:105], v[104:105], 0.5, v[156:157] op_sel_hi:[1,0,1]
	global_store_dwordx4 v[218:219], v[104:107], off
	v_pk_mul_f32 v[224:225], v[64:65], v[104:105]
	v_pk_mul_f32 v[226:227], v[66:67], v[106:107]
	v_mul_f32_e32 v175, v104, v104
	v_add_u32_e32 v224, 0x8000, v224
	v_add_u32_e32 v225, 0x8000, v225
	v_add_u32_e32 v226, 0x8000, v226
	v_add_u32_e32 v227, 0x8000, v227
	v_fmac_f32_e32 v175, v105, v105
	v_fmac_f32_e32 v175, v106, v106
	v_fmac_f32_e32 v175, v107, v107
	v_perm_b32 v222, v225, v224, s58
	v_perm_b32 v223, v227, v226, s58
	global_store_dwordx2 v[202:203], v[222:223], off
	v_pk_fma_f32 v[98:99], v[98:99], 0.5, v[162:163] op_sel_hi:[1,0,1]
	v_pk_fma_f32 v[96:97], v[96:97], 0.5, v[160:161] op_sel_hi:[1,0,1]
	global_store_dwordx4 v[218:219], v[96:99], off offset:512
	v_pk_mul_f32 v[228:229], v[72:73], v[96:97]
	v_pk_mul_f32 v[230:231], v[74:75], v[98:99]
	v_fmac_f32_e32 v175, v96, v96
	v_add_u32_e32 v228, 0x8000, v228
	v_add_u32_e32 v229, 0x8000, v229
	v_add_u32_e32 v230, 0x8000, v230
	v_add_u32_e32 v231, 0x8000, v231
	v_fmac_f32_e32 v175, v97, v97
	v_fmac_f32_e32 v175, v98, v98
	v_fmac_f32_e32 v175, v99, v99
	v_perm_b32 v232, v229, v228, s58
	v_perm_b32 v233, v231, v230, s58
	global_store_dwordx2 v[202:203], v[232:233], off offset:256
	v_pk_fma_f32 v[110:111], v[110:111], 0.5, v[178:179] op_sel_hi:[1,0,1]
	v_pk_fma_f32 v[108:109], v[108:109], 0.5, v[176:177] op_sel_hi:[1,0,1]
	global_store_dwordx4 v[220:221], v[108:111], off
	v_pk_mul_f32 v[224:225], v[80:81], v[108:109]
	v_pk_mul_f32 v[226:227], v[82:83], v[110:111]
	v_mul_f32_e32 v234, v108, v108
	v_add_u32_e32 v224, 0x8000, v224
	v_add_u32_e32 v225, 0x8000, v225
	v_add_u32_e32 v226, 0x8000, v226
	v_add_u32_e32 v227, 0x8000, v227
	v_fmac_f32_e32 v234, v109, v109
	v_fmac_f32_e32 v234, v110, v110
	v_fmac_f32_e32 v234, v111, v111
	v_perm_b32 v222, v225, v224, s58
	v_perm_b32 v223, v227, v226, s58
	global_store_dwordx2 v[204:205], v[222:223], off
	v_pk_fma_f32 v[102:103], v[102:103], 0.5, v[182:183] op_sel_hi:[1,0,1]
	v_pk_fma_f32 v[100:101], v[100:101], 0.5, v[180:181] op_sel_hi:[1,0,1]
	global_store_dwordx4 v[220:221], v[100:103], off offset:512
	v_pk_mul_f32 v[228:229], v[84:85], v[100:101]
	v_pk_mul_f32 v[230:231], v[86:87], v[102:103]
	v_fmac_f32_e32 v234, v100, v100
	v_add_u32_e32 v228, 0x8000, v228
	v_add_u32_e32 v229, 0x8000, v229
	v_add_u32_e32 v230, 0x8000, v230
	v_add_u32_e32 v231, 0x8000, v231
	v_fmac_f32_e32 v234, v101, v101
	v_fmac_f32_e32 v234, v102, v102
	v_fmac_f32_e32 v234, v103, v103
	v_perm_b32 v232, v229, v228, s58
	v_perm_b32 v233, v231, v230, s58
	global_store_dwordx2 v[204:205], v[232:233], off offset:256
	s_nop 1
	v_mov_b32_dpp v241, v175 row_ror:8 row_mask:0xf bank_mask:0xf
	v_mov_b32_dpp v242, v234 row_ror:8 row_mask:0xf bank_mask:0xf
	v_add_f32_e32 v175, v175, v241
	v_add_f32_e32 v234, v234, v242
	v_cndmask_b32_e64 v175, v234, v175, s[34:35]
	s_nop 0
	ds_bpermute_b32 v241, v235, v175
	global_load_dwordx4 v[156:159], v[164:165], off nt
	global_load_dwordx4 v[160:163], v[164:165], off offset:512 nt
	global_load_dwordx4 v[176:179], v[200:201], off nt
	global_load_dwordx4 v[180:183], v[200:201], off offset:512 nt
	s_mov_b64 vcc, 0x20000
	v_lshl_add_u64 v[164:165], v[164:165], 0, vcc
	v_lshl_add_u64 v[200:201], v[200:201], 0, vcc
	s_mov_b64 vcc, 0x20000
	v_lshl_add_u64 v[218:219], v[218:219], 0, vcc
	v_lshl_add_u64 v[220:221], v[220:221], 0, vcc
	s_mov_b64 vcc, 0x10000
	v_lshl_add_u64 v[202:203], v[202:203], 0, vcc
	v_lshl_add_u64 v[204:205], v[204:205], 0, vcc
	s_waitcnt lgkmcnt(0)
	v_add_f32_e32 v175, v175, v241
	s_nop 0
	ds_bpermute_b32 v242, v240, v175
	s_waitcnt lgkmcnt(0)
;     __device__ __forceinline__ void operator()(const f32x4 (&acc)[2][2][4][2], const Unit& u, int wr, int wc, int fr, int fq) const {
;     ...
; #pragma unroll
;         for (int ai = 0; ai < 2; ++ai)
; #pragma unroll
;             for (int m = 0; m < 4; ++m) {
;                 const int row = row0 + ai * HALF + m * 16;
;                 const size_t off = (size_t)row * ldc + col0;
;                 float q = 0.f;
; #pragma unroll
;                 for (int bj = 0; bj < 2; ++bj)
; #pragma unroll
;                     for (int n = 0; n < 2; ++n) {
;                         const f32x4 rv = *(const f32x4*)(rbase + off + bj * HALF + n * 16);
;                         const f32x4 v = rv + acc[ai][bj][m][n] * scale;
;                         if (out) *(f32x4*)(out + off + bj * HALF + n * 16) = v;
;                         if (xn) { q += (v.x * v.x + v.y * v.y) + (v.z * v.z + v.w * v.w); const f32x4 o = v * wv[bj][n];
;                             u32x2 p; p.x = pk2(o.x, o.y); p.y = pk2(o.z, o.w); *(u32x2*)(xn + off + bj * HALF + n * 16) = p; }
;                     }
;                 if (xn) { q += __shfl_xor(q, 16); q += __shfl_xor(q, 32); if (fq == 0) (void)__hip_atomic_fetch_add(ss + row, q, __ATOMIC_RELAXED, __HIP_MEMORY_SCOPE_AGENT); }
	v_add_f32_e32 v175, v175, v242
	s_mov_b64 exec, s[0:1]
	global_atomic_add_f32 v[206:207], v175, off
	s_mov_b64 exec, -1
	s_mov_b64 vcc, 64
	v_lshl_add_u64 v[206:207], v[206:207], 0, vcc
	v_mov_b32_dpp v236, v88 row_ror:8 row_mask:0xf bank_mask:0xf
	v_mov_b32_dpp v237, v89 row_ror:8 row_mask:0xf bank_mask:0xf
	v_mov_b32_dpp v238, v90 row_ror:8 row_mask:0xf bank_mask:0xf
	v_mov_b32_dpp v239, v91 row_ror:8 row_mask:0xf bank_mask:0xf
	v_cndmask_b32_e64 v88, v236, v92, s[34:35]
	v_cndmask_b32_e64 v89, v237, v93, s[34:35]
	v_cndmask_b32_e64 v90, v238, v94, s[34:35]
	v_cndmask_b32_e64 v91, v239, v95, s[34:35]
	v_cndmask_b32_e64 v92, v92, v236, s[34:35]
	v_cndmask_b32_e64 v93, v93, v237, s[34:35]
	v_cndmask_b32_e64 v94, v94, v238, s[34:35]
	v_cndmask_b32_e64 v95, v95, v239, s[34:35]
	v_mov_b32_dpp v236, v68 row_ror:8 row_mask:0xf bank_mask:0xf
	v_mov_b32_dpp v237, v69 row_ror:8 row_mask:0xf bank_mask:0xf
	v_mov_b32_dpp v238, v70 row_ror:8 row_mask:0xf bank_mask:0xf
	v_mov_b32_dpp v239, v71 row_ror:8 row_mask:0xf bank_mask:0xf
	v_cndmask_b32_e64 v68, v236, v76, s[34:35]
	v_cndmask_b32_e64 v69, v237, v77, s[34:35]
	v_cndmask_b32_e64 v70, v238, v78, s[34:35]
	v_cndmask_b32_e64 v71, v239, v79, s[34:35]
	v_cndmask_b32_e64 v76, v76, v236, s[34:35]
	v_cndmask_b32_e64 v77, v77, v237, s[34:35]
	v_cndmask_b32_e64 v78, v78, v238, s[34:35]
	v_cndmask_b32_e64 v79, v79, v239, s[34:35]
	s_waitcnt vmcnt(14)
	v_pk_fma_f32 v[90:91], v[90:91], 0.5, v[186:187] op_sel_hi:[1,0,1]
	v_pk_fma_f32 v[88:89], v[88:89], 0.5, v[184:185] op_sel_hi:[1,0,1]
	global_store_dwordx4 v[218:219], v[88:91], off
	v_pk_mul_f32 v[224:225], v[64:65], v[88:89]
	v_pk_mul_f32 v[226:227], v[66:67], v[90:91]
	v_mul_f32_e32 v175, v88, v88
	v_add_u32_e32 v224, 0x8000, v224
	v_add_u32_e32 v225, 0x8000, v225
	v_add_u32_e32 v226, 0x8000, v226
	v_add_u32_e32 v227, 0x8000, v227
	v_fmac_f32_e32 v175, v89, v89
	v_fmac_f32_e32 v175, v90, v90
	v_fmac_f32_e32 v175, v91, v91
	v_perm_b32 v222, v225, v224, s58
	v_perm_b32 v223, v227, v226, s58
	global_store_dwordx2 v[202:203], v[222:223], off
	v_pk_fma_f32 v[70:71], v[70:71], 0.5, v[190:191] op_sel_hi:[1,0,1]
	v_pk_fma_f32 v[68:69], v[68:69], 0.5, v[188:189] op_sel_hi:[1,0,1]
	global_store_dwordx4 v[218:219], v[68:71], off offset:512
	v_pk_mul_f32 v[228:229], v[72:73], v[68:69]
	v_pk_mul_f32 v[230:231], v[74:75], v[70:71]
	v_fmac_f32_e32 v175, v68, v68
	v_add_u32_e32 v228, 0x8000, v228
	v_add_u32_e32 v229, 0x8000, v229
	v_add_u32_e32 v230, 0x8000, v230
	v_add_u32_e32 v231, 0x8000, v231
	v_fmac_f32_e32 v175, v69, v69
	v_fmac_f32_e32 v175, v70, v70
	v_fmac_f32_e32 v175, v71, v71
	v_perm_b32 v232, v229, v228, s58
	v_perm_b32 v233, v231, v230, s58
	global_store_dwordx2 v[202:203], v[232:233], off offset:256
	v_pk_fma_f32 v[94:95], v[94:95], 0.5, v[194:195] op_sel_hi:[1,0,1]
	v_pk_fma_f32 v[92:93], v[92:93], 0.5, v[192:193] op_sel_hi:[1,0,1]
	global_store_dwordx4 v[220:221], v[92:95], off
	v_pk_mul_f32 v[224:225], v[80:81], v[92:93]
	v_pk_mul_f32 v[226:227], v[82:83], v[94:95]
	v_mul_f32_e32 v234, v92, v92
	v_add_u32_e32 v224, 0x8000, v224
	v_add_u32_e32 v225, 0x8000, v225
	v_add_u32_e32 v226, 0x8000, v226
	v_add_u32_e32 v227, 0x8000, v227
	v_fmac_f32_e32 v234, v93, v93
	v_fmac_f32_e32 v234, v94, v94
	v_fmac_f32_e32 v234, v95, v95
	v_perm_b32 v222, v225, v224, s58
	v_perm_b32 v223, v227, v226, s58
	global_store_dwordx2 v[204:205], v[222:223], off
	v_pk_fma_f32 v[78:79], v[78:79], 0.5, v[198:199] op_sel_hi:[1,0,1]
	v_pk_fma_f32 v[76:77], v[76:77], 0.5, v[196:197] op_sel_hi:[1,0,1]
	global_store_dwordx4 v[220:221], v[76:79], off offset:512
	v_pk_mul_f32 v[228:229], v[84:85], v[76:77]
	v_pk_mul_f32 v[230:231], v[86:87], v[78:79]
	v_fmac_f32_e32 v234, v76, v76
	v_add_u32_e32 v228, 0x8000, v228
	v_add_u32_e32 v229, 0x8000, v229
	v_add_u32_e32 v230, 0x8000, v230
	v_add_u32_e32 v231, 0x8000, v231
	v_fmac_f32_e32 v234, v77, v77
	v_fmac_f32_e32 v234, v78, v78
	v_fmac_f32_e32 v234, v79, v79
	v_perm_b32 v232, v229, v228, s58
	v_perm_b32 v233, v231, v230, s58
	global_store_dwordx2 v[204:205], v[232:233], off offset:256
	s_nop 1
	v_mov_b32_dpp v241, v175 row_ror:8 row_mask:0xf bank_mask:0xf
	v_mov_b32_dpp v242, v234 row_ror:8 row_mask:0xf bank_mask:0xf
	v_add_f32_e32 v175, v175, v241
	v_add_f32_e32 v234, v234, v242
	v_cndmask_b32_e64 v175, v234, v175, s[34:35]
	s_nop 0
	ds_bpermute_b32 v241, v235, v175
	global_load_dwordx4 v[184:187], v[164:165], off nt
	global_load_dwordx4 v[188:191], v[164:165], off offset:512 nt
	global_load_dwordx4 v[192:195], v[200:201], off nt
	global_load_dwordx4 v[196:199], v[200:201], off offset:512 nt
	s_mov_b64 vcc, 0x20000
	v_lshl_add_u64 v[164:165], v[164:165], 0, vcc
	v_lshl_add_u64 v[200:201], v[200:201], 0, vcc
	s_mov_b64 vcc, 0xa0000
	v_lshl_add_u64 v[218:219], v[218:219], 0, vcc
	v_lshl_add_u64 v[220:221], v[220:221], 0, vcc
	s_mov_b64 vcc, 0x50000
	v_lshl_add_u64 v[202:203], v[202:203], 0, vcc
	v_lshl_add_u64 v[204:205], v[204:205], 0, vcc
	s_waitcnt lgkmcnt(0)
	v_add_f32_e32 v175, v175, v241
	s_nop 0
	ds_bpermute_b32 v242, v240, v175
	s_waitcnt lgkmcnt(0)
;     __device__ __forceinline__ void operator()(const f32x4 (&acc)[2][2][4][2], const Unit& u, int wr, int wc, int fr, int fq) const {
;     ...
; #pragma unroll
;         for (int ai = 0; ai < 2; ++ai)
; #pragma unroll
;             for (int m = 0; m < 4; ++m) {
;                 const int row = row0 + ai * HALF + m * 16;
;                 const size_t off = (size_t)row * ldc + col0;
;                 float q = 0.f;
; #pragma unroll
;                 for (int bj = 0; bj < 2; ++bj)
; #pragma unroll
;                     for (int n = 0; n < 2; ++n) {
;                         const f32x4 rv = *(const f32x4*)(rbase + off + bj * HALF + n * 16);
;                         const f32x4 v = rv + acc[ai][bj][m][n] * scale;
;                         if (out) *(f32x4*)(out + off + bj * HALF + n * 16) = v;
;                         if (xn) { q += (v.x * v.x + v.y * v.y) + (v.z * v.z + v.w * v.w); const f32x4 o = v * wv[bj][n];
;                             u32x2 p; p.x = pk2(o.x, o.y); p.y = pk2(o.z, o.w); *(u32x2*)(xn + off + bj * HALF + n * 16) = p; }
;                     }
;                 if (xn) { q += __shfl_xor(q, 16); q += __shfl_xor(q, 32); if (fq == 0) (void)__hip_atomic_fetch_add(ss + row, q, __ATOMIC_RELAXED, __HIP_MEMORY_SCOPE_AGENT); }
	v_add_f32_e32 v175, v175, v242
	s_mov_b64 exec, s[0:1]
	global_atomic_add_f32 v[206:207], v175, off
	s_mov_b64 exec, -1
	s_mov_b64 vcc, 320
	v_lshl_add_u64 v[206:207], v[206:207], 0, vcc
	v_mov_b32_dpp v236, v56 row_ror:8 row_mask:0xf bank_mask:0xf
	v_mov_b32_dpp v237, v57 row_ror:8 row_mask:0xf bank_mask:0xf
	v_mov_b32_dpp v238, v58 row_ror:8 row_mask:0xf bank_mask:0xf
	v_mov_b32_dpp v239, v59 row_ror:8 row_mask:0xf bank_mask:0xf
	v_cndmask_b32_e64 v56, v236, v60, s[34:35]
	v_cndmask_b32_e64 v57, v237, v61, s[34:35]
	v_cndmask_b32_e64 v58, v238, v62, s[34:35]
	v_cndmask_b32_e64 v59, v239, v63, s[34:35]
	v_cndmask_b32_e64 v60, v60, v236, s[34:35]
	v_cndmask_b32_e64 v61, v61, v237, s[34:35]
	v_cndmask_b32_e64 v62, v62, v238, s[34:35]
	v_cndmask_b32_e64 v63, v63, v239, s[34:35]
	v_mov_b32_dpp v236, v48 row_ror:8 row_mask:0xf bank_mask:0xf
	v_mov_b32_dpp v237, v49 row_ror:8 row_mask:0xf bank_mask:0xf
	v_mov_b32_dpp v238, v50 row_ror:8 row_mask:0xf bank_mask:0xf
	v_mov_b32_dpp v239, v51 row_ror:8 row_mask:0xf bank_mask:0xf
	v_cndmask_b32_e64 v48, v236, v52, s[34:35]
	v_cndmask_b32_e64 v49, v237, v53, s[34:35]
	v_cndmask_b32_e64 v50, v238, v54, s[34:35]
	v_cndmask_b32_e64 v51, v239, v55, s[34:35]
	v_cndmask_b32_e64 v52, v52, v236, s[34:35]
	v_cndmask_b32_e64 v53, v53, v237, s[34:35]
	v_cndmask_b32_e64 v54, v54, v238, s[34:35]
	v_cndmask_b32_e64 v55, v55, v239, s[34:35]
	s_waitcnt vmcnt(14)
	v_pk_fma_f32 v[58:59], v[58:59], 0.5, v[158:159] op_sel_hi:[1,0,1]
	v_pk_fma_f32 v[56:57], v[56:57], 0.5, v[156:157] op_sel_hi:[1,0,1]
	global_store_dwordx4 v[218:219], v[56:59], off
	v_pk_mul_f32 v[224:225], v[64:65], v[56:57]
	v_pk_mul_f32 v[226:227], v[66:67], v[58:59]
	v_mul_f32_e32 v175, v56, v56
	v_add_u32_e32 v224, 0x8000, v224
	v_add_u32_e32 v225, 0x8000, v225
	v_add_u32_e32 v226, 0x8000, v226
	v_add_u32_e32 v227, 0x8000, v227
	v_fmac_f32_e32 v175, v57, v57
	v_fmac_f32_e32 v175, v58, v58
	v_fmac_f32_e32 v175, v59, v59
	v_perm_b32 v222, v225, v224, s58
	v_perm_b32 v223, v227, v226, s58
	global_store_dwordx2 v[202:203], v[222:223], off
	v_pk_fma_f32 v[50:51], v[50:51], 0.5, v[162:163] op_sel_hi:[1,0,1]
	v_pk_fma_f32 v[48:49], v[48:49], 0.5, v[160:161] op_sel_hi:[1,0,1]
	global_store_dwordx4 v[218:219], v[48:51], off offset:512
	v_pk_mul_f32 v[228:229], v[72:73], v[48:49]
	v_pk_mul_f32 v[230:231], v[74:75], v[50:51]
	v_fmac_f32_e32 v175, v48, v48
	v_add_u32_e32 v228, 0x8000, v228
	v_add_u32_e32 v229, 0x8000, v229
	v_add_u32_e32 v230, 0x8000, v230
	v_add_u32_e32 v231, 0x8000, v231
	v_fmac_f32_e32 v175, v49, v49
	v_fmac_f32_e32 v175, v50, v50
	v_fmac_f32_e32 v175, v51, v51
	v_perm_b32 v232, v229, v228, s58
	v_perm_b32 v233, v231, v230, s58
	global_store_dwordx2 v[202:203], v[232:233], off offset:256
	v_pk_fma_f32 v[62:63], v[62:63], 0.5, v[178:179] op_sel_hi:[1,0,1]
	v_pk_fma_f32 v[60:61], v[60:61], 0.5, v[176:177] op_sel_hi:[1,0,1]
	global_store_dwordx4 v[220:221], v[60:63], off
	v_pk_mul_f32 v[224:225], v[80:81], v[60:61]
	v_pk_mul_f32 v[226:227], v[82:83], v[62:63]
	v_mul_f32_e32 v234, v60, v60
	v_add_u32_e32 v224, 0x8000, v224
	v_add_u32_e32 v225, 0x8000, v225
	v_add_u32_e32 v226, 0x8000, v226
	v_add_u32_e32 v227, 0x8000, v227
	v_fmac_f32_e32 v234, v61, v61
	v_fmac_f32_e32 v234, v62, v62
	v_fmac_f32_e32 v234, v63, v63
	v_perm_b32 v222, v225, v224, s58
	v_perm_b32 v223, v227, v226, s58
	global_store_dwordx2 v[204:205], v[222:223], off
	v_pk_fma_f32 v[54:55], v[54:55], 0.5, v[182:183] op_sel_hi:[1,0,1]
	v_pk_fma_f32 v[52:53], v[52:53], 0.5, v[180:181] op_sel_hi:[1,0,1]
	global_store_dwordx4 v[220:221], v[52:55], off offset:512
	v_pk_mul_f32 v[228:229], v[84:85], v[52:53]
	v_pk_mul_f32 v[230:231], v[86:87], v[54:55]
	v_fmac_f32_e32 v234, v52, v52
	v_add_u32_e32 v228, 0x8000, v228
	v_add_u32_e32 v229, 0x8000, v229
	v_add_u32_e32 v230, 0x8000, v230
	v_add_u32_e32 v231, 0x8000, v231
	v_fmac_f32_e32 v234, v53, v53
	v_fmac_f32_e32 v234, v54, v54
	v_fmac_f32_e32 v234, v55, v55
	v_perm_b32 v232, v229, v228, s58
	v_perm_b32 v233, v231, v230, s58
	global_store_dwordx2 v[204:205], v[232:233], off offset:256
	s_nop 1
	v_mov_b32_dpp v241, v175 row_ror:8 row_mask:0xf bank_mask:0xf
	v_mov_b32_dpp v242, v234 row_ror:8 row_mask:0xf bank_mask:0xf
	v_add_f32_e32 v175, v175, v241
	v_add_f32_e32 v234, v234, v242
	v_cndmask_b32_e64 v175, v234, v175, s[34:35]
	s_nop 0
	ds_bpermute_b32 v241, v235, v175
	global_load_dwordx4 v[156:159], v[164:165], off nt
	global_load_dwordx4 v[160:163], v[164:165], off offset:512 nt
	global_load_dwordx4 v[176:179], v[200:201], off nt
	global_load_dwordx4 v[180:183], v[200:201], off offset:512 nt
	s_mov_b64 vcc, 0x20000
	v_lshl_add_u64 v[164:165], v[164:165], 0, vcc
	v_lshl_add_u64 v[200:201], v[200:201], 0, vcc
	s_mov_b64 vcc, 0x20000
	v_lshl_add_u64 v[218:219], v[218:219], 0, vcc
	v_lshl_add_u64 v[220:221], v[220:221], 0, vcc
	s_mov_b64 vcc, 0x10000
	v_lshl_add_u64 v[202:203], v[202:203], 0, vcc
	v_lshl_add_u64 v[204:205], v[204:205], 0, vcc
	s_waitcnt lgkmcnt(0)
	v_add_f32_e32 v175, v175, v241
	s_nop 0
	ds_bpermute_b32 v242, v240, v175
	s_waitcnt lgkmcnt(0)
;     __device__ __forceinline__ void operator()(const f32x4 (&acc)[2][2][4][2], const Unit& u, int wr, int wc, int fr, int fq) const {
;     ...
; #pragma unroll
;         for (int ai = 0; ai < 2; ++ai)
; #pragma unroll
;             for (int m = 0; m < 4; ++m) {
;                 const int row = row0 + ai * HALF + m * 16;
;                 const size_t off = (size_t)row * ldc + col0;
;                 float q = 0.f;
; #pragma unroll
;                 for (int bj = 0; bj < 2; ++bj)
; #pragma unroll
;                     for (int n = 0; n < 2; ++n) {
;                         const f32x4 rv = *(const f32x4*)(rbase + off + bj * HALF + n * 16);
;                         const f32x4 v = rv + acc[ai][bj][m][n] * scale;
;                         if (out) *(f32x4*)(out + off + bj * HALF + n * 16) = v;
;                         if (xn) { q += (v.x * v.x + v.y * v.y) + (v.z * v.z + v.w * v.w); const f32x4 o = v * wv[bj][n];
;                             u32x2 p; p.x = pk2(o.x, o.y); p.y = pk2(o.z, o.w); *(u32x2*)(xn + off + bj * HALF + n * 16) = p; }
;                     }
;                 if (xn) { q += __shfl_xor(q, 16); q += __shfl_xor(q, 32); if (fq == 0) (void)__hip_atomic_fetch_add(ss + row, q, __ATOMIC_RELAXED, __HIP_MEMORY_SCOPE_AGENT); }
	v_add_f32_e32 v175, v175, v242
	s_mov_b64 exec, s[0:1]
	global_atomic_add_f32 v[206:207], v175, off
	s_mov_b64 exec, -1
	s_mov_b64 vcc, 64
	v_lshl_add_u64 v[206:207], v[206:207], 0, vcc
	v_mov_b32_dpp v236, v40 row_ror:8 row_mask:0xf bank_mask:0xf
	v_mov_b32_dpp v237, v41 row_ror:8 row_mask:0xf bank_mask:0xf
	v_mov_b32_dpp v238, v42 row_ror:8 row_mask:0xf bank_mask:0xf
	v_mov_b32_dpp v239, v43 row_ror:8 row_mask:0xf bank_mask:0xf
	v_cndmask_b32_e64 v40, v236, v44, s[34:35]
	v_cndmask_b32_e64 v41, v237, v45, s[34:35]
	v_cndmask_b32_e64 v42, v238, v46, s[34:35]
	v_cndmask_b32_e64 v43, v239, v47, s[34:35]
	v_cndmask_b32_e64 v44, v44, v236, s[34:35]
	v_cndmask_b32_e64 v45, v45, v237, s[34:35]
	v_cndmask_b32_e64 v46, v46, v238, s[34:35]
	v_cndmask_b32_e64 v47, v47, v239, s[34:35]
	v_mov_b32_dpp v236, v32 row_ror:8 row_mask:0xf bank_mask:0xf
	v_mov_b32_dpp v237, v33 row_ror:8 row_mask:0xf bank_mask:0xf
	v_mov_b32_dpp v238, v34 row_ror:8 row_mask:0xf bank_mask:0xf
	v_mov_b32_dpp v239, v35 row_ror:8 row_mask:0xf bank_mask:0xf
	v_cndmask_b32_e64 v32, v236, v36, s[34:35]
	v_cndmask_b32_e64 v33, v237, v37, s[34:35]
	v_cndmask_b32_e64 v34, v238, v38, s[34:35]
	v_cndmask_b32_e64 v35, v239, v39, s[34:35]
	v_cndmask_b32_e64 v36, v36, v236, s[34:35]
	v_cndmask_b32_e64 v37, v37, v237, s[34:35]
	v_cndmask_b32_e64 v38, v38, v238, s[34:35]
	v_cndmask_b32_e64 v39, v39, v239, s[34:35]
	s_waitcnt vmcnt(14)
	v_pk_fma_f32 v[42:43], v[42:43], 0.5, v[186:187] op_sel_hi:[1,0,1]
	v_pk_fma_f32 v[40:41], v[40:41], 0.5, v[184:185] op_sel_hi:[1,0,1]
	global_store_dwordx4 v[218:219], v[40:43], off
	v_pk_mul_f32 v[224:225], v[64:65], v[40:41]
	v_pk_mul_f32 v[226:227], v[66:67], v[42:43]
	v_mul_f32_e32 v175, v40, v40
	v_add_u32_e32 v224, 0x8000, v224
	v_add_u32_e32 v225, 0x8000, v225
	v_add_u32_e32 v226, 0x8000, v226
	v_add_u32_e32 v227, 0x8000, v227
	v_fmac_f32_e32 v175, v41, v41
	v_fmac_f32_e32 v175, v42, v42
	v_fmac_f32_e32 v175, v43, v43
	v_perm_b32 v222, v225, v224, s58
	v_perm_b32 v223, v227, v226, s58
	global_store_dwordx2 v[202:203], v[222:223], off
	v_pk_fma_f32 v[34:35], v[34:35], 0.5, v[190:191] op_sel_hi:[1,0,1]
	v_pk_fma_f32 v[32:33], v[32:33], 0.5, v[188:189] op_sel_hi:[1,0,1]
	global_store_dwordx4 v[218:219], v[32:35], off offset:512
	v_pk_mul_f32 v[228:229], v[72:73], v[32:33]
	v_pk_mul_f32 v[230:231], v[74:75], v[34:35]
	v_fmac_f32_e32 v175, v32, v32
	v_add_u32_e32 v228, 0x8000, v228
	v_add_u32_e32 v229, 0x8000, v229
	v_add_u32_e32 v230, 0x8000, v230
	v_add_u32_e32 v231, 0x8000, v231
	v_fmac_f32_e32 v175, v33, v33
	v_fmac_f32_e32 v175, v34, v34
	v_fmac_f32_e32 v175, v35, v35
	v_perm_b32 v232, v229, v228, s58
	v_perm_b32 v233, v231, v230, s58
	global_store_dwordx2 v[202:203], v[232:233], off offset:256
	v_pk_fma_f32 v[46:47], v[46:47], 0.5, v[194:195] op_sel_hi:[1,0,1]
	v_pk_fma_f32 v[44:45], v[44:45], 0.5, v[192:193] op_sel_hi:[1,0,1]
	global_store_dwordx4 v[220:221], v[44:47], off
	v_pk_mul_f32 v[224:225], v[80:81], v[44:45]
	v_pk_mul_f32 v[226:227], v[82:83], v[46:47]
	v_mul_f32_e32 v234, v44, v44
	v_add_u32_e32 v224, 0x8000, v224
	v_add_u32_e32 v225, 0x8000, v225
	v_add_u32_e32 v226, 0x8000, v226
	v_add_u32_e32 v227, 0x8000, v227
	v_fmac_f32_e32 v234, v45, v45
	v_fmac_f32_e32 v234, v46, v46
	v_fmac_f32_e32 v234, v47, v47
	v_perm_b32 v222, v225, v224, s58
	v_perm_b32 v223, v227, v226, s58
	global_store_dwordx2 v[204:205], v[222:223], off
	v_pk_fma_f32 v[38:39], v[38:39], 0.5, v[198:199] op_sel_hi:[1,0,1]
	v_pk_fma_f32 v[36:37], v[36:37], 0.5, v[196:197] op_sel_hi:[1,0,1]
	global_store_dwordx4 v[220:221], v[36:39], off offset:512
	v_pk_mul_f32 v[228:229], v[84:85], v[36:37]
	v_pk_mul_f32 v[230:231], v[86:87], v[38:39]
	v_fmac_f32_e32 v234, v36, v36
	v_add_u32_e32 v228, 0x8000, v228
	v_add_u32_e32 v229, 0x8000, v229
	v_add_u32_e32 v230, 0x8000, v230
	v_add_u32_e32 v231, 0x8000, v231
	v_fmac_f32_e32 v234, v37, v37
	v_fmac_f32_e32 v234, v38, v38
	v_fmac_f32_e32 v234, v39, v39
	v_perm_b32 v232, v229, v228, s58
	v_perm_b32 v233, v231, v230, s58
	global_store_dwordx2 v[204:205], v[232:233], off offset:256
	s_nop 1
	v_mov_b32_dpp v241, v175 row_ror:8 row_mask:0xf bank_mask:0xf
	v_mov_b32_dpp v242, v234 row_ror:8 row_mask:0xf bank_mask:0xf
	v_add_f32_e32 v175, v175, v241
	v_add_f32_e32 v234, v234, v242
	v_cndmask_b32_e64 v175, v234, v175, s[34:35]
	s_nop 0
	ds_bpermute_b32 v241, v235, v175
	global_load_dwordx4 v[184:187], v[164:165], off nt
	global_load_dwordx4 v[188:191], v[164:165], off offset:512 nt
	global_load_dwordx4 v[192:195], v[200:201], off nt
	global_load_dwordx4 v[196:199], v[200:201], off offset:512 nt
	s_mov_b64 vcc, 0x20000
	v_lshl_add_u64 v[218:219], v[218:219], 0, vcc
	v_lshl_add_u64 v[220:221], v[220:221], 0, vcc
	s_mov_b64 vcc, 0x10000
	v_lshl_add_u64 v[202:203], v[202:203], 0, vcc
	v_lshl_add_u64 v[204:205], v[204:205], 0, vcc
	s_waitcnt lgkmcnt(0)
	v_add_f32_e32 v175, v175, v241
	s_nop 0
	ds_bpermute_b32 v242, v240, v175
	s_waitcnt lgkmcnt(0)
	v_add_f32_e32 v175, v175, v242
	s_mov_b64 exec, s[0:1]
	global_atomic_add_f32 v[206:207], v175, off
	s_mov_b64 exec, -1
	s_mov_b64 vcc, 64
	v_lshl_add_u64 v[206:207], v[206:207], 0, vcc
	v_mov_b32_dpp v236, v24 row_ror:8 row_mask:0xf bank_mask:0xf
	v_mov_b32_dpp v237, v25 row_ror:8 row_mask:0xf bank_mask:0xf
	v_mov_b32_dpp v238, v26 row_ror:8 row_mask:0xf bank_mask:0xf
	v_mov_b32_dpp v239, v27 row_ror:8 row_mask:0xf bank_mask:0xf
	v_cndmask_b32_e64 v24, v236, v28, s[34:35]
	v_cndmask_b32_e64 v25, v237, v29, s[34:35]
	v_cndmask_b32_e64 v26, v238, v30, s[34:35]
	v_cndmask_b32_e64 v27, v239, v31, s[34:35]
	v_cndmask_b32_e64 v28, v28, v236, s[34:35]
	v_cndmask_b32_e64 v29, v29, v237, s[34:35]
	v_cndmask_b32_e64 v30, v30, v238, s[34:35]
	v_cndmask_b32_e64 v31, v31, v239, s[34:35]
	v_mov_b32_dpp v236, v16 row_ror:8 row_mask:0xf bank_mask:0xf
	v_mov_b32_dpp v237, v17 row_ror:8 row_mask:0xf bank_mask:0xf
	v_mov_b32_dpp v238, v18 row_ror:8 row_mask:0xf bank_mask:0xf
	v_mov_b32_dpp v239, v19 row_ror:8 row_mask:0xf bank_mask:0xf
	v_cndmask_b32_e64 v16, v236, v20, s[34:35]
	v_cndmask_b32_e64 v17, v237, v21, s[34:35]
	v_cndmask_b32_e64 v18, v238, v22, s[34:35]
	v_cndmask_b32_e64 v19, v239, v23, s[34:35]
	v_cndmask_b32_e64 v20, v20, v236, s[34:35]
	v_cndmask_b32_e64 v21, v21, v237, s[34:35]
	v_cndmask_b32_e64 v22, v22, v238, s[34:35]
	v_cndmask_b32_e64 v23, v23, v239, s[34:35]
	s_waitcnt vmcnt(14)
;     __device__ __forceinline__ void operator()(const f32x4 (&acc)[2][2][4][2], const Unit& u, int wr, int wc, int fr, int fq) const {
;     ...
;                 for (int bj = 0; bj < 2; ++bj)
; #pragma unroll
;                     for (int n = 0; n < 2; ++n) {
;                         const f32x4 rv = *(const f32x4*)(rbase + off + bj * HALF + n * 16);
;                         const f32x4 v = rv + acc[ai][bj][m][n] * scale;
;                         if (out) *(f32x4*)(out + off + bj * HALF + n * 16) = v;
;                         if (xn) { q += (v.x * v.x + v.y * v.y) + (v.z * v.z + v.w * v.w); const f32x4 o = v * wv[bj][n];
;                             u32x2 p; p.x = pk2(o.x, o.y); p.y = pk2(o.z, o.w); *(u32x2*)(xn + off + bj * HALF + n * 16) = p; }
;                     }
;                 if (xn) { q += __shfl_xor(q, 16); q += __shfl_xor(q, 32); if (fq == 0) (void)__hip_atomic_fetch_add(ss + row, q, __ATOMIC_RELAXED, __HIP_MEMORY_SCOPE_AGENT); }
	v_pk_fma_f32 v[26:27], v[26:27], 0.5, v[158:159] op_sel_hi:[1,0,1]
	v_pk_fma_f32 v[24:25], v[24:25], 0.5, v[156:157] op_sel_hi:[1,0,1]
	global_store_dwordx4 v[218:219], v[24:27], off
	v_pk_mul_f32 v[224:225], v[64:65], v[24:25]
	v_pk_mul_f32 v[226:227], v[66:67], v[26:27]
	v_mul_f32_e32 v175, v24, v24
	v_add_u32_e32 v224, 0x8000, v224
	v_add_u32_e32 v225, 0x8000, v225
	v_add_u32_e32 v226, 0x8000, v226
	v_add_u32_e32 v227, 0x8000, v227
	v_fmac_f32_e32 v175, v25, v25
	v_fmac_f32_e32 v175, v26, v26
	v_fmac_f32_e32 v175, v27, v27
	v_perm_b32 v222, v225, v224, s58
	v_perm_b32 v223, v227, v226, s58
	global_store_dwordx2 v[202:203], v[222:223], off
	v_pk_fma_f32 v[18:19], v[18:19], 0.5, v[162:163] op_sel_hi:[1,0,1]
	v_pk_fma_f32 v[16:17], v[16:17], 0.5, v[160:161] op_sel_hi:[1,0,1]
	global_store_dwordx4 v[218:219], v[16:19], off offset:512
	v_pk_mul_f32 v[228:229], v[72:73], v[16:17]
	v_pk_mul_f32 v[230:231], v[74:75], v[18:19]
	v_fmac_f32_e32 v175, v16, v16
	v_add_u32_e32 v228, 0x8000, v228
	v_add_u32_e32 v229, 0x8000, v229
	v_add_u32_e32 v230, 0x8000, v230
	v_add_u32_e32 v231, 0x8000, v231
	v_fmac_f32_e32 v175, v17, v17
	v_fmac_f32_e32 v175, v18, v18
	v_fmac_f32_e32 v175, v19, v19
	v_perm_b32 v232, v229, v228, s58
	v_perm_b32 v233, v231, v230, s58
	global_store_dwordx2 v[202:203], v[232:233], off offset:256
	v_pk_fma_f32 v[30:31], v[30:31], 0.5, v[178:179] op_sel_hi:[1,0,1]
	v_pk_fma_f32 v[28:29], v[28:29], 0.5, v[176:177] op_sel_hi:[1,0,1]
	global_store_dwordx4 v[220:221], v[28:31], off
	v_pk_mul_f32 v[224:225], v[80:81], v[28:29]
	v_pk_mul_f32 v[226:227], v[82:83], v[30:31]
	v_mul_f32_e32 v234, v28, v28
	v_add_u32_e32 v224, 0x8000, v224
	v_add_u32_e32 v225, 0x8000, v225
	v_add_u32_e32 v226, 0x8000, v226
	v_add_u32_e32 v227, 0x8000, v227
	v_fmac_f32_e32 v234, v29, v29
	v_fmac_f32_e32 v234, v30, v30
	v_fmac_f32_e32 v234, v31, v31
	v_perm_b32 v222, v225, v224, s58
	v_perm_b32 v223, v227, v226, s58
	global_store_dwordx2 v[204:205], v[222:223], off
	v_pk_fma_f32 v[22:23], v[22:23], 0.5, v[182:183] op_sel_hi:[1,0,1]
	v_pk_fma_f32 v[20:21], v[20:21], 0.5, v[180:181] op_sel_hi:[1,0,1]
	global_store_dwordx4 v[220:221], v[20:23], off offset:512
	v_pk_mul_f32 v[228:229], v[84:85], v[20:21]
	v_pk_mul_f32 v[230:231], v[86:87], v[22:23]
	v_fmac_f32_e32 v234, v20, v20
	v_add_u32_e32 v228, 0x8000, v228
	v_add_u32_e32 v229, 0x8000, v229
	v_add_u32_e32 v230, 0x8000, v230
	v_add_u32_e32 v231, 0x8000, v231
	v_fmac_f32_e32 v234, v21, v21
	v_fmac_f32_e32 v234, v22, v22
	v_fmac_f32_e32 v234, v23, v23
	v_perm_b32 v232, v229, v228, s58
	v_perm_b32 v233, v231, v230, s58
	global_store_dwordx2 v[204:205], v[232:233], off offset:256
	s_nop 1
	v_mov_b32_dpp v241, v175 row_ror:8 row_mask:0xf bank_mask:0xf
	v_mov_b32_dpp v242, v234 row_ror:8 row_mask:0xf bank_mask:0xf
	v_add_f32_e32 v175, v175, v241
	v_add_f32_e32 v234, v234, v242
	v_cndmask_b32_e64 v175, v234, v175, s[34:35]
	s_nop 0
	ds_bpermute_b32 v241, v235, v175
	s_mov_b64 vcc, 0x20000
	v_lshl_add_u64 v[218:219], v[218:219], 0, vcc
	v_lshl_add_u64 v[220:221], v[220:221], 0, vcc
	s_mov_b64 vcc, 0x10000
	v_lshl_add_u64 v[202:203], v[202:203], 0, vcc
	v_lshl_add_u64 v[204:205], v[204:205], 0, vcc
	s_waitcnt lgkmcnt(0)
	v_add_f32_e32 v175, v175, v241
	s_nop 0
	ds_bpermute_b32 v242, v240, v175
	s_waitcnt lgkmcnt(0)
; #define PG8_BAR __builtin_amdgcn_s_barrier()
;     __device__ __forceinline__ void operator()(const f32x4 (&acc)[2][2][4][2], const Unit& u, int wr, int wc, int fr, int fq) const {
;     ...
;                 for (int bj = 0; bj < 2; ++bj)
; #pragma unroll
;                     for (int n = 0; n < 2; ++n) {
;                         const f32x4 rv = *(const f32x4*)(rbase + off + bj * HALF + n * 16);
;                         const f32x4 v = rv + acc[ai][bj][m][n] * scale;
;                         if (out) *(f32x4*)(out + off + bj * HALF + n * 16) = v;
;                         if (xn) { q += (v.x * v.x + v.y * v.y) + (v.z * v.z + v.w * v.w); const f32x4 o = v * wv[bj][n];
;                             u32x2 p; p.x = pk2(o.x, o.y); p.y = pk2(o.z, o.w); *(u32x2*)(xn + off + bj * HALF + n * 16) = p; }
;                     }
;                 if (xn) { q += __shfl_xor(q, 16); q += __shfl_xor(q, 32); if (fq == 0) (void)__hip_atomic_fetch_add(ss + row, q, __ATOMIC_RELAXED, __HIP_MEMORY_SCOPE_AGENT); }
;             }
; template <class Epi, bool ALIGN_EPI>
; __device__ __forceinline__ void gemm_phase(LAS unsigned char* lds, const Gemm g, const StaticOrder& S, const Epi& E) {
;     ...
;         if constexpr (ALIGN_EPI) { if (wr == 0) PG8_BAR; }
;         E(acc, cur, wr, wc, fr, fq);
;         if (!has_next) break;
; #pragma unroll
;         for (int a = 0; a < 2; ++a)
; #pragma unroll
;             for (int b = 0; b < 2; ++b)
; #pragma unroll
;                 for (int m = 0; m < 4; ++m)
; #pragma unroll
;                     for (int n = 0; n < 2; ++n) acc[a][b][m][n] = (f32x4){0.f, 0.f, 0.f, 0.f};
;         cur = nxt; cA = nA; cB = nB; ++ui;
;         if constexpr (ALIGN_EPI) { if (wr == 1) PG8_BAR; }
	v_add_f32_e32 v175, v175, v242
	s_mov_b64 exec, s[0:1]
	global_atomic_add_f32 v[206:207], v175, off
	s_mov_b64 exec, -1
	s_mov_b64 vcc, 64
	v_lshl_add_u64 v[206:207], v[206:207], 0, vcc
	v_mov_b32_dpp v236, v8 row_ror:8 row_mask:0xf bank_mask:0xf
	v_mov_b32_dpp v237, v9 row_ror:8 row_mask:0xf bank_mask:0xf
	v_mov_b32_dpp v238, v10 row_ror:8 row_mask:0xf bank_mask:0xf
	v_mov_b32_dpp v239, v11 row_ror:8 row_mask:0xf bank_mask:0xf
	v_cndmask_b32_e64 v8, v236, v12, s[34:35]
	v_cndmask_b32_e64 v9, v237, v13, s[34:35]
	v_cndmask_b32_e64 v10, v238, v14, s[34:35]
	v_cndmask_b32_e64 v11, v239, v15, s[34:35]
	v_cndmask_b32_e64 v12, v12, v236, s[34:35]
	v_cndmask_b32_e64 v13, v13, v237, s[34:35]
	v_cndmask_b32_e64 v14, v14, v238, s[34:35]
	v_cndmask_b32_e64 v15, v15, v239, s[34:35]
	v_mov_b32_dpp v236, v0 row_ror:8 row_mask:0xf bank_mask:0xf
	v_mov_b32_dpp v237, v1 row_ror:8 row_mask:0xf bank_mask:0xf
	v_mov_b32_dpp v238, v2 row_ror:8 row_mask:0xf bank_mask:0xf
	v_mov_b32_dpp v239, v3 row_ror:8 row_mask:0xf bank_mask:0xf
	v_cndmask_b32_e64 v0, v236, v4, s[34:35]
	v_cndmask_b32_e64 v1, v237, v5, s[34:35]
	v_cndmask_b32_e64 v2, v238, v6, s[34:35]
	v_cndmask_b32_e64 v3, v239, v7, s[34:35]
	v_cndmask_b32_e64 v4, v4, v236, s[34:35]
	v_cndmask_b32_e64 v5, v5, v237, s[34:35]
	v_cndmask_b32_e64 v6, v6, v238, s[34:35]
	v_cndmask_b32_e64 v7, v7, v239, s[34:35]
	s_waitcnt vmcnt(10)
	v_pk_fma_f32 v[10:11], v[10:11], 0.5, v[186:187] op_sel_hi:[1,0,1]
	v_pk_fma_f32 v[8:9], v[8:9], 0.5, v[184:185] op_sel_hi:[1,0,1]
	global_store_dwordx4 v[218:219], v[8:11], off
	v_pk_mul_f32 v[224:225], v[64:65], v[8:9]
	v_pk_mul_f32 v[226:227], v[66:67], v[10:11]
	v_mul_f32_e32 v175, v8, v8
	v_add_u32_e32 v224, 0x8000, v224
	v_add_u32_e32 v225, 0x8000, v225
	v_add_u32_e32 v226, 0x8000, v226
	v_add_u32_e32 v227, 0x8000, v227
	v_fmac_f32_e32 v175, v9, v9
	v_fmac_f32_e32 v175, v10, v10
	v_fmac_f32_e32 v175, v11, v11
	v_perm_b32 v222, v225, v224, s58
	v_perm_b32 v223, v227, v226, s58
	global_store_dwordx2 v[202:203], v[222:223], off
	v_pk_fma_f32 v[2:3], v[2:3], 0.5, v[190:191] op_sel_hi:[1,0,1]
	v_pk_fma_f32 v[0:1], v[0:1], 0.5, v[188:189] op_sel_hi:[1,0,1]
	global_store_dwordx4 v[218:219], v[0:3], off offset:512
	v_pk_mul_f32 v[228:229], v[72:73], v[0:1]
	v_pk_mul_f32 v[230:231], v[74:75], v[2:3]
	v_fmac_f32_e32 v175, v0, v0
	v_add_u32_e32 v228, 0x8000, v228
	v_add_u32_e32 v229, 0x8000, v229
	v_add_u32_e32 v230, 0x8000, v230
	v_add_u32_e32 v231, 0x8000, v231
	v_fmac_f32_e32 v175, v1, v1
	v_fmac_f32_e32 v175, v2, v2
	v_fmac_f32_e32 v175, v3, v3
	v_perm_b32 v232, v229, v228, s58
	v_perm_b32 v233, v231, v230, s58
	global_store_dwordx2 v[202:203], v[232:233], off offset:256
	v_pk_fma_f32 v[14:15], v[14:15], 0.5, v[194:195] op_sel_hi:[1,0,1]
	v_pk_fma_f32 v[12:13], v[12:13], 0.5, v[192:193] op_sel_hi:[1,0,1]
	global_store_dwordx4 v[220:221], v[12:15], off
	v_pk_mul_f32 v[224:225], v[80:81], v[12:13]
	v_pk_mul_f32 v[226:227], v[82:83], v[14:15]
	v_mul_f32_e32 v234, v12, v12
	v_add_u32_e32 v224, 0x8000, v224
	v_add_u32_e32 v225, 0x8000, v225
	v_add_u32_e32 v226, 0x8000, v226
	v_add_u32_e32 v227, 0x8000, v227
	v_fmac_f32_e32 v234, v13, v13
	v_fmac_f32_e32 v234, v14, v14
	v_fmac_f32_e32 v234, v15, v15
	v_perm_b32 v222, v225, v224, s58
	v_perm_b32 v223, v227, v226, s58
	global_store_dwordx2 v[204:205], v[222:223], off
	v_pk_fma_f32 v[6:7], v[6:7], 0.5, v[198:199] op_sel_hi:[1,0,1]
	v_pk_fma_f32 v[4:5], v[4:5], 0.5, v[196:197] op_sel_hi:[1,0,1]
	global_store_dwordx4 v[220:221], v[4:7], off offset:512
	v_pk_mul_f32 v[228:229], v[84:85], v[4:5]
	v_pk_mul_f32 v[230:231], v[86:87], v[6:7]
	v_fmac_f32_e32 v234, v4, v4
	v_add_u32_e32 v228, 0x8000, v228
	v_add_u32_e32 v229, 0x8000, v229
	v_add_u32_e32 v230, 0x8000, v230
	v_add_u32_e32 v231, 0x8000, v231
	v_fmac_f32_e32 v234, v5, v5
	v_fmac_f32_e32 v234, v6, v6
	v_fmac_f32_e32 v234, v7, v7
	v_perm_b32 v232, v229, v228, s58
	v_perm_b32 v233, v231, v230, s58
	global_store_dwordx2 v[204:205], v[232:233], off offset:256
	s_nop 1
	v_mov_b32_dpp v241, v175 row_ror:8 row_mask:0xf bank_mask:0xf
	v_mov_b32_dpp v242, v234 row_ror:8 row_mask:0xf bank_mask:0xf
	v_add_f32_e32 v175, v175, v241
	v_add_f32_e32 v234, v234, v242
	v_cndmask_b32_e64 v175, v234, v175, s[34:35]
	s_nop 0
	ds_bpermute_b32 v241, v235, v175
	s_waitcnt lgkmcnt(0)
	v_add_f32_e32 v175, v175, v241
	s_nop 0
	ds_bpermute_b32 v242, v240, v175
	s_waitcnt lgkmcnt(0)
	v_add_f32_e32 v175, v175, v242
	s_mov_b64 exec, s[0:1]
	global_atomic_add_f32 v[206:207], v175, off
	s_mov_b64 exec, -1
	s_and_b64 vcc, exec, s[6:7]
	s_mov_b64 s[4:5], -1
	s_cbranch_vccnz .LBB0_301
	s_andn2_b64 vcc, exec, s[12:13]
	s_cbranch_vccnz .LBB0_300
	s_barrier
	s_branch .LBB0_300

;     __device__ __forceinline__ void operator()(const f32x4 (&acc)[2][2][4][2], const Unit& u, int wr, int wc, int fr, int fq) const {
;         const int row0 = u.pm * BM + wr * 64 + fr, col0 = u.pn * BM + wc * 32 + 4 * fq;
;         const float* rbase = (u.pm * BM < SEQ_P) ? resA : (resB - (size_t)SEQ_P * ldc);
;         f32x4 wv[2][2];
;         if (xn) {
; #pragma unroll
;             for (int bj = 0; bj < 2; ++bj)
; #pragma unroll
;                 for (int n = 0; n < 2; ++n) wv[bj][n] = *(const f32x4*)(wn + col0 + bj * HALF + n * 16);
;         }
; #pragma unroll
;         for (int ai = 0; ai < 2; ++ai)
; #pragma unroll
;             for (int m = 0; m < 4; ++m) {
;                 const int row = row0 + ai * HALF + m * 16;
;                 const size_t off = (size_t)row * ldc + col0;
;                 float q = 0.f;
; #pragma unroll
;                 for (int bj = 0; bj < 2; ++bj)
; #pragma unroll
;                     for (int n = 0; n < 2; ++n) {
;                         const f32x4 rv = *(const f32x4*)(rbase + off + bj * HALF + n * 16);
;                         const f32x4 v = rv + acc[ai][bj][m][n] * scale;
;                         if (out) *(f32x4*)(out + off + bj * HALF + n * 16) = v;
;                         if (xn) { q += (v.x * v.x + v.y * v.y) + (v.z * v.z + v.w * v.w); const f32x4 o = v * wv[bj][n];
;                             u32x2 p; p.x = pk2(o.x, o.y); p.y = pk2(o.z, o.w); *(u32x2*)(xn + off + bj * HALF + n * 16) = p; }
;                     }
;                 if (xn) { q += __shfl_xor(q, 16); q += __shfl_xor(q, 32); if (fq == 0) (void)__hip_atomic_fetch_add(ss + row, q, __ATOMIC_RELAXED, __HIP_MEMORY_SCOPE_AGENT); }
.LBB0_1085:
	v_lshl_add_u32 v212, s34, 8, v164
	v_lshl_or_b32 v214, s4, 8, v168
	v_and_b32_e32 v243, 8, v172
	v_mov_b32_e32 v213, 0
	v_cmp_eq_u32_e64 s[34:35], 0, v243
	v_lshlrev_b32_e32 v173, 1, v243
	v_add_u32_e32 v216, v214, v173
	v_sub_u32_e32 v234, 16, v173
	v_add_u32_e32 v234, v214, v234
	v_mov_b32_e32 v214, v216
	v_mov_b32_e32 v216, v234
	v_mov_b32_e32 v215, 0
	v_mov_b32_e32 v217, 0
	v_sub_u32_e32 v210, v212, v243
	v_mov_b32_e32 v211, 0
	v_lshlrev_b64 v[208:209], 11, v[210:211]
	v_add_u32_e32 v210, 8, v210
	v_lshlrev_b64 v[210:211], 11, v[210:211]
	v_lshl_add_u64 v[208:209], v[208:209], 0, v[214:215]
	v_lshl_add_u64 v[210:211], v[210:211], 0, v[216:217]
	v_lshl_add_u64 v[174:175], v[208:209], 2, s[8:9]
	v_lshl_add_u64 v[200:201], v[210:211], 2, s[8:9]
	v_lshl_add_u64 v[202:203], v[214:215], 2, s[10:11]
	v_lshl_add_u64 v[204:205], v[216:217], 2, s[10:11]
	global_load_dwordx4 v[64:67], v[202:203], off
	global_load_dwordx4 v[72:75], v[202:203], off offset:512
	global_load_dwordx4 v[76:79], v[204:205], off
	global_load_dwordx4 v[84:87], v[204:205], off offset:512
	global_load_dwordx4 v[156:159], v[174:175], off nt
	global_load_dwordx4 v[160:163], v[174:175], off offset:512 nt
	global_load_dwordx4 v[176:179], v[200:201], off nt
	global_load_dwordx4 v[180:183], v[200:201], off offset:512 nt
	s_mov_b64 vcc, 0x20000
	v_lshl_add_u64 v[174:175], v[174:175], 0, vcc
	v_lshl_add_u64 v[200:201], v[200:201], 0, vcc
	global_load_dwordx4 v[184:187], v[174:175], off nt
	global_load_dwordx4 v[188:191], v[174:175], off offset:512 nt
	global_load_dwordx4 v[192:195], v[200:201], off nt
	global_load_dwordx4 v[196:199], v[200:201], off offset:512 nt
	s_mov_b64 vcc, 0x20000
	v_lshl_add_u64 v[174:175], v[174:175], 0, vcc
	v_lshl_add_u64 v[200:201], v[200:201], 0, vcc
	v_lshl_add_u64 v[218:219], v[208:209], 2, s[8:9]
	v_lshl_add_u64 v[220:221], v[210:211], 2, s[8:9]
	v_lshl_add_u64 v[202:203], v[208:209], 1, s[14:15]
	v_lshl_add_u64 v[204:205], v[210:211], 1, s[14:15]
	v_lshl_add_u64 v[206:207], v[212:213], 2, s[16:17]
	v_xor_b32_e32 v235, 16, v172
	v_xor_b32_e32 v240, 32, v172
	v_lshlrev_b32_e32 v235, 2, v235
	v_lshlrev_b32_e32 v240, 2, v240
	v_mov_b32_dpp v236, v136 row_ror:8 row_mask:0xf bank_mask:0xf
	v_mov_b32_dpp v237, v137 row_ror:8 row_mask:0xf bank_mask:0xf
	v_mov_b32_dpp v238, v138 row_ror:8 row_mask:0xf bank_mask:0xf
	v_mov_b32_dpp v239, v139 row_ror:8 row_mask:0xf bank_mask:0xf
	v_cndmask_b32_e64 v136, v236, v140, s[34:35]
	v_cndmask_b32_e64 v137, v237, v141, s[34:35]
	v_cndmask_b32_e64 v138, v238, v142, s[34:35]
	v_cndmask_b32_e64 v139, v239, v143, s[34:35]
	v_cndmask_b32_e64 v140, v140, v236, s[34:35]
	v_cndmask_b32_e64 v141, v141, v237, s[34:35]
	v_cndmask_b32_e64 v142, v142, v238, s[34:35]
	v_cndmask_b32_e64 v143, v143, v239, s[34:35]
	v_mov_b32_dpp v236, v128 row_ror:8 row_mask:0xf bank_mask:0xf
	v_mov_b32_dpp v237, v129 row_ror:8 row_mask:0xf bank_mask:0xf
	v_mov_b32_dpp v238, v130 row_ror:8 row_mask:0xf bank_mask:0xf
	v_mov_b32_dpp v239, v131 row_ror:8 row_mask:0xf bank_mask:0xf
	v_cndmask_b32_e64 v128, v236, v132, s[34:35]
	v_cndmask_b32_e64 v129, v237, v133, s[34:35]
	v_cndmask_b32_e64 v130, v238, v134, s[34:35]
	v_cndmask_b32_e64 v131, v239, v135, s[34:35]
	v_cndmask_b32_e64 v132, v132, v236, s[34:35]
	v_cndmask_b32_e64 v133, v133, v237, s[34:35]
	v_cndmask_b32_e64 v134, v134, v238, s[34:35]
	v_cndmask_b32_e64 v135, v135, v239, s[34:35]
	s_waitcnt vmcnt(4)
	v_pk_add_f32 v[138:139], v[138:139], v[158:159]
	v_pk_add_f32 v[136:137], v[136:137], v[156:157]
	global_store_dwordx4 v[218:219], v[136:139], off
	v_pk_mul_f32 v[224:225], v[64:65], v[136:137]
	v_pk_mul_f32 v[226:227], v[66:67], v[138:139]
	v_mul_f32_e32 v173, v136, v136
	v_add_u32_e32 v224, 0x8000, v224
	v_add_u32_e32 v225, 0x8000, v225
	v_add_u32_e32 v226, 0x8000, v226
	v_add_u32_e32 v227, 0x8000, v227
	v_fmac_f32_e32 v173, v137, v137
	v_fmac_f32_e32 v173, v138, v138
	v_fmac_f32_e32 v173, v139, v139
	v_perm_b32 v222, v225, v224, s58
	v_perm_b32 v223, v227, v226, s58
	global_store_dwordx2 v[202:203], v[222:223], off
	v_pk_add_f32 v[130:131], v[130:131], v[162:163]
	v_pk_add_f32 v[128:129], v[128:129], v[160:161]
	global_store_dwordx4 v[218:219], v[128:131], off offset:512
	v_pk_mul_f32 v[228:229], v[72:73], v[128:129]
	v_pk_mul_f32 v[230:231], v[74:75], v[130:131]
	v_fmac_f32_e32 v173, v128, v128
	v_add_u32_e32 v228, 0x8000, v228
	v_add_u32_e32 v229, 0x8000, v229
	v_add_u32_e32 v230, 0x8000, v230
	v_add_u32_e32 v231, 0x8000, v231
	v_fmac_f32_e32 v173, v129, v129
	v_fmac_f32_e32 v173, v130, v130
	v_fmac_f32_e32 v173, v131, v131
	v_perm_b32 v232, v229, v228, s58
	v_perm_b32 v233, v231, v230, s58
	global_store_dwordx2 v[202:203], v[232:233], off offset:256
	v_pk_add_f32 v[142:143], v[142:143], v[178:179]
	v_pk_add_f32 v[140:141], v[140:141], v[176:177]
	global_store_dwordx4 v[220:221], v[140:143], off
	v_pk_mul_f32 v[224:225], v[76:77], v[140:141]
	v_pk_mul_f32 v[226:227], v[78:79], v[142:143]
	v_mul_f32_e32 v234, v140, v140
	v_add_u32_e32 v224, 0x8000, v224
	v_add_u32_e32 v225, 0x8000, v225
	v_add_u32_e32 v226, 0x8000, v226
	v_add_u32_e32 v227, 0x8000, v227
	v_fmac_f32_e32 v234, v141, v141
	v_fmac_f32_e32 v234, v142, v142
	v_fmac_f32_e32 v234, v143, v143
	v_perm_b32 v222, v225, v224, s58
	v_perm_b32 v223, v227, v226, s58
	global_store_dwordx2 v[204:205], v[222:223], off
	v_pk_add_f32 v[134:135], v[134:135], v[182:183]
	v_pk_add_f32 v[132:133], v[132:133], v[180:181]
	global_store_dwordx4 v[220:221], v[132:135], off offset:512
	v_pk_mul_f32 v[228:229], v[84:85], v[132:133]
	v_pk_mul_f32 v[230:231], v[86:87], v[134:135]
	v_fmac_f32_e32 v234, v132, v132
	v_add_u32_e32 v228, 0x8000, v228
	v_add_u32_e32 v229, 0x8000, v229
	v_add_u32_e32 v230, 0x8000, v230
	v_add_u32_e32 v231, 0x8000, v231
	v_fmac_f32_e32 v234, v133, v133
	v_fmac_f32_e32 v234, v134, v134
	v_fmac_f32_e32 v234, v135, v135
	v_perm_b32 v232, v229, v228, s58
	v_perm_b32 v233, v231, v230, s58
	global_store_dwordx2 v[204:205], v[232:233], off offset:256
	s_nop 1
	v_mov_b32_dpp v241, v173 row_ror:8 row_mask:0xf bank_mask:0xf
	v_mov_b32_dpp v242, v234 row_ror:8 row_mask:0xf bank_mask:0xf
	v_add_f32_e32 v173, v173, v241
	v_add_f32_e32 v234, v234, v242
	v_cndmask_b32_e64 v173, v234, v173, s[34:35]
	s_nop 0
	ds_bpermute_b32 v241, v235, v173
	global_load_dwordx4 v[156:159], v[174:175], off nt
	global_load_dwordx4 v[160:163], v[174:175], off offset:512 nt
	global_load_dwordx4 v[176:179], v[200:201], off nt
	global_load_dwordx4 v[180:183], v[200:201], off offset:512 nt
	s_mov_b64 vcc, 0x20000
	v_lshl_add_u64 v[174:175], v[174:175], 0, vcc
	v_lshl_add_u64 v[200:201], v[200:201], 0, vcc
	s_mov_b64 vcc, 0x20000
	v_lshl_add_u64 v[218:219], v[218:219], 0, vcc
	v_lshl_add_u64 v[220:221], v[220:221], 0, vcc
	s_mov_b64 vcc, 0x10000
	v_lshl_add_u64 v[202:203], v[202:203], 0, vcc
	v_lshl_add_u64 v[204:205], v[204:205], 0, vcc
	s_waitcnt lgkmcnt(0)
;     __device__ __forceinline__ void operator()(const f32x4 (&acc)[2][2][4][2], const Unit& u, int wr, int wc, int fr, int fq) const {
;     ...
;         for (int ai = 0; ai < 2; ++ai)
; #pragma unroll
;             for (int m = 0; m < 4; ++m) {
;                 const int row = row0 + ai * HALF + m * 16;
;                 const size_t off = (size_t)row * ldc + col0;
;                 float q = 0.f;
; #pragma unroll
;                 for (int bj = 0; bj < 2; ++bj)
; #pragma unroll
;                     for (int n = 0; n < 2; ++n) {
;                         const f32x4 rv = *(const f32x4*)(rbase + off + bj * HALF + n * 16);
;                         const f32x4 v = rv + acc[ai][bj][m][n] * scale;
;                         if (out) *(f32x4*)(out + off + bj * HALF + n * 16) = v;
;                         if (xn) { q += (v.x * v.x + v.y * v.y) + (v.z * v.z + v.w * v.w); const f32x4 o = v * wv[bj][n];
;                             u32x2 p; p.x = pk2(o.x, o.y); p.y = pk2(o.z, o.w); *(u32x2*)(xn + off + bj * HALF + n * 16) = p; }
;                     }
;                 if (xn) { q += __shfl_xor(q, 16); q += __shfl_xor(q, 32); if (fq == 0) (void)__hip_atomic_fetch_add(ss + row, q, __ATOMIC_RELAXED, __HIP_MEMORY_SCOPE_AGENT); }
;             }
	v_add_f32_e32 v173, v173, v241
	s_nop 0
	ds_bpermute_b32 v242, v240, v173
	s_waitcnt lgkmcnt(0)
	v_add_f32_e32 v173, v173, v242
	s_mov_b64 exec, s[0:1]
	global_atomic_add_f32 v[206:207], v173, off
	s_mov_b64 exec, -1
	s_mov_b64 vcc, 64
	v_lshl_add_u64 v[206:207], v[206:207], 0, vcc
	v_mov_b32_dpp v236, v120 row_ror:8 row_mask:0xf bank_mask:0xf
	v_mov_b32_dpp v237, v121 row_ror:8 row_mask:0xf bank_mask:0xf
	v_mov_b32_dpp v238, v122 row_ror:8 row_mask:0xf bank_mask:0xf
	v_mov_b32_dpp v239, v123 row_ror:8 row_mask:0xf bank_mask:0xf
	v_cndmask_b32_e64 v120, v236, v124, s[34:35]
	v_cndmask_b32_e64 v121, v237, v125, s[34:35]
	v_cndmask_b32_e64 v122, v238, v126, s[34:35]
	v_cndmask_b32_e64 v123, v239, v127, s[34:35]
	v_cndmask_b32_e64 v124, v124, v236, s[34:35]
	v_cndmask_b32_e64 v125, v125, v237, s[34:35]
	v_cndmask_b32_e64 v126, v126, v238, s[34:35]
	v_cndmask_b32_e64 v127, v127, v239, s[34:35]
	v_mov_b32_dpp v236, v112 row_ror:8 row_mask:0xf bank_mask:0xf
	v_mov_b32_dpp v237, v113 row_ror:8 row_mask:0xf bank_mask:0xf
	v_mov_b32_dpp v238, v114 row_ror:8 row_mask:0xf bank_mask:0xf
	v_mov_b32_dpp v239, v115 row_ror:8 row_mask:0xf bank_mask:0xf
	v_cndmask_b32_e64 v112, v236, v116, s[34:35]
	v_cndmask_b32_e64 v113, v237, v117, s[34:35]
	v_cndmask_b32_e64 v114, v238, v118, s[34:35]
	v_cndmask_b32_e64 v115, v239, v119, s[34:35]
	v_cndmask_b32_e64 v116, v116, v236, s[34:35]
	v_cndmask_b32_e64 v117, v117, v237, s[34:35]
	v_cndmask_b32_e64 v118, v118, v238, s[34:35]
	v_cndmask_b32_e64 v119, v119, v239, s[34:35]
	s_waitcnt vmcnt(13)
	v_pk_add_f32 v[122:123], v[122:123], v[186:187]
	v_pk_add_f32 v[120:121], v[120:121], v[184:185]
	global_store_dwordx4 v[218:219], v[120:123], off
	v_pk_mul_f32 v[224:225], v[64:65], v[120:121]
	v_pk_mul_f32 v[226:227], v[66:67], v[122:123]
	v_mul_f32_e32 v173, v120, v120
	v_add_u32_e32 v224, 0x8000, v224
	v_add_u32_e32 v225, 0x8000, v225
	v_add_u32_e32 v226, 0x8000, v226
	v_add_u32_e32 v227, 0x8000, v227
	v_fmac_f32_e32 v173, v121, v121
	v_fmac_f32_e32 v173, v122, v122
	v_fmac_f32_e32 v173, v123, v123
	v_perm_b32 v222, v225, v224, s58
	v_perm_b32 v223, v227, v226, s58
	global_store_dwordx2 v[202:203], v[222:223], off
	v_pk_add_f32 v[114:115], v[114:115], v[190:191]
	v_pk_add_f32 v[112:113], v[112:113], v[188:189]
	global_store_dwordx4 v[218:219], v[112:115], off offset:512
	v_pk_mul_f32 v[228:229], v[72:73], v[112:113]
	v_pk_mul_f32 v[230:231], v[74:75], v[114:115]
	v_fmac_f32_e32 v173, v112, v112
	v_add_u32_e32 v228, 0x8000, v228
	v_add_u32_e32 v229, 0x8000, v229
	v_add_u32_e32 v230, 0x8000, v230
	v_add_u32_e32 v231, 0x8000, v231
	v_fmac_f32_e32 v173, v113, v113
	v_fmac_f32_e32 v173, v114, v114
	v_fmac_f32_e32 v173, v115, v115
	v_perm_b32 v232, v229, v228, s58
	v_perm_b32 v233, v231, v230, s58
	global_store_dwordx2 v[202:203], v[232:233], off offset:256
	v_pk_add_f32 v[126:127], v[126:127], v[194:195]
	v_pk_add_f32 v[124:125], v[124:125], v[192:193]
	global_store_dwordx4 v[220:221], v[124:127], off
	v_pk_mul_f32 v[224:225], v[76:77], v[124:125]
	v_pk_mul_f32 v[226:227], v[78:79], v[126:127]
	v_mul_f32_e32 v234, v124, v124
	v_add_u32_e32 v224, 0x8000, v224
	v_add_u32_e32 v225, 0x8000, v225
	v_add_u32_e32 v226, 0x8000, v226
	v_add_u32_e32 v227, 0x8000, v227
	v_fmac_f32_e32 v234, v125, v125
	v_fmac_f32_e32 v234, v126, v126
	v_fmac_f32_e32 v234, v127, v127
	v_perm_b32 v222, v225, v224, s58
	v_perm_b32 v223, v227, v226, s58
	global_store_dwordx2 v[204:205], v[222:223], off
	v_pk_add_f32 v[118:119], v[118:119], v[198:199]
	v_pk_add_f32 v[116:117], v[116:117], v[196:197]
	global_store_dwordx4 v[220:221], v[116:119], off offset:512
	v_pk_mul_f32 v[228:229], v[84:85], v[116:117]
	v_pk_mul_f32 v[230:231], v[86:87], v[118:119]
	v_fmac_f32_e32 v234, v116, v116
	v_add_u32_e32 v228, 0x8000, v228
	v_add_u32_e32 v229, 0x8000, v229
	v_add_u32_e32 v230, 0x8000, v230
	v_add_u32_e32 v231, 0x8000, v231
	v_fmac_f32_e32 v234, v117, v117
	v_fmac_f32_e32 v234, v118, v118
	v_fmac_f32_e32 v234, v119, v119
	v_perm_b32 v232, v229, v228, s58
	v_perm_b32 v233, v231, v230, s58
	global_store_dwordx2 v[204:205], v[232:233], off offset:256
	s_nop 1
	v_mov_b32_dpp v241, v173 row_ror:8 row_mask:0xf bank_mask:0xf
	v_mov_b32_dpp v242, v234 row_ror:8 row_mask:0xf bank_mask:0xf
	v_add_f32_e32 v173, v173, v241
	v_add_f32_e32 v234, v234, v242
	v_cndmask_b32_e64 v173, v234, v173, s[34:35]
	s_nop 0
	ds_bpermute_b32 v241, v235, v173
	global_load_dwordx4 v[184:187], v[174:175], off nt
	global_load_dwordx4 v[188:191], v[174:175], off offset:512 nt
	global_load_dwordx4 v[192:195], v[200:201], off nt
	global_load_dwordx4 v[196:199], v[200:201], off offset:512 nt
	s_mov_b64 vcc, 0xa0000
	v_lshl_add_u64 v[174:175], v[174:175], 0, vcc
	v_lshl_add_u64 v[200:201], v[200:201], 0, vcc
	s_mov_b64 vcc, 0x20000
	v_lshl_add_u64 v[218:219], v[218:219], 0, vcc
	v_lshl_add_u64 v[220:221], v[220:221], 0, vcc
	s_mov_b64 vcc, 0x10000
	v_lshl_add_u64 v[202:203], v[202:203], 0, vcc
	v_lshl_add_u64 v[204:205], v[204:205], 0, vcc
	s_waitcnt lgkmcnt(0)
	v_add_f32_e32 v173, v173, v241
	s_nop 0
	ds_bpermute_b32 v242, v240, v173
	s_waitcnt lgkmcnt(0)
;     __device__ __forceinline__ void operator()(const f32x4 (&acc)[2][2][4][2], const Unit& u, int wr, int wc, int fr, int fq) const {
;     ...
;         for (int ai = 0; ai < 2; ++ai)
; #pragma unroll
;             for (int m = 0; m < 4; ++m) {
;                 const int row = row0 + ai * HALF + m * 16;
;                 const size_t off = (size_t)row * ldc + col0;
;                 float q = 0.f;
; #pragma unroll
;                 for (int bj = 0; bj < 2; ++bj)
; #pragma unroll
;                     for (int n = 0; n < 2; ++n) {
;                         const f32x4 rv = *(const f32x4*)(rbase + off + bj * HALF + n * 16);
;                         const f32x4 v = rv + acc[ai][bj][m][n] * scale;
;                         if (out) *(f32x4*)(out + off + bj * HALF + n * 16) = v;
;                         if (xn) { q += (v.x * v.x + v.y * v.y) + (v.z * v.z + v.w * v.w); const f32x4 o = v * wv[bj][n];
;                             u32x2 p; p.x = pk2(o.x, o.y); p.y = pk2(o.z, o.w); *(u32x2*)(xn + off + bj * HALF + n * 16) = p; }
;                     }
;                 if (xn) { q += __shfl_xor(q, 16); q += __shfl_xor(q, 32); if (fq == 0) (void)__hip_atomic_fetch_add(ss + row, q, __ATOMIC_RELAXED, __HIP_MEMORY_SCOPE_AGENT); }
;             }
	v_add_f32_e32 v173, v173, v242
	s_mov_b64 exec, s[0:1]
	global_atomic_add_f32 v[206:207], v173, off
	s_mov_b64 exec, -1
	s_mov_b64 vcc, 64
	v_lshl_add_u64 v[206:207], v[206:207], 0, vcc
	v_mov_b32_dpp v236, v104 row_ror:8 row_mask:0xf bank_mask:0xf
	v_mov_b32_dpp v237, v105 row_ror:8 row_mask:0xf bank_mask:0xf
	v_mov_b32_dpp v238, v106 row_ror:8 row_mask:0xf bank_mask:0xf
	v_mov_b32_dpp v239, v107 row_ror:8 row_mask:0xf bank_mask:0xf
	v_cndmask_b32_e64 v104, v236, v108, s[34:35]
	v_cndmask_b32_e64 v105, v237, v109, s[34:35]
	v_cndmask_b32_e64 v106, v238, v110, s[34:35]
	v_cndmask_b32_e64 v107, v239, v111, s[34:35]
	v_cndmask_b32_e64 v108, v108, v236, s[34:35]
	v_cndmask_b32_e64 v109, v109, v237, s[34:35]
	v_cndmask_b32_e64 v110, v110, v238, s[34:35]
	v_cndmask_b32_e64 v111, v111, v239, s[34:35]
	v_mov_b32_dpp v236, v96 row_ror:8 row_mask:0xf bank_mask:0xf
	v_mov_b32_dpp v237, v97 row_ror:8 row_mask:0xf bank_mask:0xf
	v_mov_b32_dpp v238, v98 row_ror:8 row_mask:0xf bank_mask:0xf
	v_mov_b32_dpp v239, v99 row_ror:8 row_mask:0xf bank_mask:0xf
	v_cndmask_b32_e64 v96, v236, v100, s[34:35]
	v_cndmask_b32_e64 v97, v237, v101, s[34:35]
	v_cndmask_b32_e64 v98, v238, v102, s[34:35]
	v_cndmask_b32_e64 v99, v239, v103, s[34:35]
	v_cndmask_b32_e64 v100, v100, v236, s[34:35]
	v_cndmask_b32_e64 v101, v101, v237, s[34:35]
	v_cndmask_b32_e64 v102, v102, v238, s[34:35]
	v_cndmask_b32_e64 v103, v103, v239, s[34:35]
	s_waitcnt vmcnt(14)
	v_pk_add_f32 v[106:107], v[106:107], v[158:159]
	v_pk_add_f32 v[104:105], v[104:105], v[156:157]
	global_store_dwordx4 v[218:219], v[104:107], off
	v_pk_mul_f32 v[224:225], v[64:65], v[104:105]
	v_pk_mul_f32 v[226:227], v[66:67], v[106:107]
	v_mul_f32_e32 v173, v104, v104
	v_add_u32_e32 v224, 0x8000, v224
	v_add_u32_e32 v225, 0x8000, v225
	v_add_u32_e32 v226, 0x8000, v226
	v_add_u32_e32 v227, 0x8000, v227
	v_fmac_f32_e32 v173, v105, v105
	v_fmac_f32_e32 v173, v106, v106
	v_fmac_f32_e32 v173, v107, v107
	v_perm_b32 v222, v225, v224, s58
	v_perm_b32 v223, v227, v226, s58
	global_store_dwordx2 v[202:203], v[222:223], off
	v_pk_add_f32 v[98:99], v[98:99], v[162:163]
	v_pk_add_f32 v[96:97], v[96:97], v[160:161]
	global_store_dwordx4 v[218:219], v[96:99], off offset:512
	v_pk_mul_f32 v[228:229], v[72:73], v[96:97]
	v_pk_mul_f32 v[230:231], v[74:75], v[98:99]
	v_fmac_f32_e32 v173, v96, v96
	v_add_u32_e32 v228, 0x8000, v228
	v_add_u32_e32 v229, 0x8000, v229
	v_add_u32_e32 v230, 0x8000, v230
	v_add_u32_e32 v231, 0x8000, v231
	v_fmac_f32_e32 v173, v97, v97
	v_fmac_f32_e32 v173, v98, v98
	v_fmac_f32_e32 v173, v99, v99
	v_perm_b32 v232, v229, v228, s58
	v_perm_b32 v233, v231, v230, s58
	global_store_dwordx2 v[202:203], v[232:233], off offset:256
	v_pk_add_f32 v[110:111], v[110:111], v[178:179]
	v_pk_add_f32 v[108:109], v[108:109], v[176:177]
	global_store_dwordx4 v[220:221], v[108:111], off
	v_pk_mul_f32 v[224:225], v[76:77], v[108:109]
	v_pk_mul_f32 v[226:227], v[78:79], v[110:111]
	v_mul_f32_e32 v234, v108, v108
	v_add_u32_e32 v224, 0x8000, v224
	v_add_u32_e32 v225, 0x8000, v225
	v_add_u32_e32 v226, 0x8000, v226
	v_add_u32_e32 v227, 0x8000, v227
	v_fmac_f32_e32 v234, v109, v109
	v_fmac_f32_e32 v234, v110, v110
	v_fmac_f32_e32 v234, v111, v111
	v_perm_b32 v222, v225, v224, s58
	v_perm_b32 v223, v227, v226, s58
	global_store_dwordx2 v[204:205], v[222:223], off
	v_pk_add_f32 v[102:103], v[102:103], v[182:183]
	v_pk_add_f32 v[100:101], v[100:101], v[180:181]
	global_store_dwordx4 v[220:221], v[100:103], off offset:512
	v_pk_mul_f32 v[228:229], v[84:85], v[100:101]
	v_pk_mul_f32 v[230:231], v[86:87], v[102:103]
	v_fmac_f32_e32 v234, v100, v100
	v_add_u32_e32 v228, 0x8000, v228
	v_add_u32_e32 v229, 0x8000, v229
	v_add_u32_e32 v230, 0x8000, v230
	v_add_u32_e32 v231, 0x8000, v231
	v_fmac_f32_e32 v234, v101, v101
	v_fmac_f32_e32 v234, v102, v102
	v_fmac_f32_e32 v234, v103, v103
	v_perm_b32 v232, v229, v228, s58
	v_perm_b32 v233, v231, v230, s58
	global_store_dwordx2 v[204:205], v[232:233], off offset:256
	s_nop 1
	v_mov_b32_dpp v241, v173 row_ror:8 row_mask:0xf bank_mask:0xf
	v_mov_b32_dpp v242, v234 row_ror:8 row_mask:0xf bank_mask:0xf
	v_add_f32_e32 v173, v173, v241
	v_add_f32_e32 v234, v234, v242
	v_cndmask_b32_e64 v173, v234, v173, s[34:35]
	s_nop 0
	ds_bpermute_b32 v241, v235, v173
	global_load_dwordx4 v[156:159], v[174:175], off nt
	global_load_dwordx4 v[160:163], v[174:175], off offset:512 nt
	global_load_dwordx4 v[176:179], v[200:201], off nt
	global_load_dwordx4 v[180:183], v[200:201], off offset:512 nt
	s_mov_b64 vcc, 0x20000
	v_lshl_add_u64 v[174:175], v[174:175], 0, vcc
	v_lshl_add_u64 v[200:201], v[200:201], 0, vcc
	s_mov_b64 vcc, 0x20000
	v_lshl_add_u64 v[218:219], v[218:219], 0, vcc
	v_lshl_add_u64 v[220:221], v[220:221], 0, vcc
	s_mov_b64 vcc, 0x10000
	v_lshl_add_u64 v[202:203], v[202:203], 0, vcc
	v_lshl_add_u64 v[204:205], v[204:205], 0, vcc
	s_waitcnt lgkmcnt(0)
	v_add_f32_e32 v173, v173, v241
	s_nop 0
	ds_bpermute_b32 v242, v240, v173
	s_waitcnt lgkmcnt(0)
;     __device__ __forceinline__ void operator()(const f32x4 (&acc)[2][2][4][2], const Unit& u, int wr, int wc, int fr, int fq) const {
;     ...
;         for (int ai = 0; ai < 2; ++ai)
; #pragma unroll
;             for (int m = 0; m < 4; ++m) {
;                 const int row = row0 + ai * HALF + m * 16;
;                 const size_t off = (size_t)row * ldc + col0;
;                 float q = 0.f;
; #pragma unroll
;                 for (int bj = 0; bj < 2; ++bj)
; #pragma unroll
;                     for (int n = 0; n < 2; ++n) {
;                         const f32x4 rv = *(const f32x4*)(rbase + off + bj * HALF + n * 16);
;                         const f32x4 v = rv + acc[ai][bj][m][n] * scale;
;                         if (out) *(f32x4*)(out + off + bj * HALF + n * 16) = v;
;                         if (xn) { q += (v.x * v.x + v.y * v.y) + (v.z * v.z + v.w * v.w); const f32x4 o = v * wv[bj][n];
;                             u32x2 p; p.x = pk2(o.x, o.y); p.y = pk2(o.z, o.w); *(u32x2*)(xn + off + bj * HALF + n * 16) = p; }
;                     }
;                 if (xn) { q += __shfl_xor(q, 16); q += __shfl_xor(q, 32); if (fq == 0) (void)__hip_atomic_fetch_add(ss + row, q, __ATOMIC_RELAXED, __HIP_MEMORY_SCOPE_AGENT); }
;             }
	v_add_f32_e32 v173, v173, v242
	s_mov_b64 exec, s[0:1]
	global_atomic_add_f32 v[206:207], v173, off
	s_mov_b64 exec, -1
	s_mov_b64 vcc, 64
	v_lshl_add_u64 v[206:207], v[206:207], 0, vcc
	v_mov_b32_dpp v236, v88 row_ror:8 row_mask:0xf bank_mask:0xf
	v_mov_b32_dpp v237, v89 row_ror:8 row_mask:0xf bank_mask:0xf
	v_mov_b32_dpp v238, v90 row_ror:8 row_mask:0xf bank_mask:0xf
	v_mov_b32_dpp v239, v91 row_ror:8 row_mask:0xf bank_mask:0xf
	v_cndmask_b32_e64 v88, v236, v92, s[34:35]
	v_cndmask_b32_e64 v89, v237, v93, s[34:35]
	v_cndmask_b32_e64 v90, v238, v94, s[34:35]
	v_cndmask_b32_e64 v91, v239, v95, s[34:35]
	v_cndmask_b32_e64 v92, v92, v236, s[34:35]
	v_cndmask_b32_e64 v93, v93, v237, s[34:35]
	v_cndmask_b32_e64 v94, v94, v238, s[34:35]
	v_cndmask_b32_e64 v95, v95, v239, s[34:35]
	v_mov_b32_dpp v236, v68 row_ror:8 row_mask:0xf bank_mask:0xf
	v_mov_b32_dpp v237, v69 row_ror:8 row_mask:0xf bank_mask:0xf
	v_mov_b32_dpp v238, v70 row_ror:8 row_mask:0xf bank_mask:0xf
	v_mov_b32_dpp v239, v71 row_ror:8 row_mask:0xf bank_mask:0xf
	v_cndmask_b32_e64 v68, v236, v80, s[34:35]
	v_cndmask_b32_e64 v69, v237, v81, s[34:35]
	v_cndmask_b32_e64 v70, v238, v82, s[34:35]
	v_cndmask_b32_e64 v71, v239, v83, s[34:35]
	v_cndmask_b32_e64 v80, v80, v236, s[34:35]
	v_cndmask_b32_e64 v81, v81, v237, s[34:35]
	v_cndmask_b32_e64 v82, v82, v238, s[34:35]
	v_cndmask_b32_e64 v83, v83, v239, s[34:35]
	s_waitcnt vmcnt(14)
	v_pk_add_f32 v[90:91], v[90:91], v[186:187]
	v_pk_add_f32 v[88:89], v[88:89], v[184:185]
	global_store_dwordx4 v[218:219], v[88:91], off
	v_pk_mul_f32 v[224:225], v[64:65], v[88:89]
	v_pk_mul_f32 v[226:227], v[66:67], v[90:91]
	v_mul_f32_e32 v173, v88, v88
	v_add_u32_e32 v224, 0x8000, v224
	v_add_u32_e32 v225, 0x8000, v225
	v_add_u32_e32 v226, 0x8000, v226
	v_add_u32_e32 v227, 0x8000, v227
	v_fmac_f32_e32 v173, v89, v89
	v_fmac_f32_e32 v173, v90, v90
	v_fmac_f32_e32 v173, v91, v91
	v_perm_b32 v222, v225, v224, s58
	v_perm_b32 v223, v227, v226, s58
	global_store_dwordx2 v[202:203], v[222:223], off
	v_pk_add_f32 v[70:71], v[70:71], v[190:191]
	v_pk_add_f32 v[68:69], v[68:69], v[188:189]
	global_store_dwordx4 v[218:219], v[68:71], off offset:512
	v_pk_mul_f32 v[228:229], v[72:73], v[68:69]
	v_pk_mul_f32 v[230:231], v[74:75], v[70:71]
	v_fmac_f32_e32 v173, v68, v68
	v_add_u32_e32 v228, 0x8000, v228
	v_add_u32_e32 v229, 0x8000, v229
	v_add_u32_e32 v230, 0x8000, v230
	v_add_u32_e32 v231, 0x8000, v231
	v_fmac_f32_e32 v173, v69, v69
	v_fmac_f32_e32 v173, v70, v70
	v_fmac_f32_e32 v173, v71, v71
	v_perm_b32 v232, v229, v228, s58
	v_perm_b32 v233, v231, v230, s58
	global_store_dwordx2 v[202:203], v[232:233], off offset:256
	v_pk_add_f32 v[94:95], v[94:95], v[194:195]
	v_pk_add_f32 v[92:93], v[92:93], v[192:193]
	global_store_dwordx4 v[220:221], v[92:95], off
	v_pk_mul_f32 v[224:225], v[76:77], v[92:93]
	v_pk_mul_f32 v[226:227], v[78:79], v[94:95]
	v_mul_f32_e32 v234, v92, v92
	v_add_u32_e32 v224, 0x8000, v224
	v_add_u32_e32 v225, 0x8000, v225
	v_add_u32_e32 v226, 0x8000, v226
	v_add_u32_e32 v227, 0x8000, v227
	v_fmac_f32_e32 v234, v93, v93
	v_fmac_f32_e32 v234, v94, v94
	v_fmac_f32_e32 v234, v95, v95
	v_perm_b32 v222, v225, v224, s58
	v_perm_b32 v223, v227, v226, s58
	global_store_dwordx2 v[204:205], v[222:223], off
	v_pk_add_f32 v[82:83], v[82:83], v[198:199]
	v_pk_add_f32 v[80:81], v[80:81], v[196:197]
	global_store_dwordx4 v[220:221], v[80:83], off offset:512
	v_pk_mul_f32 v[228:229], v[84:85], v[80:81]
	v_pk_mul_f32 v[230:231], v[86:87], v[82:83]
	v_fmac_f32_e32 v234, v80, v80
	v_add_u32_e32 v228, 0x8000, v228
	v_add_u32_e32 v229, 0x8000, v229
	v_add_u32_e32 v230, 0x8000, v230
	v_add_u32_e32 v231, 0x8000, v231
	v_fmac_f32_e32 v234, v81, v81
	v_fmac_f32_e32 v234, v82, v82
	v_fmac_f32_e32 v234, v83, v83
	v_perm_b32 v232, v229, v228, s58
	v_perm_b32 v233, v231, v230, s58
	global_store_dwordx2 v[204:205], v[232:233], off offset:256
	s_nop 1
	v_mov_b32_dpp v241, v173 row_ror:8 row_mask:0xf bank_mask:0xf
	v_mov_b32_dpp v242, v234 row_ror:8 row_mask:0xf bank_mask:0xf
	v_add_f32_e32 v173, v173, v241
	v_add_f32_e32 v234, v234, v242
	v_cndmask_b32_e64 v173, v234, v173, s[34:35]
	s_nop 0
	ds_bpermute_b32 v241, v235, v173
	global_load_dwordx4 v[184:187], v[174:175], off nt
	global_load_dwordx4 v[188:191], v[174:175], off offset:512 nt
	global_load_dwordx4 v[192:195], v[200:201], off nt
	global_load_dwordx4 v[196:199], v[200:201], off offset:512 nt
	s_mov_b64 vcc, 0x20000
	v_lshl_add_u64 v[174:175], v[174:175], 0, vcc
	v_lshl_add_u64 v[200:201], v[200:201], 0, vcc
	s_mov_b64 vcc, 0xa0000
	v_lshl_add_u64 v[218:219], v[218:219], 0, vcc
	v_lshl_add_u64 v[220:221], v[220:221], 0, vcc
	s_mov_b64 vcc, 0x50000
	v_lshl_add_u64 v[202:203], v[202:203], 0, vcc
	v_lshl_add_u64 v[204:205], v[204:205], 0, vcc
	s_waitcnt lgkmcnt(0)
	v_add_f32_e32 v173, v173, v241
	s_nop 0
	ds_bpermute_b32 v242, v240, v173
	s_waitcnt lgkmcnt(0)
	v_add_f32_e32 v173, v173, v242
	s_mov_b64 exec, s[0:1]
	global_atomic_add_f32 v[206:207], v173, off
	s_mov_b64 exec, -1
	s_mov_b64 vcc, 320
	v_lshl_add_u64 v[206:207], v[206:207], 0, vcc
	v_mov_b32_dpp v236, v56 row_ror:8 row_mask:0xf bank_mask:0xf
	v_mov_b32_dpp v237, v57 row_ror:8 row_mask:0xf bank_mask:0xf
	v_mov_b32_dpp v238, v58 row_ror:8 row_mask:0xf bank_mask:0xf
	v_mov_b32_dpp v239, v59 row_ror:8 row_mask:0xf bank_mask:0xf
	v_cndmask_b32_e64 v56, v236, v60, s[34:35]
	v_cndmask_b32_e64 v57, v237, v61, s[34:35]
	v_cndmask_b32_e64 v58, v238, v62, s[34:35]
	v_cndmask_b32_e64 v59, v239, v63, s[34:35]
	v_cndmask_b32_e64 v60, v60, v236, s[34:35]
	v_cndmask_b32_e64 v61, v61, v237, s[34:35]
	v_cndmask_b32_e64 v62, v62, v238, s[34:35]
	v_cndmask_b32_e64 v63, v63, v239, s[34:35]
	v_mov_b32_dpp v236, v48 row_ror:8 row_mask:0xf bank_mask:0xf
	v_mov_b32_dpp v237, v49 row_ror:8 row_mask:0xf bank_mask:0xf
	v_mov_b32_dpp v238, v50 row_ror:8 row_mask:0xf bank_mask:0xf
	v_mov_b32_dpp v239, v51 row_ror:8 row_mask:0xf bank_mask:0xf
	v_cndmask_b32_e64 v48, v236, v52, s[34:35]
	v_cndmask_b32_e64 v49, v237, v53, s[34:35]
	v_cndmask_b32_e64 v50, v238, v54, s[34:35]
	v_cndmask_b32_e64 v51, v239, v55, s[34:35]
	v_cndmask_b32_e64 v52, v52, v236, s[34:35]
	v_cndmask_b32_e64 v53, v53, v237, s[34:35]
	v_cndmask_b32_e64 v54, v54, v238, s[34:35]
	v_cndmask_b32_e64 v55, v55, v239, s[34:35]
	s_waitcnt vmcnt(14)
;     __device__ __forceinline__ void operator()(const f32x4 (&acc)[2][2][4][2], const Unit& u, int wr, int wc, int fr, int fq) const {
;     ...
;         for (int ai = 0; ai < 2; ++ai)
; #pragma unroll
;             for (int m = 0; m < 4; ++m) {
;                 const int row = row0 + ai * HALF + m * 16;
;                 const size_t off = (size_t)row * ldc + col0;
;                 float q = 0.f;
; #pragma unroll
;                 for (int bj = 0; bj < 2; ++bj)
; #pragma unroll
;                     for (int n = 0; n < 2; ++n) {
;                         const f32x4 rv = *(const f32x4*)(rbase + off + bj * HALF + n * 16);
;                         const f32x4 v = rv + acc[ai][bj][m][n] * scale;
;                         if (out) *(f32x4*)(out + off + bj * HALF + n * 16) = v;
;                         if (xn) { q += (v.x * v.x + v.y * v.y) + (v.z * v.z + v.w * v.w); const f32x4 o = v * wv[bj][n];
;                             u32x2 p; p.x = pk2(o.x, o.y); p.y = pk2(o.z, o.w); *(u32x2*)(xn + off + bj * HALF + n * 16) = p; }
;                     }
;                 if (xn) { q += __shfl_xor(q, 16); q += __shfl_xor(q, 32); if (fq == 0) (void)__hip_atomic_fetch_add(ss + row, q, __ATOMIC_RELAXED, __HIP_MEMORY_SCOPE_AGENT); }
;             }
	v_pk_add_f32 v[58:59], v[58:59], v[158:159]
	v_pk_add_f32 v[56:57], v[56:57], v[156:157]
	global_store_dwordx4 v[218:219], v[56:59], off
	v_pk_mul_f32 v[224:225], v[64:65], v[56:57]
	v_pk_mul_f32 v[226:227], v[66:67], v[58:59]
	v_mul_f32_e32 v173, v56, v56
	v_add_u32_e32 v224, 0x8000, v224
	v_add_u32_e32 v225, 0x8000, v225
	v_add_u32_e32 v226, 0x8000, v226
	v_add_u32_e32 v227, 0x8000, v227
	v_fmac_f32_e32 v173, v57, v57
	v_fmac_f32_e32 v173, v58, v58
	v_fmac_f32_e32 v173, v59, v59
	v_perm_b32 v222, v225, v224, s58
	v_perm_b32 v223, v227, v226, s58
	global_store_dwordx2 v[202:203], v[222:223], off
	v_pk_add_f32 v[50:51], v[50:51], v[162:163]
	v_pk_add_f32 v[48:49], v[48:49], v[160:161]
	global_store_dwordx4 v[218:219], v[48:51], off offset:512
	v_pk_mul_f32 v[228:229], v[72:73], v[48:49]
	v_pk_mul_f32 v[230:231], v[74:75], v[50:51]
	v_fmac_f32_e32 v173, v48, v48
	v_add_u32_e32 v228, 0x8000, v228
	v_add_u32_e32 v229, 0x8000, v229
	v_add_u32_e32 v230, 0x8000, v230
	v_add_u32_e32 v231, 0x8000, v231
	v_fmac_f32_e32 v173, v49, v49
	v_fmac_f32_e32 v173, v50, v50
	v_fmac_f32_e32 v173, v51, v51
	v_perm_b32 v232, v229, v228, s58
	v_perm_b32 v233, v231, v230, s58
	global_store_dwordx2 v[202:203], v[232:233], off offset:256
	v_pk_add_f32 v[62:63], v[62:63], v[178:179]
	v_pk_add_f32 v[60:61], v[60:61], v[176:177]
	global_store_dwordx4 v[220:221], v[60:63], off
	v_pk_mul_f32 v[224:225], v[76:77], v[60:61]
	v_pk_mul_f32 v[226:227], v[78:79], v[62:63]
	v_mul_f32_e32 v234, v60, v60
	v_add_u32_e32 v224, 0x8000, v224
	v_add_u32_e32 v225, 0x8000, v225
	v_add_u32_e32 v226, 0x8000, v226
	v_add_u32_e32 v227, 0x8000, v227
	v_fmac_f32_e32 v234, v61, v61
	v_fmac_f32_e32 v234, v62, v62
	v_fmac_f32_e32 v234, v63, v63
	v_perm_b32 v222, v225, v224, s58
	v_perm_b32 v223, v227, v226, s58
	global_store_dwordx2 v[204:205], v[222:223], off
	v_pk_add_f32 v[54:55], v[54:55], v[182:183]
	v_pk_add_f32 v[52:53], v[52:53], v[180:181]
	global_store_dwordx4 v[220:221], v[52:55], off offset:512
	v_pk_mul_f32 v[228:229], v[84:85], v[52:53]
	v_pk_mul_f32 v[230:231], v[86:87], v[54:55]
	v_fmac_f32_e32 v234, v52, v52
	v_add_u32_e32 v228, 0x8000, v228
	v_add_u32_e32 v229, 0x8000, v229
	v_add_u32_e32 v230, 0x8000, v230
	v_add_u32_e32 v231, 0x8000, v231
	v_fmac_f32_e32 v234, v53, v53
	v_fmac_f32_e32 v234, v54, v54
	v_fmac_f32_e32 v234, v55, v55
	v_perm_b32 v232, v229, v228, s58
	v_perm_b32 v233, v231, v230, s58
	global_store_dwordx2 v[204:205], v[232:233], off offset:256
	s_nop 1
	v_mov_b32_dpp v241, v173 row_ror:8 row_mask:0xf bank_mask:0xf
	v_mov_b32_dpp v242, v234 row_ror:8 row_mask:0xf bank_mask:0xf
	v_add_f32_e32 v173, v173, v241
	v_add_f32_e32 v234, v234, v242
	v_cndmask_b32_e64 v173, v234, v173, s[34:35]
	s_nop 0
	ds_bpermute_b32 v241, v235, v173
	global_load_dwordx4 v[156:159], v[174:175], off nt
	global_load_dwordx4 v[160:163], v[174:175], off offset:512 nt
	global_load_dwordx4 v[176:179], v[200:201], off nt
	global_load_dwordx4 v[180:183], v[200:201], off offset:512 nt
	s_mov_b64 vcc, 0x20000
	v_lshl_add_u64 v[174:175], v[174:175], 0, vcc
	v_lshl_add_u64 v[200:201], v[200:201], 0, vcc
	s_mov_b64 vcc, 0x20000
	v_lshl_add_u64 v[218:219], v[218:219], 0, vcc
	v_lshl_add_u64 v[220:221], v[220:221], 0, vcc
	s_mov_b64 vcc, 0x10000
	v_lshl_add_u64 v[202:203], v[202:203], 0, vcc
	v_lshl_add_u64 v[204:205], v[204:205], 0, vcc
	s_waitcnt lgkmcnt(0)
	v_add_f32_e32 v173, v173, v241
	s_nop 0
	ds_bpermute_b32 v242, v240, v173
	s_waitcnt lgkmcnt(0)
	v_add_f32_e32 v173, v173, v242
	s_mov_b64 exec, s[0:1]
	global_atomic_add_f32 v[206:207], v173, off
	s_mov_b64 exec, -1
	s_mov_b64 vcc, 64
	v_lshl_add_u64 v[206:207], v[206:207], 0, vcc
	v_mov_b32_dpp v236, v40 row_ror:8 row_mask:0xf bank_mask:0xf
	v_mov_b32_dpp v237, v41 row_ror:8 row_mask:0xf bank_mask:0xf
	v_mov_b32_dpp v238, v42 row_ror:8 row_mask:0xf bank_mask:0xf
	v_mov_b32_dpp v239, v43 row_ror:8 row_mask:0xf bank_mask:0xf
	v_cndmask_b32_e64 v40, v236, v44, s[34:35]
	v_cndmask_b32_e64 v41, v237, v45, s[34:35]
	v_cndmask_b32_e64 v42, v238, v46, s[34:35]
	v_cndmask_b32_e64 v43, v239, v47, s[34:35]
	v_cndmask_b32_e64 v44, v44, v236, s[34:35]
	v_cndmask_b32_e64 v45, v45, v237, s[34:35]
	v_cndmask_b32_e64 v46, v46, v238, s[34:35]
	v_cndmask_b32_e64 v47, v47, v239, s[34:35]
	v_mov_b32_dpp v236, v32 row_ror:8 row_mask:0xf bank_mask:0xf
	v_mov_b32_dpp v237, v33 row_ror:8 row_mask:0xf bank_mask:0xf
	v_mov_b32_dpp v238, v34 row_ror:8 row_mask:0xf bank_mask:0xf
	v_mov_b32_dpp v239, v35 row_ror:8 row_mask:0xf bank_mask:0xf
	v_cndmask_b32_e64 v32, v236, v36, s[34:35]
	v_cndmask_b32_e64 v33, v237, v37, s[34:35]
	v_cndmask_b32_e64 v34, v238, v38, s[34:35]
	v_cndmask_b32_e64 v35, v239, v39, s[34:35]
	v_cndmask_b32_e64 v36, v36, v236, s[34:35]
	v_cndmask_b32_e64 v37, v37, v237, s[34:35]
	v_cndmask_b32_e64 v38, v38, v238, s[34:35]
	v_cndmask_b32_e64 v39, v39, v239, s[34:35]
	s_waitcnt vmcnt(14)
;     __device__ __forceinline__ void operator()(const f32x4 (&acc)[2][2][4][2], const Unit& u, int wr, int wc, int fr, int fq) const {
;     ...
;         for (int ai = 0; ai < 2; ++ai)
; #pragma unroll
;             for (int m = 0; m < 4; ++m) {
;                 const int row = row0 + ai * HALF + m * 16;
;                 const size_t off = (size_t)row * ldc + col0;
;                 float q = 0.f;
; #pragma unroll
;                 for (int bj = 0; bj < 2; ++bj)
; #pragma unroll
;                     for (int n = 0; n < 2; ++n) {
;                         const f32x4 rv = *(const f32x4*)(rbase + off + bj * HALF + n * 16);
;                         const f32x4 v = rv + acc[ai][bj][m][n] * scale;
;                         if (out) *(f32x4*)(out + off + bj * HALF + n * 16) = v;
;                         if (xn) { q += (v.x * v.x + v.y * v.y) + (v.z * v.z + v.w * v.w); const f32x4 o = v * wv[bj][n];
;                             u32x2 p; p.x = pk2(o.x, o.y); p.y = pk2(o.z, o.w); *(u32x2*)(xn + off + bj * HALF + n * 16) = p; }
;                     }
;                 if (xn) { q += __shfl_xor(q, 16); q += __shfl_xor(q, 32); if (fq == 0) (void)__hip_atomic_fetch_add(ss + row, q, __ATOMIC_RELAXED, __HIP_MEMORY_SCOPE_AGENT); }
;             }
	v_pk_add_f32 v[42:43], v[42:43], v[186:187]
	v_pk_add_f32 v[40:41], v[40:41], v[184:185]
	global_store_dwordx4 v[218:219], v[40:43], off
	v_pk_mul_f32 v[224:225], v[64:65], v[40:41]
	v_pk_mul_f32 v[226:227], v[66:67], v[42:43]
	v_mul_f32_e32 v173, v40, v40
	v_add_u32_e32 v224, 0x8000, v224
	v_add_u32_e32 v225, 0x8000, v225
	v_add_u32_e32 v226, 0x8000, v226
	v_add_u32_e32 v227, 0x8000, v227
	v_fmac_f32_e32 v173, v41, v41
	v_fmac_f32_e32 v173, v42, v42
	v_fmac_f32_e32 v173, v43, v43
	v_perm_b32 v222, v225, v224, s58
	v_perm_b32 v223, v227, v226, s58
	global_store_dwordx2 v[202:203], v[222:223], off
	v_pk_add_f32 v[34:35], v[34:35], v[190:191]
	v_pk_add_f32 v[32:33], v[32:33], v[188:189]
	global_store_dwordx4 v[218:219], v[32:35], off offset:512
	v_pk_mul_f32 v[228:229], v[72:73], v[32:33]
	v_pk_mul_f32 v[230:231], v[74:75], v[34:35]
	v_fmac_f32_e32 v173, v32, v32
	v_add_u32_e32 v228, 0x8000, v228
	v_add_u32_e32 v229, 0x8000, v229
	v_add_u32_e32 v230, 0x8000, v230
	v_add_u32_e32 v231, 0x8000, v231
	v_fmac_f32_e32 v173, v33, v33
	v_fmac_f32_e32 v173, v34, v34
	v_fmac_f32_e32 v173, v35, v35
	v_perm_b32 v232, v229, v228, s58
	v_perm_b32 v233, v231, v230, s58
	global_store_dwordx2 v[202:203], v[232:233], off offset:256
	v_pk_add_f32 v[46:47], v[46:47], v[194:195]
	v_pk_add_f32 v[44:45], v[44:45], v[192:193]
	global_store_dwordx4 v[220:221], v[44:47], off
	v_pk_mul_f32 v[224:225], v[76:77], v[44:45]
	v_pk_mul_f32 v[226:227], v[78:79], v[46:47]
	v_mul_f32_e32 v234, v44, v44
	v_add_u32_e32 v224, 0x8000, v224
	v_add_u32_e32 v225, 0x8000, v225
	v_add_u32_e32 v226, 0x8000, v226
	v_add_u32_e32 v227, 0x8000, v227
	v_fmac_f32_e32 v234, v45, v45
	v_fmac_f32_e32 v234, v46, v46
	v_fmac_f32_e32 v234, v47, v47
	v_perm_b32 v222, v225, v224, s58
	v_perm_b32 v223, v227, v226, s58
	global_store_dwordx2 v[204:205], v[222:223], off
	v_pk_add_f32 v[38:39], v[38:39], v[198:199]
	v_pk_add_f32 v[36:37], v[36:37], v[196:197]
	global_store_dwordx4 v[220:221], v[36:39], off offset:512
	v_pk_mul_f32 v[228:229], v[84:85], v[36:37]
	v_pk_mul_f32 v[230:231], v[86:87], v[38:39]
	v_fmac_f32_e32 v234, v36, v36
	v_add_u32_e32 v228, 0x8000, v228
	v_add_u32_e32 v229, 0x8000, v229
	v_add_u32_e32 v230, 0x8000, v230
	v_add_u32_e32 v231, 0x8000, v231
	v_fmac_f32_e32 v234, v37, v37
	v_fmac_f32_e32 v234, v38, v38
	v_fmac_f32_e32 v234, v39, v39
	v_perm_b32 v232, v229, v228, s58
	v_perm_b32 v233, v231, v230, s58
	global_store_dwordx2 v[204:205], v[232:233], off offset:256
	s_nop 1
	v_mov_b32_dpp v241, v173 row_ror:8 row_mask:0xf bank_mask:0xf
	v_mov_b32_dpp v242, v234 row_ror:8 row_mask:0xf bank_mask:0xf
	v_add_f32_e32 v173, v173, v241
	v_add_f32_e32 v234, v234, v242
	v_cndmask_b32_e64 v173, v234, v173, s[34:35]
	s_nop 0
	ds_bpermute_b32 v241, v235, v173
	global_load_dwordx4 v[184:187], v[174:175], off nt
	global_load_dwordx4 v[188:191], v[174:175], off offset:512 nt
	global_load_dwordx4 v[192:195], v[200:201], off nt
	global_load_dwordx4 v[196:199], v[200:201], off offset:512 nt
	s_mov_b64 vcc, 0x20000
	v_lshl_add_u64 v[218:219], v[218:219], 0, vcc
	v_lshl_add_u64 v[220:221], v[220:221], 0, vcc
	s_mov_b64 vcc, 0x10000
	v_lshl_add_u64 v[202:203], v[202:203], 0, vcc
	v_lshl_add_u64 v[204:205], v[204:205], 0, vcc
	s_waitcnt lgkmcnt(0)
	v_add_f32_e32 v173, v173, v241
	s_nop 0
	ds_bpermute_b32 v242, v240, v173
	s_waitcnt lgkmcnt(0)
	v_add_f32_e32 v173, v173, v242
	s_mov_b64 exec, s[0:1]
	global_atomic_add_f32 v[206:207], v173, off
	s_mov_b64 exec, -1
	s_mov_b64 vcc, 64
	v_lshl_add_u64 v[206:207], v[206:207], 0, vcc
	v_mov_b32_dpp v236, v24 row_ror:8 row_mask:0xf bank_mask:0xf
	v_mov_b32_dpp v237, v25 row_ror:8 row_mask:0xf bank_mask:0xf
	v_mov_b32_dpp v238, v26 row_ror:8 row_mask:0xf bank_mask:0xf
	v_mov_b32_dpp v239, v27 row_ror:8 row_mask:0xf bank_mask:0xf
	v_cndmask_b32_e64 v24, v236, v28, s[34:35]
	v_cndmask_b32_e64 v25, v237, v29, s[34:35]
	v_cndmask_b32_e64 v26, v238, v30, s[34:35]
	v_cndmask_b32_e64 v27, v239, v31, s[34:35]
	v_cndmask_b32_e64 v28, v28, v236, s[34:35]
	v_cndmask_b32_e64 v29, v29, v237, s[34:35]
	v_cndmask_b32_e64 v30, v30, v238, s[34:35]
	v_cndmask_b32_e64 v31, v31, v239, s[34:35]
	v_mov_b32_dpp v236, v16 row_ror:8 row_mask:0xf bank_mask:0xf
	v_mov_b32_dpp v237, v17 row_ror:8 row_mask:0xf bank_mask:0xf
	v_mov_b32_dpp v238, v18 row_ror:8 row_mask:0xf bank_mask:0xf
	v_mov_b32_dpp v239, v19 row_ror:8 row_mask:0xf bank_mask:0xf
	v_cndmask_b32_e64 v16, v236, v20, s[34:35]
	v_cndmask_b32_e64 v17, v237, v21, s[34:35]
	v_cndmask_b32_e64 v18, v238, v22, s[34:35]
	v_cndmask_b32_e64 v19, v239, v23, s[34:35]
	v_cndmask_b32_e64 v20, v20, v236, s[34:35]
	v_cndmask_b32_e64 v21, v21, v237, s[34:35]
	v_cndmask_b32_e64 v22, v22, v238, s[34:35]
	v_cndmask_b32_e64 v23, v23, v239, s[34:35]
	s_waitcnt vmcnt(14)
;     __device__ __forceinline__ void operator()(const f32x4 (&acc)[2][2][4][2], const Unit& u, int wr, int wc, int fr, int fq) const {
;     ...
;         for (int ai = 0; ai < 2; ++ai)
; #pragma unroll
;             for (int m = 0; m < 4; ++m) {
;                 const int row = row0 + ai * HALF + m * 16;
;                 const size_t off = (size_t)row * ldc + col0;
;                 float q = 0.f;
; #pragma unroll
;                 for (int bj = 0; bj < 2; ++bj)
; #pragma unroll
;                     for (int n = 0; n < 2; ++n) {
;                         const f32x4 rv = *(const f32x4*)(rbase + off + bj * HALF + n * 16);
;                         const f32x4 v = rv + acc[ai][bj][m][n] * scale;
;                         if (out) *(f32x4*)(out + off + bj * HALF + n * 16) = v;
;                         if (xn) { q += (v.x * v.x + v.y * v.y) + (v.z * v.z + v.w * v.w); const f32x4 o = v * wv[bj][n];
;                             u32x2 p; p.x = pk2(o.x, o.y); p.y = pk2(o.z, o.w); *(u32x2*)(xn + off + bj * HALF + n * 16) = p; }
;                     }
;                 if (xn) { q += __shfl_xor(q, 16); q += __shfl_xor(q, 32); if (fq == 0) (void)__hip_atomic_fetch_add(ss + row, q, __ATOMIC_RELAXED, __HIP_MEMORY_SCOPE_AGENT); }
;             }
	v_pk_add_f32 v[26:27], v[26:27], v[158:159]
	v_pk_add_f32 v[24:25], v[24:25], v[156:157]
	global_store_dwordx4 v[218:219], v[24:27], off
	v_pk_mul_f32 v[224:225], v[64:65], v[24:25]
	v_pk_mul_f32 v[226:227], v[66:67], v[26:27]
	v_mul_f32_e32 v173, v24, v24
	v_add_u32_e32 v224, 0x8000, v224
	v_add_u32_e32 v225, 0x8000, v225
	v_add_u32_e32 v226, 0x8000, v226
	v_add_u32_e32 v227, 0x8000, v227
	v_fmac_f32_e32 v173, v25, v25
	v_fmac_f32_e32 v173, v26, v26
	v_fmac_f32_e32 v173, v27, v27
	v_perm_b32 v222, v225, v224, s58
	v_perm_b32 v223, v227, v226, s58
	global_store_dwordx2 v[202:203], v[222:223], off
	v_pk_add_f32 v[18:19], v[18:19], v[162:163]
	v_pk_add_f32 v[16:17], v[16:17], v[160:161]
	global_store_dwordx4 v[218:219], v[16:19], off offset:512
	v_pk_mul_f32 v[228:229], v[72:73], v[16:17]
	v_pk_mul_f32 v[230:231], v[74:75], v[18:19]
	v_fmac_f32_e32 v173, v16, v16
	v_add_u32_e32 v228, 0x8000, v228
	v_add_u32_e32 v229, 0x8000, v229
	v_add_u32_e32 v230, 0x8000, v230
	v_add_u32_e32 v231, 0x8000, v231
	v_fmac_f32_e32 v173, v17, v17
	v_fmac_f32_e32 v173, v18, v18
	v_fmac_f32_e32 v173, v19, v19
	v_perm_b32 v232, v229, v228, s58
	v_perm_b32 v233, v231, v230, s58
	global_store_dwordx2 v[202:203], v[232:233], off offset:256
	v_pk_add_f32 v[30:31], v[30:31], v[178:179]
	v_pk_add_f32 v[28:29], v[28:29], v[176:177]
	global_store_dwordx4 v[220:221], v[28:31], off
	v_pk_mul_f32 v[224:225], v[76:77], v[28:29]
	v_pk_mul_f32 v[226:227], v[78:79], v[30:31]
	v_mul_f32_e32 v234, v28, v28
	v_add_u32_e32 v224, 0x8000, v224
	v_add_u32_e32 v225, 0x8000, v225
	v_add_u32_e32 v226, 0x8000, v226
	v_add_u32_e32 v227, 0x8000, v227
	v_fmac_f32_e32 v234, v29, v29
	v_fmac_f32_e32 v234, v30, v30
	v_fmac_f32_e32 v234, v31, v31
	v_perm_b32 v222, v225, v224, s58
	v_perm_b32 v223, v227, v226, s58
	global_store_dwordx2 v[204:205], v[222:223], off
	v_pk_add_f32 v[22:23], v[22:23], v[182:183]
	v_pk_add_f32 v[20:21], v[20:21], v[180:181]
	global_store_dwordx4 v[220:221], v[20:23], off offset:512
	v_pk_mul_f32 v[228:229], v[84:85], v[20:21]
	v_pk_mul_f32 v[230:231], v[86:87], v[22:23]
	v_fmac_f32_e32 v234, v20, v20
	v_add_u32_e32 v228, 0x8000, v228
	v_add_u32_e32 v229, 0x8000, v229
	v_add_u32_e32 v230, 0x8000, v230
	v_add_u32_e32 v231, 0x8000, v231
	v_fmac_f32_e32 v234, v21, v21
	v_fmac_f32_e32 v234, v22, v22
	v_fmac_f32_e32 v234, v23, v23
	v_perm_b32 v232, v229, v228, s58
	v_perm_b32 v233, v231, v230, s58
	global_store_dwordx2 v[204:205], v[232:233], off offset:256
	s_nop 1
	v_mov_b32_dpp v241, v173 row_ror:8 row_mask:0xf bank_mask:0xf
	v_mov_b32_dpp v242, v234 row_ror:8 row_mask:0xf bank_mask:0xf
	v_add_f32_e32 v173, v173, v241
	v_add_f32_e32 v234, v234, v242
	v_cndmask_b32_e64 v173, v234, v173, s[34:35]
	s_nop 0
	ds_bpermute_b32 v241, v235, v173
	s_mov_b64 vcc, 0x20000
	v_lshl_add_u64 v[218:219], v[218:219], 0, vcc
	v_lshl_add_u64 v[220:221], v[220:221], 0, vcc
	s_mov_b64 vcc, 0x10000
	v_lshl_add_u64 v[202:203], v[202:203], 0, vcc
	v_lshl_add_u64 v[204:205], v[204:205], 0, vcc
	s_waitcnt lgkmcnt(0)
	v_add_f32_e32 v173, v173, v241
	s_nop 0
	ds_bpermute_b32 v242, v240, v173
	s_waitcnt lgkmcnt(0)
	v_add_f32_e32 v173, v173, v242
	s_mov_b64 exec, s[0:1]
	global_atomic_add_f32 v[206:207], v173, off
	s_mov_b64 exec, -1
	s_mov_b64 vcc, 64
	v_lshl_add_u64 v[206:207], v[206:207], 0, vcc
	v_mov_b32_dpp v236, v8 row_ror:8 row_mask:0xf bank_mask:0xf
	v_mov_b32_dpp v237, v9 row_ror:8 row_mask:0xf bank_mask:0xf
	v_mov_b32_dpp v238, v10 row_ror:8 row_mask:0xf bank_mask:0xf
	v_mov_b32_dpp v239, v11 row_ror:8 row_mask:0xf bank_mask:0xf
	v_cndmask_b32_e64 v8, v236, v12, s[34:35]
	v_cndmask_b32_e64 v9, v237, v13, s[34:35]
	v_cndmask_b32_e64 v10, v238, v14, s[34:35]
	v_cndmask_b32_e64 v11, v239, v15, s[34:35]
	v_cndmask_b32_e64 v12, v12, v236, s[34:35]
	v_cndmask_b32_e64 v13, v13, v237, s[34:35]
	v_cndmask_b32_e64 v14, v14, v238, s[34:35]
	v_cndmask_b32_e64 v15, v15, v239, s[34:35]
	v_mov_b32_dpp v236, v0 row_ror:8 row_mask:0xf bank_mask:0xf
	v_mov_b32_dpp v237, v1 row_ror:8 row_mask:0xf bank_mask:0xf
	v_mov_b32_dpp v238, v2 row_ror:8 row_mask:0xf bank_mask:0xf
	v_mov_b32_dpp v239, v3 row_ror:8 row_mask:0xf bank_mask:0xf
	v_cndmask_b32_e64 v0, v236, v4, s[34:35]
	v_cndmask_b32_e64 v1, v237, v5, s[34:35]
	v_cndmask_b32_e64 v2, v238, v6, s[34:35]
	v_cndmask_b32_e64 v3, v239, v7, s[34:35]
	v_cndmask_b32_e64 v4, v4, v236, s[34:35]
	v_cndmask_b32_e64 v5, v5, v237, s[34:35]
	v_cndmask_b32_e64 v6, v6, v238, s[34:35]
	v_cndmask_b32_e64 v7, v7, v239, s[34:35]
	s_waitcnt vmcnt(10)
; #define PG8_BAR __builtin_amdgcn_s_barrier()
;     __device__ __forceinline__ void operator()(const f32x4 (&acc)[2][2][4][2], const Unit& u, int wr, int wc, int fr, int fq) const {
;     ...
;         for (int ai = 0; ai < 2; ++ai)
; #pragma unroll
;             for (int m = 0; m < 4; ++m) {
;                 const int row = row0 + ai * HALF + m * 16;
;                 const size_t off = (size_t)row * ldc + col0;
;                 float q = 0.f;
; #pragma unroll
;                 for (int bj = 0; bj < 2; ++bj)
; #pragma unroll
;                     for (int n = 0; n < 2; ++n) {
;                         const f32x4 rv = *(const f32x4*)(rbase + off + bj * HALF + n * 16);
;                         const f32x4 v = rv + acc[ai][bj][m][n] * scale;
;                         if (out) *(f32x4*)(out + off + bj * HALF + n * 16) = v;
;                         if (xn) { q += (v.x * v.x + v.y * v.y) + (v.z * v.z + v.w * v.w); const f32x4 o = v * wv[bj][n];
;                             u32x2 p; p.x = pk2(o.x, o.y); p.y = pk2(o.z, o.w); *(u32x2*)(xn + off + bj * HALF + n * 16) = p; }
;                     }
;                 if (xn) { q += __shfl_xor(q, 16); q += __shfl_xor(q, 32); if (fq == 0) (void)__hip_atomic_fetch_add(ss + row, q, __ATOMIC_RELAXED, __HIP_MEMORY_SCOPE_AGENT); }
;             }
; template <class Epi, bool ALIGN_EPI>
; __device__ __forceinline__ void gemm_phase(LAS unsigned char* lds, const Gemm g, const StaticOrder& S, const Epi& E) {
;     ...
;         if (!has_next) break;
; #pragma unroll
;         for (int a = 0; a < 2; ++a)
; #pragma unroll
;             for (int b = 0; b < 2; ++b)
; #pragma unroll
;                 for (int m = 0; m < 4; ++m)
; #pragma unroll
;                     for (int n = 0; n < 2; ++n) acc[a][b][m][n] = (f32x4){0.f, 0.f, 0.f, 0.f};
;         cur = nxt; cA = nA; cB = nB; ++ui;
;         if constexpr (ALIGN_EPI) { if (wr == 1) PG8_BAR; }
	v_pk_add_f32 v[10:11], v[10:11], v[186:187]
	v_pk_add_f32 v[8:9], v[8:9], v[184:185]
	global_store_dwordx4 v[218:219], v[8:11], off
	v_pk_mul_f32 v[224:225], v[64:65], v[8:9]
	v_pk_mul_f32 v[226:227], v[66:67], v[10:11]
	v_mul_f32_e32 v173, v8, v8
	v_add_u32_e32 v224, 0x8000, v224
	v_add_u32_e32 v225, 0x8000, v225
	v_add_u32_e32 v226, 0x8000, v226
	v_add_u32_e32 v227, 0x8000, v227
	v_fmac_f32_e32 v173, v9, v9
	v_fmac_f32_e32 v173, v10, v10
	v_fmac_f32_e32 v173, v11, v11
	v_perm_b32 v222, v225, v224, s58
	v_perm_b32 v223, v227, v226, s58
	global_store_dwordx2 v[202:203], v[222:223], off
	v_pk_add_f32 v[2:3], v[2:3], v[190:191]
	v_pk_add_f32 v[0:1], v[0:1], v[188:189]
	global_store_dwordx4 v[218:219], v[0:3], off offset:512
	v_pk_mul_f32 v[228:229], v[72:73], v[0:1]
	v_pk_mul_f32 v[230:231], v[74:75], v[2:3]
	v_fmac_f32_e32 v173, v0, v0
	v_add_u32_e32 v228, 0x8000, v228
	v_add_u32_e32 v229, 0x8000, v229
	v_add_u32_e32 v230, 0x8000, v230
	v_add_u32_e32 v231, 0x8000, v231
	v_fmac_f32_e32 v173, v1, v1
	v_fmac_f32_e32 v173, v2, v2
	v_fmac_f32_e32 v173, v3, v3
	v_perm_b32 v232, v229, v228, s58
	v_perm_b32 v233, v231, v230, s58
	global_store_dwordx2 v[202:203], v[232:233], off offset:256
	v_pk_add_f32 v[14:15], v[14:15], v[194:195]
	v_pk_add_f32 v[12:13], v[12:13], v[192:193]
	global_store_dwordx4 v[220:221], v[12:15], off
	v_pk_mul_f32 v[224:225], v[76:77], v[12:13]
	v_pk_mul_f32 v[226:227], v[78:79], v[14:15]
	v_mul_f32_e32 v234, v12, v12
	v_add_u32_e32 v224, 0x8000, v224
	v_add_u32_e32 v225, 0x8000, v225
	v_add_u32_e32 v226, 0x8000, v226
	v_add_u32_e32 v227, 0x8000, v227
	v_fmac_f32_e32 v234, v13, v13
	v_fmac_f32_e32 v234, v14, v14
	v_fmac_f32_e32 v234, v15, v15
	v_perm_b32 v222, v225, v224, s58
	v_perm_b32 v223, v227, v226, s58
	global_store_dwordx2 v[204:205], v[222:223], off
	v_pk_add_f32 v[6:7], v[6:7], v[198:199]
	v_pk_add_f32 v[4:5], v[4:5], v[196:197]
	global_store_dwordx4 v[220:221], v[4:7], off offset:512
	v_pk_mul_f32 v[228:229], v[84:85], v[4:5]
	v_pk_mul_f32 v[230:231], v[86:87], v[6:7]
	v_fmac_f32_e32 v234, v4, v4
	v_add_u32_e32 v228, 0x8000, v228
	v_add_u32_e32 v229, 0x8000, v229
	v_add_u32_e32 v230, 0x8000, v230
	v_add_u32_e32 v231, 0x8000, v231
	v_fmac_f32_e32 v234, v5, v5
	v_fmac_f32_e32 v234, v6, v6
	v_fmac_f32_e32 v234, v7, v7
	v_perm_b32 v232, v229, v228, s58
	v_perm_b32 v233, v231, v230, s58
	global_store_dwordx2 v[204:205], v[232:233], off offset:256
	s_nop 1
	v_mov_b32_dpp v241, v173 row_ror:8 row_mask:0xf bank_mask:0xf
	v_mov_b32_dpp v242, v234 row_ror:8 row_mask:0xf bank_mask:0xf
	v_add_f32_e32 v173, v173, v241
	v_add_f32_e32 v234, v234, v242
	v_cndmask_b32_e64 v173, v234, v173, s[34:35]
	s_nop 0
	ds_bpermute_b32 v241, v235, v173
	s_waitcnt lgkmcnt(0)
	v_add_f32_e32 v173, v173, v241
	s_nop 0
	ds_bpermute_b32 v242, v240, v173
	s_waitcnt lgkmcnt(0)
	v_add_f32_e32 v173, v173, v242
	s_mov_b64 exec, s[0:1]
	global_atomic_add_f32 v[206:207], v173, off
	s_mov_b64 exec, -1
	s_andn2_b64 vcc, exec, s[6:7]
	s_mov_b64 s[4:5], -1
	s_cbranch_vccnz .LBB0_1078
	s_andn2_b64 vcc, exec, s[12:13]
	s_cbranch_vccnz .LBB0_1077
	s_barrier
	s_branch .LBB0_1077

;     __device__ __forceinline__ void operator()(const f32x4 (&acc)[2][2][4][2], const Unit& u, int wr, int wc, int fr, int fq) const {
;         const int row0 = u.pm * BM + wr * 64 + fr, col0 = u.pn * BM + wc * 32 + 4 * fq;
;         const float* rbase = (u.pm * BM < SEQ_P) ? resA : (resB - (size_t)SEQ_P * ldc);
;         f32x4 wv[2][2];
;         if (xn) {
; #pragma unroll
;             for (int bj = 0; bj < 2; ++bj)
; #pragma unroll
;                 for (int n = 0; n < 2; ++n) wv[bj][n] = *(const f32x4*)(wn + col0 + bj * HALF + n * 16);
;         }
; #pragma unroll
;         for (int ai = 0; ai < 2; ++ai)
; #pragma unroll
;             for (int m = 0; m < 4; ++m) {
;                 const int row = row0 + ai * HALF + m * 16;
;                 const size_t off = (size_t)row * ldc + col0;
;                 float q = 0.f;
; #pragma unroll
;                 for (int bj = 0; bj < 2; ++bj)
; #pragma unroll
;                     for (int n = 0; n < 2; ++n) {
;                         const f32x4 rv = *(const f32x4*)(rbase + off + bj * HALF + n * 16);
;                         const f32x4 v = rv + acc[ai][bj][m][n] * scale;
;                         if (out) *(f32x4*)(out + off + bj * HALF + n * 16) = v;
;                         if (xn) { q += (v.x * v.x + v.y * v.y) + (v.z * v.z + v.w * v.w); const f32x4 o = v * wv[bj][n];
;                             u32x2 p; p.x = pk2(o.x, o.y); p.y = pk2(o.z, o.w); *(u32x2*)(xn + off + bj * HALF + n * 16) = p; }
;                     }
;                 if (xn) { q += __shfl_xor(q, 16); q += __shfl_xor(q, 32); if (fq == 0) (void)__hip_atomic_fetch_add(ss + row, q, __ATOMIC_RELAXED, __HIP_MEMORY_SCOPE_AGENT); }
;             }
.LBB0_1382:
	v_lshl_add_u32 v210, s54, 8, v160
	v_lshl_or_b32 v212, s53, 8, v162
	v_and_b32_e32 v238, 8, v167
	v_mov_b32_e32 v211, 0
	v_cmp_eq_u32_e64 s[24:25], 0, v238
	v_lshlrev_b32_e32 v232, 1, v238
	v_add_u32_e32 v214, v212, v232
	v_sub_u32_e32 v233, 16, v232
	v_add_u32_e32 v233, v212, v233
	v_mov_b32_e32 v212, v214
	v_mov_b32_e32 v214, v233
	v_mov_b32_e32 v213, 0
	v_mov_b32_e32 v215, 0
	v_sub_u32_e32 v208, v210, v238
	v_mov_b32_e32 v209, 0
	v_lshlrev_b64 v[206:207], 11, v[208:209]
	v_add_u32_e32 v208, 8, v208
	v_lshlrev_b64 v[208:209], 11, v[208:209]
	v_lshl_add_u64 v[206:207], v[206:207], 0, v[212:213]
	v_lshl_add_u64 v[208:209], v[208:209], 0, v[214:215]
	v_lshl_add_u64 v[196:197], v[206:207], 2, s[8:9]
	v_lshl_add_u64 v[198:199], v[208:209], 2, s[8:9]
	v_lshl_add_u64 v[200:201], v[212:213], 2, s[10:11]
	v_lshl_add_u64 v[202:203], v[214:215], 2, s[10:11]
	global_load_dwordx4 v[72:75], v[200:201], off
	global_load_dwordx4 v[84:87], v[200:201], off offset:512
	global_load_dwordx4 v[88:91], v[202:203], off
	global_load_dwordx4 v[96:99], v[202:203], off offset:512
	global_load_dwordx4 v[156:159], v[196:197], off nt
	global_load_dwordx4 v[168:171], v[196:197], off offset:512 nt
	global_load_dwordx4 v[172:175], v[198:199], off nt
	global_load_dwordx4 v[176:179], v[198:199], off offset:512 nt
	s_mov_b64 vcc, 0x20000
	v_lshl_add_u64 v[196:197], v[196:197], 0, vcc
	v_lshl_add_u64 v[198:199], v[198:199], 0, vcc
	global_load_dwordx4 v[180:183], v[196:197], off nt
	global_load_dwordx4 v[184:187], v[196:197], off offset:512 nt
	global_load_dwordx4 v[188:191], v[198:199], off nt
	global_load_dwordx4 v[192:195], v[198:199], off offset:512 nt
	s_mov_b64 vcc, 0x20000
	v_lshl_add_u64 v[196:197], v[196:197], 0, vcc
	v_lshl_add_u64 v[198:199], v[198:199], 0, vcc
	v_lshl_add_u64 v[200:201], v[206:207], 1, s[14:15]
	v_lshl_add_u64 v[202:203], v[208:209], 1, s[14:15]
	v_lshl_add_u64 v[204:205], v[210:211], 2, s[16:17]
	v_xor_b32_e32 v234, 16, v167
	v_xor_b32_e32 v235, 32, v167
	v_lshlrev_b32_e32 v234, 2, v234
	v_lshlrev_b32_e32 v235, 2, v235
	v_mov_b32_dpp v228, v136 row_ror:8 row_mask:0xf bank_mask:0xf
	v_mov_b32_dpp v229, v137 row_ror:8 row_mask:0xf bank_mask:0xf
	v_mov_b32_dpp v230, v138 row_ror:8 row_mask:0xf bank_mask:0xf
	v_mov_b32_dpp v231, v139 row_ror:8 row_mask:0xf bank_mask:0xf
	v_cndmask_b32_e64 v136, v228, v140, s[24:25]
	v_cndmask_b32_e64 v137, v229, v141, s[24:25]
	v_cndmask_b32_e64 v138, v230, v142, s[24:25]
	v_cndmask_b32_e64 v139, v231, v143, s[24:25]
	v_cndmask_b32_e64 v140, v140, v228, s[24:25]
	v_cndmask_b32_e64 v141, v141, v229, s[24:25]
	v_cndmask_b32_e64 v142, v142, v230, s[24:25]
	v_cndmask_b32_e64 v143, v143, v231, s[24:25]
	v_mov_b32_dpp v228, v128 row_ror:8 row_mask:0xf bank_mask:0xf
	v_mov_b32_dpp v229, v129 row_ror:8 row_mask:0xf bank_mask:0xf
	v_mov_b32_dpp v230, v130 row_ror:8 row_mask:0xf bank_mask:0xf
	v_mov_b32_dpp v231, v131 row_ror:8 row_mask:0xf bank_mask:0xf
	v_cndmask_b32_e64 v128, v228, v132, s[24:25]
	v_cndmask_b32_e64 v129, v229, v133, s[24:25]
	v_cndmask_b32_e64 v130, v230, v134, s[24:25]
	v_cndmask_b32_e64 v131, v231, v135, s[24:25]
	v_cndmask_b32_e64 v132, v132, v228, s[24:25]
	v_cndmask_b32_e64 v133, v133, v229, s[24:25]
	v_cndmask_b32_e64 v134, v134, v230, s[24:25]
	v_cndmask_b32_e64 v135, v135, v231, s[24:25]
	s_waitcnt vmcnt(4)
	v_pk_fma_f32 v[138:139], v[138:139], 0.5, v[158:159] op_sel_hi:[1,0,1]
	v_pk_fma_f32 v[136:137], v[136:137], 0.5, v[156:157] op_sel_hi:[1,0,1]
	v_pk_mul_f32 v[216:217], v[72:73], v[136:137]
	v_pk_mul_f32 v[218:219], v[74:75], v[138:139]
	v_mul_f32_e32 v232, v136, v136
	v_add_u32_e32 v216, 0x8000, v216
	v_add_u32_e32 v217, 0x8000, v217
	v_add_u32_e32 v218, 0x8000, v218
	v_add_u32_e32 v219, 0x8000, v219
	v_fmac_f32_e32 v232, v137, v137
	v_fmac_f32_e32 v232, v138, v138
	v_fmac_f32_e32 v232, v139, v139
	v_perm_b32 v224, v217, v216, s50
	v_perm_b32 v225, v219, v218, s50
	global_store_dwordx2 v[200:201], v[224:225], off
	v_pk_fma_f32 v[130:131], v[130:131], 0.5, v[170:171] op_sel_hi:[1,0,1]
	v_pk_fma_f32 v[128:129], v[128:129], 0.5, v[168:169] op_sel_hi:[1,0,1]
	v_pk_mul_f32 v[220:221], v[84:85], v[128:129]
	v_pk_mul_f32 v[222:223], v[86:87], v[130:131]
	v_fmac_f32_e32 v232, v128, v128
	v_add_u32_e32 v220, 0x8000, v220
	v_add_u32_e32 v221, 0x8000, v221
	v_add_u32_e32 v222, 0x8000, v222
	v_add_u32_e32 v223, 0x8000, v223
	v_fmac_f32_e32 v232, v129, v129
	v_fmac_f32_e32 v232, v130, v130
	v_fmac_f32_e32 v232, v131, v131
	v_perm_b32 v226, v221, v220, s50
	v_perm_b32 v227, v223, v222, s50
	global_store_dwordx2 v[200:201], v[226:227], off offset:256
	v_pk_fma_f32 v[142:143], v[142:143], 0.5, v[174:175] op_sel_hi:[1,0,1]
	v_pk_fma_f32 v[140:141], v[140:141], 0.5, v[172:173] op_sel_hi:[1,0,1]
	v_pk_mul_f32 v[216:217], v[88:89], v[140:141]
	v_pk_mul_f32 v[218:219], v[90:91], v[142:143]
	v_mul_f32_e32 v233, v140, v140
	v_add_u32_e32 v216, 0x8000, v216
	v_add_u32_e32 v217, 0x8000, v217
	v_add_u32_e32 v218, 0x8000, v218
	v_add_u32_e32 v219, 0x8000, v219
	v_fmac_f32_e32 v233, v141, v141
	v_fmac_f32_e32 v233, v142, v142
	v_fmac_f32_e32 v233, v143, v143
	v_perm_b32 v224, v217, v216, s50
	v_perm_b32 v225, v219, v218, s50
	global_store_dwordx2 v[202:203], v[224:225], off
	v_pk_fma_f32 v[134:135], v[134:135], 0.5, v[178:179] op_sel_hi:[1,0,1]
	v_pk_fma_f32 v[132:133], v[132:133], 0.5, v[176:177] op_sel_hi:[1,0,1]
	v_pk_mul_f32 v[220:221], v[96:97], v[132:133]
	v_pk_mul_f32 v[222:223], v[98:99], v[134:135]
	v_fmac_f32_e32 v233, v132, v132
	v_add_u32_e32 v220, 0x8000, v220
	v_add_u32_e32 v221, 0x8000, v221
	v_add_u32_e32 v222, 0x8000, v222
	v_add_u32_e32 v223, 0x8000, v223
	v_fmac_f32_e32 v233, v133, v133
	v_fmac_f32_e32 v233, v134, v134
	v_fmac_f32_e32 v233, v135, v135
	v_perm_b32 v226, v221, v220, s50
	v_perm_b32 v227, v223, v222, s50
	global_store_dwordx2 v[202:203], v[226:227], off offset:256
	s_nop 1
	v_mov_b32_dpp v236, v232 row_ror:8 row_mask:0xf bank_mask:0xf
	v_mov_b32_dpp v237, v233 row_ror:8 row_mask:0xf bank_mask:0xf
	v_add_f32_e32 v232, v232, v236
	v_add_f32_e32 v233, v233, v237
	v_cndmask_b32_e64 v232, v233, v232, s[24:25]
	s_nop 0
	ds_bpermute_b32 v236, v234, v232
	global_load_dwordx4 v[156:159], v[196:197], off nt
	global_load_dwordx4 v[168:171], v[196:197], off offset:512 nt
	global_load_dwordx4 v[172:175], v[198:199], off nt
	global_load_dwordx4 v[176:179], v[198:199], off offset:512 nt
	s_mov_b64 vcc, 0x20000
	v_lshl_add_u64 v[196:197], v[196:197], 0, vcc
	v_lshl_add_u64 v[198:199], v[198:199], 0, vcc
	s_mov_b64 vcc, 0x20000
	s_mov_b64 vcc, 0x10000
	v_lshl_add_u64 v[200:201], v[200:201], 0, vcc
	v_lshl_add_u64 v[202:203], v[202:203], 0, vcc
	s_waitcnt lgkmcnt(0)
;     __device__ __forceinline__ void operator()(const f32x4 (&acc)[2][2][4][2], const Unit& u, int wr, int wc, int fr, int fq) const {
;     ...
;         for (int ai = 0; ai < 2; ++ai)
; #pragma unroll
;             for (int m = 0; m < 4; ++m) {
;                 const int row = row0 + ai * HALF + m * 16;
;                 const size_t off = (size_t)row * ldc + col0;
;                 float q = 0.f;
; #pragma unroll
;                 for (int bj = 0; bj < 2; ++bj)
; #pragma unroll
;                     for (int n = 0; n < 2; ++n) {
;                         const f32x4 rv = *(const f32x4*)(rbase + off + bj * HALF + n * 16);
;                         const f32x4 v = rv + acc[ai][bj][m][n] * scale;
;                         if (out) *(f32x4*)(out + off + bj * HALF + n * 16) = v;
;                         if (xn) { q += (v.x * v.x + v.y * v.y) + (v.z * v.z + v.w * v.w); const f32x4 o = v * wv[bj][n];
;                             u32x2 p; p.x = pk2(o.x, o.y); p.y = pk2(o.z, o.w); *(u32x2*)(xn + off + bj * HALF + n * 16) = p; }
;                     }
;                 if (xn) { q += __shfl_xor(q, 16); q += __shfl_xor(q, 32); if (fq == 0) (void)__hip_atomic_fetch_add(ss + row, q, __ATOMIC_RELAXED, __HIP_MEMORY_SCOPE_AGENT); }
;             }
	v_add_f32_e32 v232, v232, v236
	s_nop 0
	ds_bpermute_b32 v237, v235, v232
	s_waitcnt lgkmcnt(0)
	v_add_f32_e32 v232, v232, v237
	s_mov_b64 exec, s[0:1]
	global_atomic_add_f32 v[204:205], v232, off
	s_mov_b64 exec, -1
	s_mov_b64 vcc, 64
	v_lshl_add_u64 v[204:205], v[204:205], 0, vcc
	v_mov_b32_dpp v228, v120 row_ror:8 row_mask:0xf bank_mask:0xf
	v_mov_b32_dpp v229, v121 row_ror:8 row_mask:0xf bank_mask:0xf
	v_mov_b32_dpp v230, v122 row_ror:8 row_mask:0xf bank_mask:0xf
	v_mov_b32_dpp v231, v123 row_ror:8 row_mask:0xf bank_mask:0xf
	v_cndmask_b32_e64 v120, v228, v124, s[24:25]
	v_cndmask_b32_e64 v121, v229, v125, s[24:25]
	v_cndmask_b32_e64 v122, v230, v126, s[24:25]
	v_cndmask_b32_e64 v123, v231, v127, s[24:25]
	v_cndmask_b32_e64 v124, v124, v228, s[24:25]
	v_cndmask_b32_e64 v125, v125, v229, s[24:25]
	v_cndmask_b32_e64 v126, v126, v230, s[24:25]
	v_cndmask_b32_e64 v127, v127, v231, s[24:25]
	v_mov_b32_dpp v228, v112 row_ror:8 row_mask:0xf bank_mask:0xf
	v_mov_b32_dpp v229, v113 row_ror:8 row_mask:0xf bank_mask:0xf
	v_mov_b32_dpp v230, v114 row_ror:8 row_mask:0xf bank_mask:0xf
	v_mov_b32_dpp v231, v115 row_ror:8 row_mask:0xf bank_mask:0xf
	v_cndmask_b32_e64 v112, v228, v116, s[24:25]
	v_cndmask_b32_e64 v113, v229, v117, s[24:25]
	v_cndmask_b32_e64 v114, v230, v118, s[24:25]
	v_cndmask_b32_e64 v115, v231, v119, s[24:25]
	v_cndmask_b32_e64 v116, v116, v228, s[24:25]
	v_cndmask_b32_e64 v117, v117, v229, s[24:25]
	v_cndmask_b32_e64 v118, v118, v230, s[24:25]
	v_cndmask_b32_e64 v119, v119, v231, s[24:25]
	s_waitcnt vmcnt(9)
	v_pk_fma_f32 v[122:123], v[122:123], 0.5, v[182:183] op_sel_hi:[1,0,1]
	v_pk_fma_f32 v[120:121], v[120:121], 0.5, v[180:181] op_sel_hi:[1,0,1]
	v_pk_mul_f32 v[216:217], v[72:73], v[120:121]
	v_pk_mul_f32 v[218:219], v[74:75], v[122:123]
	v_mul_f32_e32 v232, v120, v120
	v_add_u32_e32 v216, 0x8000, v216
	v_add_u32_e32 v217, 0x8000, v217
	v_add_u32_e32 v218, 0x8000, v218
	v_add_u32_e32 v219, 0x8000, v219
	v_fmac_f32_e32 v232, v121, v121
	v_fmac_f32_e32 v232, v122, v122
	v_fmac_f32_e32 v232, v123, v123
	v_perm_b32 v224, v217, v216, s50
	v_perm_b32 v225, v219, v218, s50
	global_store_dwordx2 v[200:201], v[224:225], off
	v_pk_fma_f32 v[114:115], v[114:115], 0.5, v[186:187] op_sel_hi:[1,0,1]
	v_pk_fma_f32 v[112:113], v[112:113], 0.5, v[184:185] op_sel_hi:[1,0,1]
	v_pk_mul_f32 v[220:221], v[84:85], v[112:113]
	v_pk_mul_f32 v[222:223], v[86:87], v[114:115]
	v_fmac_f32_e32 v232, v112, v112
	v_add_u32_e32 v220, 0x8000, v220
	v_add_u32_e32 v221, 0x8000, v221
	v_add_u32_e32 v222, 0x8000, v222
	v_add_u32_e32 v223, 0x8000, v223
	v_fmac_f32_e32 v232, v113, v113
	v_fmac_f32_e32 v232, v114, v114
	v_fmac_f32_e32 v232, v115, v115
	v_perm_b32 v226, v221, v220, s50
	v_perm_b32 v227, v223, v222, s50
	global_store_dwordx2 v[200:201], v[226:227], off offset:256
	v_pk_fma_f32 v[126:127], v[126:127], 0.5, v[190:191] op_sel_hi:[1,0,1]
	v_pk_fma_f32 v[124:125], v[124:125], 0.5, v[188:189] op_sel_hi:[1,0,1]
	v_pk_mul_f32 v[216:217], v[88:89], v[124:125]
	v_pk_mul_f32 v[218:219], v[90:91], v[126:127]
	v_mul_f32_e32 v233, v124, v124
	v_add_u32_e32 v216, 0x8000, v216
	v_add_u32_e32 v217, 0x8000, v217
	v_add_u32_e32 v218, 0x8000, v218
	v_add_u32_e32 v219, 0x8000, v219
	v_fmac_f32_e32 v233, v125, v125
	v_fmac_f32_e32 v233, v126, v126
	v_fmac_f32_e32 v233, v127, v127
	v_perm_b32 v224, v217, v216, s50
	v_perm_b32 v225, v219, v218, s50
	global_store_dwordx2 v[202:203], v[224:225], off
	v_pk_fma_f32 v[118:119], v[118:119], 0.5, v[194:195] op_sel_hi:[1,0,1]
	v_pk_fma_f32 v[116:117], v[116:117], 0.5, v[192:193] op_sel_hi:[1,0,1]
	v_pk_mul_f32 v[220:221], v[96:97], v[116:117]
	v_pk_mul_f32 v[222:223], v[98:99], v[118:119]
	v_fmac_f32_e32 v233, v116, v116
	v_add_u32_e32 v220, 0x8000, v220
	v_add_u32_e32 v221, 0x8000, v221
	v_add_u32_e32 v222, 0x8000, v222
	v_add_u32_e32 v223, 0x8000, v223
	v_fmac_f32_e32 v233, v117, v117
	v_fmac_f32_e32 v233, v118, v118
	v_fmac_f32_e32 v233, v119, v119
	v_perm_b32 v226, v221, v220, s50
	v_perm_b32 v227, v223, v222, s50
	global_store_dwordx2 v[202:203], v[226:227], off offset:256
	s_nop 1
	v_mov_b32_dpp v236, v232 row_ror:8 row_mask:0xf bank_mask:0xf
	v_mov_b32_dpp v237, v233 row_ror:8 row_mask:0xf bank_mask:0xf
	v_add_f32_e32 v232, v232, v236
	v_add_f32_e32 v233, v233, v237
	v_cndmask_b32_e64 v232, v233, v232, s[24:25]
	s_nop 0
	ds_bpermute_b32 v236, v234, v232
	global_load_dwordx4 v[180:183], v[196:197], off nt
	global_load_dwordx4 v[184:187], v[196:197], off offset:512 nt
	global_load_dwordx4 v[188:191], v[198:199], off nt
	global_load_dwordx4 v[192:195], v[198:199], off offset:512 nt
	s_mov_b64 vcc, 0xa0000
	v_lshl_add_u64 v[196:197], v[196:197], 0, vcc
	v_lshl_add_u64 v[198:199], v[198:199], 0, vcc
	s_mov_b64 vcc, 0x20000
	s_mov_b64 vcc, 0x10000
	v_lshl_add_u64 v[200:201], v[200:201], 0, vcc
	v_lshl_add_u64 v[202:203], v[202:203], 0, vcc
	s_waitcnt lgkmcnt(0)
	v_add_f32_e32 v232, v232, v236
	s_nop 0
	ds_bpermute_b32 v237, v235, v232
	s_waitcnt lgkmcnt(0)
;     __device__ __forceinline__ void operator()(const f32x4 (&acc)[2][2][4][2], const Unit& u, int wr, int wc, int fr, int fq) const {
;     ...
;         for (int ai = 0; ai < 2; ++ai)
; #pragma unroll
;             for (int m = 0; m < 4; ++m) {
;                 const int row = row0 + ai * HALF + m * 16;
;                 const size_t off = (size_t)row * ldc + col0;
;                 float q = 0.f;
; #pragma unroll
;                 for (int bj = 0; bj < 2; ++bj)
; #pragma unroll
;                     for (int n = 0; n < 2; ++n) {
;                         const f32x4 rv = *(const f32x4*)(rbase + off + bj * HALF + n * 16);
;                         const f32x4 v = rv + acc[ai][bj][m][n] * scale;
;                         if (out) *(f32x4*)(out + off + bj * HALF + n * 16) = v;
;                         if (xn) { q += (v.x * v.x + v.y * v.y) + (v.z * v.z + v.w * v.w); const f32x4 o = v * wv[bj][n];
;                             u32x2 p; p.x = pk2(o.x, o.y); p.y = pk2(o.z, o.w); *(u32x2*)(xn + off + bj * HALF + n * 16) = p; }
;                     }
;                 if (xn) { q += __shfl_xor(q, 16); q += __shfl_xor(q, 32); if (fq == 0) (void)__hip_atomic_fetch_add(ss + row, q, __ATOMIC_RELAXED, __HIP_MEMORY_SCOPE_AGENT); }
;             }
	v_add_f32_e32 v232, v232, v237
	s_mov_b64 exec, s[0:1]
	global_atomic_add_f32 v[204:205], v232, off
	s_mov_b64 exec, -1
	s_mov_b64 vcc, 64
	v_lshl_add_u64 v[204:205], v[204:205], 0, vcc
	v_mov_b32_dpp v228, v104 row_ror:8 row_mask:0xf bank_mask:0xf
	v_mov_b32_dpp v229, v105 row_ror:8 row_mask:0xf bank_mask:0xf
	v_mov_b32_dpp v230, v106 row_ror:8 row_mask:0xf bank_mask:0xf
	v_mov_b32_dpp v231, v107 row_ror:8 row_mask:0xf bank_mask:0xf
	v_cndmask_b32_e64 v104, v228, v108, s[24:25]
	v_cndmask_b32_e64 v105, v229, v109, s[24:25]
	v_cndmask_b32_e64 v106, v230, v110, s[24:25]
	v_cndmask_b32_e64 v107, v231, v111, s[24:25]
	v_cndmask_b32_e64 v108, v108, v228, s[24:25]
	v_cndmask_b32_e64 v109, v109, v229, s[24:25]
	v_cndmask_b32_e64 v110, v110, v230, s[24:25]
	v_cndmask_b32_e64 v111, v111, v231, s[24:25]
	v_mov_b32_dpp v228, v92 row_ror:8 row_mask:0xf bank_mask:0xf
	v_mov_b32_dpp v229, v93 row_ror:8 row_mask:0xf bank_mask:0xf
	v_mov_b32_dpp v230, v94 row_ror:8 row_mask:0xf bank_mask:0xf
	v_mov_b32_dpp v231, v95 row_ror:8 row_mask:0xf bank_mask:0xf
	v_cndmask_b32_e64 v92, v228, v100, s[24:25]
	v_cndmask_b32_e64 v93, v229, v101, s[24:25]
	v_cndmask_b32_e64 v94, v230, v102, s[24:25]
	v_cndmask_b32_e64 v95, v231, v103, s[24:25]
	v_cndmask_b32_e64 v100, v100, v228, s[24:25]
	v_cndmask_b32_e64 v101, v101, v229, s[24:25]
	v_cndmask_b32_e64 v102, v102, v230, s[24:25]
	v_cndmask_b32_e64 v103, v103, v231, s[24:25]
	s_waitcnt vmcnt(10)
	v_pk_fma_f32 v[106:107], v[106:107], 0.5, v[158:159] op_sel_hi:[1,0,1]
	v_pk_fma_f32 v[104:105], v[104:105], 0.5, v[156:157] op_sel_hi:[1,0,1]
	v_pk_mul_f32 v[216:217], v[72:73], v[104:105]
	v_pk_mul_f32 v[218:219], v[74:75], v[106:107]
	v_mul_f32_e32 v232, v104, v104
	v_add_u32_e32 v216, 0x8000, v216
	v_add_u32_e32 v217, 0x8000, v217
	v_add_u32_e32 v218, 0x8000, v218
	v_add_u32_e32 v219, 0x8000, v219
	v_fmac_f32_e32 v232, v105, v105
	v_fmac_f32_e32 v232, v106, v106
	v_fmac_f32_e32 v232, v107, v107
	v_perm_b32 v224, v217, v216, s50
	v_perm_b32 v225, v219, v218, s50
	global_store_dwordx2 v[200:201], v[224:225], off
	v_pk_fma_f32 v[94:95], v[94:95], 0.5, v[170:171] op_sel_hi:[1,0,1]
	v_pk_fma_f32 v[92:93], v[92:93], 0.5, v[168:169] op_sel_hi:[1,0,1]
	v_pk_mul_f32 v[220:221], v[84:85], v[92:93]
	v_pk_mul_f32 v[222:223], v[86:87], v[94:95]
	v_fmac_f32_e32 v232, v92, v92
	v_add_u32_e32 v220, 0x8000, v220
	v_add_u32_e32 v221, 0x8000, v221
	v_add_u32_e32 v222, 0x8000, v222
	v_add_u32_e32 v223, 0x8000, v223
	v_fmac_f32_e32 v232, v93, v93
	v_fmac_f32_e32 v232, v94, v94
	v_fmac_f32_e32 v232, v95, v95
	v_perm_b32 v226, v221, v220, s50
	v_perm_b32 v227, v223, v222, s50
	global_store_dwordx2 v[200:201], v[226:227], off offset:256
	v_pk_fma_f32 v[110:111], v[110:111], 0.5, v[174:175] op_sel_hi:[1,0,1]
	v_pk_fma_f32 v[108:109], v[108:109], 0.5, v[172:173] op_sel_hi:[1,0,1]
	v_pk_mul_f32 v[216:217], v[88:89], v[108:109]
	v_pk_mul_f32 v[218:219], v[90:91], v[110:111]
	v_mul_f32_e32 v233, v108, v108
	v_add_u32_e32 v216, 0x8000, v216
	v_add_u32_e32 v217, 0x8000, v217
	v_add_u32_e32 v218, 0x8000, v218
	v_add_u32_e32 v219, 0x8000, v219
	v_fmac_f32_e32 v233, v109, v109
	v_fmac_f32_e32 v233, v110, v110
	v_fmac_f32_e32 v233, v111, v111
	v_perm_b32 v224, v217, v216, s50
	v_perm_b32 v225, v219, v218, s50
	global_store_dwordx2 v[202:203], v[224:225], off
	v_pk_fma_f32 v[102:103], v[102:103], 0.5, v[178:179] op_sel_hi:[1,0,1]
	v_pk_fma_f32 v[100:101], v[100:101], 0.5, v[176:177] op_sel_hi:[1,0,1]
	v_pk_mul_f32 v[220:221], v[96:97], v[100:101]
	v_pk_mul_f32 v[222:223], v[98:99], v[102:103]
	v_fmac_f32_e32 v233, v100, v100
	v_add_u32_e32 v220, 0x8000, v220
	v_add_u32_e32 v221, 0x8000, v221
	v_add_u32_e32 v222, 0x8000, v222
	v_add_u32_e32 v223, 0x8000, v223
	v_fmac_f32_e32 v233, v101, v101
	v_fmac_f32_e32 v233, v102, v102
	v_fmac_f32_e32 v233, v103, v103
	v_perm_b32 v226, v221, v220, s50
	v_perm_b32 v227, v223, v222, s50
	global_store_dwordx2 v[202:203], v[226:227], off offset:256
	s_nop 1
	v_mov_b32_dpp v236, v232 row_ror:8 row_mask:0xf bank_mask:0xf
	v_mov_b32_dpp v237, v233 row_ror:8 row_mask:0xf bank_mask:0xf
	v_add_f32_e32 v232, v232, v236
	v_add_f32_e32 v233, v233, v237
	v_cndmask_b32_e64 v232, v233, v232, s[24:25]
	s_nop 0
	ds_bpermute_b32 v236, v234, v232
	global_load_dwordx4 v[156:159], v[196:197], off nt
	global_load_dwordx4 v[168:171], v[196:197], off offset:512 nt
	global_load_dwordx4 v[172:175], v[198:199], off nt
	global_load_dwordx4 v[176:179], v[198:199], off offset:512 nt
	s_mov_b64 vcc, 0x20000
	v_lshl_add_u64 v[196:197], v[196:197], 0, vcc
	v_lshl_add_u64 v[198:199], v[198:199], 0, vcc
	s_mov_b64 vcc, 0x20000
	s_mov_b64 vcc, 0x10000
	v_lshl_add_u64 v[200:201], v[200:201], 0, vcc
	v_lshl_add_u64 v[202:203], v[202:203], 0, vcc
	s_waitcnt lgkmcnt(0)
	v_add_f32_e32 v232, v232, v236
	s_nop 0
	ds_bpermute_b32 v237, v235, v232
	s_waitcnt lgkmcnt(0)
	v_add_f32_e32 v232, v232, v237
	s_mov_b64 exec, s[0:1]
	global_atomic_add_f32 v[204:205], v232, off
	s_mov_b64 exec, -1
	s_mov_b64 vcc, 64
	v_lshl_add_u64 v[204:205], v[204:205], 0, vcc
	v_mov_b32_dpp v228, v76 row_ror:8 row_mask:0xf bank_mask:0xf
	v_mov_b32_dpp v229, v77 row_ror:8 row_mask:0xf bank_mask:0xf
	v_mov_b32_dpp v230, v78 row_ror:8 row_mask:0xf bank_mask:0xf
	v_mov_b32_dpp v231, v79 row_ror:8 row_mask:0xf bank_mask:0xf
	v_cndmask_b32_e64 v76, v228, v80, s[24:25]
	v_cndmask_b32_e64 v77, v229, v81, s[24:25]
	v_cndmask_b32_e64 v78, v230, v82, s[24:25]
	v_cndmask_b32_e64 v79, v231, v83, s[24:25]
	v_cndmask_b32_e64 v80, v80, v228, s[24:25]
	v_cndmask_b32_e64 v81, v81, v229, s[24:25]
	v_cndmask_b32_e64 v82, v82, v230, s[24:25]
	v_cndmask_b32_e64 v83, v83, v231, s[24:25]
	v_mov_b32_dpp v228, v64 row_ror:8 row_mask:0xf bank_mask:0xf
	v_mov_b32_dpp v229, v65 row_ror:8 row_mask:0xf bank_mask:0xf
	v_mov_b32_dpp v230, v66 row_ror:8 row_mask:0xf bank_mask:0xf
	v_mov_b32_dpp v231, v67 row_ror:8 row_mask:0xf bank_mask:0xf
	v_cndmask_b32_e64 v64, v228, v68, s[24:25]
	v_cndmask_b32_e64 v65, v229, v69, s[24:25]
	v_cndmask_b32_e64 v66, v230, v70, s[24:25]
	v_cndmask_b32_e64 v67, v231, v71, s[24:25]
	v_cndmask_b32_e64 v68, v68, v228, s[24:25]
	v_cndmask_b32_e64 v69, v69, v229, s[24:25]
	v_cndmask_b32_e64 v70, v70, v230, s[24:25]
	v_cndmask_b32_e64 v71, v71, v231, s[24:25]
	s_waitcnt vmcnt(10)
;     __device__ __forceinline__ void operator()(const f32x4 (&acc)[2][2][4][2], const Unit& u, int wr, int wc, int fr, int fq) const {
;     ...
;         for (int ai = 0; ai < 2; ++ai)
; #pragma unroll
;             for (int m = 0; m < 4; ++m) {
;                 const int row = row0 + ai * HALF + m * 16;
;                 const size_t off = (size_t)row * ldc + col0;
;                 float q = 0.f;
; #pragma unroll
;                 for (int bj = 0; bj < 2; ++bj)
; #pragma unroll
;                     for (int n = 0; n < 2; ++n) {
;                         const f32x4 rv = *(const f32x4*)(rbase + off + bj * HALF + n * 16);
;                         const f32x4 v = rv + acc[ai][bj][m][n] * scale;
;                         if (out) *(f32x4*)(out + off + bj * HALF + n * 16) = v;
;                         if (xn) { q += (v.x * v.x + v.y * v.y) + (v.z * v.z + v.w * v.w); const f32x4 o = v * wv[bj][n];
;                             u32x2 p; p.x = pk2(o.x, o.y); p.y = pk2(o.z, o.w); *(u32x2*)(xn + off + bj * HALF + n * 16) = p; }
;                     }
;                 if (xn) { q += __shfl_xor(q, 16); q += __shfl_xor(q, 32); if (fq == 0) (void)__hip_atomic_fetch_add(ss + row, q, __ATOMIC_RELAXED, __HIP_MEMORY_SCOPE_AGENT); }
;             }
	v_pk_fma_f32 v[78:79], v[78:79], 0.5, v[182:183] op_sel_hi:[1,0,1]
	v_pk_fma_f32 v[76:77], v[76:77], 0.5, v[180:181] op_sel_hi:[1,0,1]
	v_pk_mul_f32 v[216:217], v[72:73], v[76:77]
	v_pk_mul_f32 v[218:219], v[74:75], v[78:79]
	v_mul_f32_e32 v232, v76, v76
	v_add_u32_e32 v216, 0x8000, v216
	v_add_u32_e32 v217, 0x8000, v217
	v_add_u32_e32 v218, 0x8000, v218
	v_add_u32_e32 v219, 0x8000, v219
	v_fmac_f32_e32 v232, v77, v77
	v_fmac_f32_e32 v232, v78, v78
	v_fmac_f32_e32 v232, v79, v79
	v_perm_b32 v224, v217, v216, s50
	v_perm_b32 v225, v219, v218, s50
	global_store_dwordx2 v[200:201], v[224:225], off
	v_pk_fma_f32 v[66:67], v[66:67], 0.5, v[186:187] op_sel_hi:[1,0,1]
	v_pk_fma_f32 v[64:65], v[64:65], 0.5, v[184:185] op_sel_hi:[1,0,1]
	v_pk_mul_f32 v[220:221], v[84:85], v[64:65]
	v_pk_mul_f32 v[222:223], v[86:87], v[66:67]
	v_fmac_f32_e32 v232, v64, v64
	v_add_u32_e32 v220, 0x8000, v220
	v_add_u32_e32 v221, 0x8000, v221
	v_add_u32_e32 v222, 0x8000, v222
	v_add_u32_e32 v223, 0x8000, v223
	v_fmac_f32_e32 v232, v65, v65
	v_fmac_f32_e32 v232, v66, v66
	v_fmac_f32_e32 v232, v67, v67
	v_perm_b32 v226, v221, v220, s50
	v_perm_b32 v227, v223, v222, s50
	global_store_dwordx2 v[200:201], v[226:227], off offset:256
	v_pk_fma_f32 v[82:83], v[82:83], 0.5, v[190:191] op_sel_hi:[1,0,1]
	v_pk_fma_f32 v[80:81], v[80:81], 0.5, v[188:189] op_sel_hi:[1,0,1]
	v_pk_mul_f32 v[216:217], v[88:89], v[80:81]
	v_pk_mul_f32 v[218:219], v[90:91], v[82:83]
	v_mul_f32_e32 v233, v80, v80
	v_add_u32_e32 v216, 0x8000, v216
	v_add_u32_e32 v217, 0x8000, v217
	v_add_u32_e32 v218, 0x8000, v218
	v_add_u32_e32 v219, 0x8000, v219
	v_fmac_f32_e32 v233, v81, v81
	v_fmac_f32_e32 v233, v82, v82
	v_fmac_f32_e32 v233, v83, v83
	v_perm_b32 v224, v217, v216, s50
	v_perm_b32 v225, v219, v218, s50
	global_store_dwordx2 v[202:203], v[224:225], off
	v_pk_fma_f32 v[70:71], v[70:71], 0.5, v[194:195] op_sel_hi:[1,0,1]
	v_pk_fma_f32 v[68:69], v[68:69], 0.5, v[192:193] op_sel_hi:[1,0,1]
	v_pk_mul_f32 v[220:221], v[96:97], v[68:69]
	v_pk_mul_f32 v[222:223], v[98:99], v[70:71]
	v_fmac_f32_e32 v233, v68, v68
	v_add_u32_e32 v220, 0x8000, v220
	v_add_u32_e32 v221, 0x8000, v221
	v_add_u32_e32 v222, 0x8000, v222
	v_add_u32_e32 v223, 0x8000, v223
	v_fmac_f32_e32 v233, v69, v69
	v_fmac_f32_e32 v233, v70, v70
	v_fmac_f32_e32 v233, v71, v71
	v_perm_b32 v226, v221, v220, s50
	v_perm_b32 v227, v223, v222, s50
	global_store_dwordx2 v[202:203], v[226:227], off offset:256
	s_nop 1
	v_mov_b32_dpp v236, v232 row_ror:8 row_mask:0xf bank_mask:0xf
	v_mov_b32_dpp v237, v233 row_ror:8 row_mask:0xf bank_mask:0xf
	v_add_f32_e32 v232, v232, v236
	v_add_f32_e32 v233, v233, v237
	v_cndmask_b32_e64 v232, v233, v232, s[24:25]
	s_nop 0
	ds_bpermute_b32 v236, v234, v232
	global_load_dwordx4 v[180:183], v[196:197], off nt
	global_load_dwordx4 v[184:187], v[196:197], off offset:512 nt
	global_load_dwordx4 v[188:191], v[198:199], off nt
	global_load_dwordx4 v[192:195], v[198:199], off offset:512 nt
	s_mov_b64 vcc, 0x20000
	v_lshl_add_u64 v[196:197], v[196:197], 0, vcc
	v_lshl_add_u64 v[198:199], v[198:199], 0, vcc
	s_mov_b64 vcc, 0xa0000
	s_mov_b64 vcc, 0x50000
	v_lshl_add_u64 v[200:201], v[200:201], 0, vcc
	v_lshl_add_u64 v[202:203], v[202:203], 0, vcc
	s_waitcnt lgkmcnt(0)
	v_add_f32_e32 v232, v232, v236
	s_nop 0
	ds_bpermute_b32 v237, v235, v232
	s_waitcnt lgkmcnt(0)
	v_add_f32_e32 v232, v232, v237
	s_mov_b64 exec, s[0:1]
	global_atomic_add_f32 v[204:205], v232, off
	s_mov_b64 exec, -1
	s_mov_b64 vcc, 320
	v_lshl_add_u64 v[204:205], v[204:205], 0, vcc
	v_mov_b32_dpp v228, v56 row_ror:8 row_mask:0xf bank_mask:0xf
	v_mov_b32_dpp v229, v57 row_ror:8 row_mask:0xf bank_mask:0xf
	v_mov_b32_dpp v230, v58 row_ror:8 row_mask:0xf bank_mask:0xf
	v_mov_b32_dpp v231, v59 row_ror:8 row_mask:0xf bank_mask:0xf
	v_cndmask_b32_e64 v56, v228, v60, s[24:25]
	v_cndmask_b32_e64 v57, v229, v61, s[24:25]
	v_cndmask_b32_e64 v58, v230, v62, s[24:25]
	v_cndmask_b32_e64 v59, v231, v63, s[24:25]
	v_cndmask_b32_e64 v60, v60, v228, s[24:25]
	v_cndmask_b32_e64 v61, v61, v229, s[24:25]
	v_cndmask_b32_e64 v62, v62, v230, s[24:25]
	v_cndmask_b32_e64 v63, v63, v231, s[24:25]
	v_mov_b32_dpp v228, v48 row_ror:8 row_mask:0xf bank_mask:0xf
	v_mov_b32_dpp v229, v49 row_ror:8 row_mask:0xf bank_mask:0xf
	v_mov_b32_dpp v230, v50 row_ror:8 row_mask:0xf bank_mask:0xf
	v_mov_b32_dpp v231, v51 row_ror:8 row_mask:0xf bank_mask:0xf
	v_cndmask_b32_e64 v48, v228, v52, s[24:25]
	v_cndmask_b32_e64 v49, v229, v53, s[24:25]
	v_cndmask_b32_e64 v50, v230, v54, s[24:25]
	v_cndmask_b32_e64 v51, v231, v55, s[24:25]
	v_cndmask_b32_e64 v52, v52, v228, s[24:25]
	v_cndmask_b32_e64 v53, v53, v229, s[24:25]
	v_cndmask_b32_e64 v54, v54, v230, s[24:25]
	v_cndmask_b32_e64 v55, v55, v231, s[24:25]
	s_waitcnt vmcnt(10)
;     __device__ __forceinline__ void operator()(const f32x4 (&acc)[2][2][4][2], const Unit& u, int wr, int wc, int fr, int fq) const {
;     ...
;         for (int ai = 0; ai < 2; ++ai)
; #pragma unroll
;             for (int m = 0; m < 4; ++m) {
;                 const int row = row0 + ai * HALF + m * 16;
;                 const size_t off = (size_t)row * ldc + col0;
;                 float q = 0.f;
; #pragma unroll
;                 for (int bj = 0; bj < 2; ++bj)
; #pragma unroll
;                     for (int n = 0; n < 2; ++n) {
;                         const f32x4 rv = *(const f32x4*)(rbase + off + bj * HALF + n * 16);
;                         const f32x4 v = rv + acc[ai][bj][m][n] * scale;
;                         if (out) *(f32x4*)(out + off + bj * HALF + n * 16) = v;
;                         if (xn) { q += (v.x * v.x + v.y * v.y) + (v.z * v.z + v.w * v.w); const f32x4 o = v * wv[bj][n];
;                             u32x2 p; p.x = pk2(o.x, o.y); p.y = pk2(o.z, o.w); *(u32x2*)(xn + off + bj * HALF + n * 16) = p; }
;                     }
;                 if (xn) { q += __shfl_xor(q, 16); q += __shfl_xor(q, 32); if (fq == 0) (void)__hip_atomic_fetch_add(ss + row, q, __ATOMIC_RELAXED, __HIP_MEMORY_SCOPE_AGENT); }
;             }
	v_pk_fma_f32 v[58:59], v[58:59], 0.5, v[158:159] op_sel_hi:[1,0,1]
	v_pk_fma_f32 v[56:57], v[56:57], 0.5, v[156:157] op_sel_hi:[1,0,1]
	v_pk_mul_f32 v[216:217], v[72:73], v[56:57]
	v_pk_mul_f32 v[218:219], v[74:75], v[58:59]
	v_mul_f32_e32 v232, v56, v56
	v_add_u32_e32 v216, 0x8000, v216
	v_add_u32_e32 v217, 0x8000, v217
	v_add_u32_e32 v218, 0x8000, v218
	v_add_u32_e32 v219, 0x8000, v219
	v_fmac_f32_e32 v232, v57, v57
	v_fmac_f32_e32 v232, v58, v58
	v_fmac_f32_e32 v232, v59, v59
	v_perm_b32 v224, v217, v216, s50
	v_perm_b32 v225, v219, v218, s50
	global_store_dwordx2 v[200:201], v[224:225], off
	v_pk_fma_f32 v[50:51], v[50:51], 0.5, v[170:171] op_sel_hi:[1,0,1]
	v_pk_fma_f32 v[48:49], v[48:49], 0.5, v[168:169] op_sel_hi:[1,0,1]
	v_pk_mul_f32 v[220:221], v[84:85], v[48:49]
	v_pk_mul_f32 v[222:223], v[86:87], v[50:51]
	v_fmac_f32_e32 v232, v48, v48
	v_add_u32_e32 v220, 0x8000, v220
	v_add_u32_e32 v221, 0x8000, v221
	v_add_u32_e32 v222, 0x8000, v222
	v_add_u32_e32 v223, 0x8000, v223
	v_fmac_f32_e32 v232, v49, v49
	v_fmac_f32_e32 v232, v50, v50
	v_fmac_f32_e32 v232, v51, v51
	v_perm_b32 v226, v221, v220, s50
	v_perm_b32 v227, v223, v222, s50
	global_store_dwordx2 v[200:201], v[226:227], off offset:256
	v_pk_fma_f32 v[62:63], v[62:63], 0.5, v[174:175] op_sel_hi:[1,0,1]
	v_pk_fma_f32 v[60:61], v[60:61], 0.5, v[172:173] op_sel_hi:[1,0,1]
	v_pk_mul_f32 v[216:217], v[88:89], v[60:61]
	v_pk_mul_f32 v[218:219], v[90:91], v[62:63]
	v_mul_f32_e32 v233, v60, v60
	v_add_u32_e32 v216, 0x8000, v216
	v_add_u32_e32 v217, 0x8000, v217
	v_add_u32_e32 v218, 0x8000, v218
	v_add_u32_e32 v219, 0x8000, v219
	v_fmac_f32_e32 v233, v61, v61
	v_fmac_f32_e32 v233, v62, v62
	v_fmac_f32_e32 v233, v63, v63
	v_perm_b32 v224, v217, v216, s50
	v_perm_b32 v225, v219, v218, s50
	global_store_dwordx2 v[202:203], v[224:225], off
	v_pk_fma_f32 v[54:55], v[54:55], 0.5, v[178:179] op_sel_hi:[1,0,1]
	v_pk_fma_f32 v[52:53], v[52:53], 0.5, v[176:177] op_sel_hi:[1,0,1]
	v_pk_mul_f32 v[220:221], v[96:97], v[52:53]
	v_pk_mul_f32 v[222:223], v[98:99], v[54:55]
	v_fmac_f32_e32 v233, v52, v52
	v_add_u32_e32 v220, 0x8000, v220
	v_add_u32_e32 v221, 0x8000, v221
	v_add_u32_e32 v222, 0x8000, v222
	v_add_u32_e32 v223, 0x8000, v223
	v_fmac_f32_e32 v233, v53, v53
	v_fmac_f32_e32 v233, v54, v54
	v_fmac_f32_e32 v233, v55, v55
	v_perm_b32 v226, v221, v220, s50
	v_perm_b32 v227, v223, v222, s50
	global_store_dwordx2 v[202:203], v[226:227], off offset:256
	s_nop 1
	v_mov_b32_dpp v236, v232 row_ror:8 row_mask:0xf bank_mask:0xf
	v_mov_b32_dpp v237, v233 row_ror:8 row_mask:0xf bank_mask:0xf
	v_add_f32_e32 v232, v232, v236
	v_add_f32_e32 v233, v233, v237
	v_cndmask_b32_e64 v232, v233, v232, s[24:25]
	s_nop 0
	ds_bpermute_b32 v236, v234, v232
	global_load_dwordx4 v[156:159], v[196:197], off nt
	global_load_dwordx4 v[168:171], v[196:197], off offset:512 nt
	global_load_dwordx4 v[172:175], v[198:199], off nt
	global_load_dwordx4 v[176:179], v[198:199], off offset:512 nt
	s_mov_b64 vcc, 0x20000
	v_lshl_add_u64 v[196:197], v[196:197], 0, vcc
	v_lshl_add_u64 v[198:199], v[198:199], 0, vcc
	s_mov_b64 vcc, 0x20000
	s_mov_b64 vcc, 0x10000
	v_lshl_add_u64 v[200:201], v[200:201], 0, vcc
	v_lshl_add_u64 v[202:203], v[202:203], 0, vcc
	s_waitcnt lgkmcnt(0)
	v_add_f32_e32 v232, v232, v236
	s_nop 0
	ds_bpermute_b32 v237, v235, v232
	s_waitcnt lgkmcnt(0)
	v_add_f32_e32 v232, v232, v237
	s_mov_b64 exec, s[0:1]
	global_atomic_add_f32 v[204:205], v232, off
	s_mov_b64 exec, -1
	s_mov_b64 vcc, 64
	v_lshl_add_u64 v[204:205], v[204:205], 0, vcc
	v_mov_b32_dpp v228, v40 row_ror:8 row_mask:0xf bank_mask:0xf
	v_mov_b32_dpp v229, v41 row_ror:8 row_mask:0xf bank_mask:0xf
	v_mov_b32_dpp v230, v42 row_ror:8 row_mask:0xf bank_mask:0xf
	v_mov_b32_dpp v231, v43 row_ror:8 row_mask:0xf bank_mask:0xf
	v_cndmask_b32_e64 v40, v228, v44, s[24:25]
	v_cndmask_b32_e64 v41, v229, v45, s[24:25]
	v_cndmask_b32_e64 v42, v230, v46, s[24:25]
	v_cndmask_b32_e64 v43, v231, v47, s[24:25]
	v_cndmask_b32_e64 v44, v44, v228, s[24:25]
	v_cndmask_b32_e64 v45, v45, v229, s[24:25]
	v_cndmask_b32_e64 v46, v46, v230, s[24:25]
	v_cndmask_b32_e64 v47, v47, v231, s[24:25]
	v_mov_b32_dpp v228, v32 row_ror:8 row_mask:0xf bank_mask:0xf
	v_mov_b32_dpp v229, v33 row_ror:8 row_mask:0xf bank_mask:0xf
	v_mov_b32_dpp v230, v34 row_ror:8 row_mask:0xf bank_mask:0xf
	v_mov_b32_dpp v231, v35 row_ror:8 row_mask:0xf bank_mask:0xf
	v_cndmask_b32_e64 v32, v228, v36, s[24:25]
	v_cndmask_b32_e64 v33, v229, v37, s[24:25]
	v_cndmask_b32_e64 v34, v230, v38, s[24:25]
	v_cndmask_b32_e64 v35, v231, v39, s[24:25]
	v_cndmask_b32_e64 v36, v36, v228, s[24:25]
	v_cndmask_b32_e64 v37, v37, v229, s[24:25]
	v_cndmask_b32_e64 v38, v38, v230, s[24:25]
	v_cndmask_b32_e64 v39, v39, v231, s[24:25]
	s_waitcnt vmcnt(10)
;     __device__ __forceinline__ void operator()(const f32x4 (&acc)[2][2][4][2], const Unit& u, int wr, int wc, int fr, int fq) const {
;     ...
;         for (int ai = 0; ai < 2; ++ai)
; #pragma unroll
;             for (int m = 0; m < 4; ++m) {
;                 const int row = row0 + ai * HALF + m * 16;
;                 const size_t off = (size_t)row * ldc + col0;
;                 float q = 0.f;
; #pragma unroll
;                 for (int bj = 0; bj < 2; ++bj)
; #pragma unroll
;                     for (int n = 0; n < 2; ++n) {
;                         const f32x4 rv = *(const f32x4*)(rbase + off + bj * HALF + n * 16);
;                         const f32x4 v = rv + acc[ai][bj][m][n] * scale;
;                         if (out) *(f32x4*)(out + off + bj * HALF + n * 16) = v;
;                         if (xn) { q += (v.x * v.x + v.y * v.y) + (v.z * v.z + v.w * v.w); const f32x4 o = v * wv[bj][n];
;                             u32x2 p; p.x = pk2(o.x, o.y); p.y = pk2(o.z, o.w); *(u32x2*)(xn + off + bj * HALF + n * 16) = p; }
;                     }
;                 if (xn) { q += __shfl_xor(q, 16); q += __shfl_xor(q, 32); if (fq == 0) (void)__hip_atomic_fetch_add(ss + row, q, __ATOMIC_RELAXED, __HIP_MEMORY_SCOPE_AGENT); }
;             }
	v_pk_fma_f32 v[42:43], v[42:43], 0.5, v[182:183] op_sel_hi:[1,0,1]
	v_pk_fma_f32 v[40:41], v[40:41], 0.5, v[180:181] op_sel_hi:[1,0,1]
	v_pk_mul_f32 v[216:217], v[72:73], v[40:41]
	v_pk_mul_f32 v[218:219], v[74:75], v[42:43]
	v_mul_f32_e32 v232, v40, v40
	v_add_u32_e32 v216, 0x8000, v216
	v_add_u32_e32 v217, 0x8000, v217
	v_add_u32_e32 v218, 0x8000, v218
	v_add_u32_e32 v219, 0x8000, v219
	v_fmac_f32_e32 v232, v41, v41
	v_fmac_f32_e32 v232, v42, v42
	v_fmac_f32_e32 v232, v43, v43
	v_perm_b32 v224, v217, v216, s50
	v_perm_b32 v225, v219, v218, s50
	global_store_dwordx2 v[200:201], v[224:225], off
	v_pk_fma_f32 v[34:35], v[34:35], 0.5, v[186:187] op_sel_hi:[1,0,1]
	v_pk_fma_f32 v[32:33], v[32:33], 0.5, v[184:185] op_sel_hi:[1,0,1]
	v_pk_mul_f32 v[220:221], v[84:85], v[32:33]
	v_pk_mul_f32 v[222:223], v[86:87], v[34:35]
	v_fmac_f32_e32 v232, v32, v32
	v_add_u32_e32 v220, 0x8000, v220
	v_add_u32_e32 v221, 0x8000, v221
	v_add_u32_e32 v222, 0x8000, v222
	v_add_u32_e32 v223, 0x8000, v223
	v_fmac_f32_e32 v232, v33, v33
	v_fmac_f32_e32 v232, v34, v34
	v_fmac_f32_e32 v232, v35, v35
	v_perm_b32 v226, v221, v220, s50
	v_perm_b32 v227, v223, v222, s50
	global_store_dwordx2 v[200:201], v[226:227], off offset:256
	v_pk_fma_f32 v[46:47], v[46:47], 0.5, v[190:191] op_sel_hi:[1,0,1]
	v_pk_fma_f32 v[44:45], v[44:45], 0.5, v[188:189] op_sel_hi:[1,0,1]
	v_pk_mul_f32 v[216:217], v[88:89], v[44:45]
	v_pk_mul_f32 v[218:219], v[90:91], v[46:47]
	v_mul_f32_e32 v233, v44, v44
	v_add_u32_e32 v216, 0x8000, v216
	v_add_u32_e32 v217, 0x8000, v217
	v_add_u32_e32 v218, 0x8000, v218
	v_add_u32_e32 v219, 0x8000, v219
	v_fmac_f32_e32 v233, v45, v45
	v_fmac_f32_e32 v233, v46, v46
	v_fmac_f32_e32 v233, v47, v47
	v_perm_b32 v224, v217, v216, s50
	v_perm_b32 v225, v219, v218, s50
	global_store_dwordx2 v[202:203], v[224:225], off
	v_pk_fma_f32 v[38:39], v[38:39], 0.5, v[194:195] op_sel_hi:[1,0,1]
	v_pk_fma_f32 v[36:37], v[36:37], 0.5, v[192:193] op_sel_hi:[1,0,1]
	v_pk_mul_f32 v[220:221], v[96:97], v[36:37]
	v_pk_mul_f32 v[222:223], v[98:99], v[38:39]
	v_fmac_f32_e32 v233, v36, v36
	v_add_u32_e32 v220, 0x8000, v220
	v_add_u32_e32 v221, 0x8000, v221
	v_add_u32_e32 v222, 0x8000, v222
	v_add_u32_e32 v223, 0x8000, v223
	v_fmac_f32_e32 v233, v37, v37
	v_fmac_f32_e32 v233, v38, v38
	v_fmac_f32_e32 v233, v39, v39
	v_perm_b32 v226, v221, v220, s50
	v_perm_b32 v227, v223, v222, s50
	global_store_dwordx2 v[202:203], v[226:227], off offset:256
	s_nop 1
	v_mov_b32_dpp v236, v232 row_ror:8 row_mask:0xf bank_mask:0xf
	v_mov_b32_dpp v237, v233 row_ror:8 row_mask:0xf bank_mask:0xf
	v_add_f32_e32 v232, v232, v236
	v_add_f32_e32 v233, v233, v237
	v_cndmask_b32_e64 v232, v233, v232, s[24:25]
	s_nop 0
	ds_bpermute_b32 v236, v234, v232
	global_load_dwordx4 v[180:183], v[196:197], off nt
	global_load_dwordx4 v[184:187], v[196:197], off offset:512 nt
	global_load_dwordx4 v[188:191], v[198:199], off nt
	global_load_dwordx4 v[192:195], v[198:199], off offset:512 nt
	s_mov_b64 vcc, 0x20000
	s_mov_b64 vcc, 0x10000
	v_lshl_add_u64 v[200:201], v[200:201], 0, vcc
	v_lshl_add_u64 v[202:203], v[202:203], 0, vcc
	s_waitcnt lgkmcnt(0)
	v_add_f32_e32 v232, v232, v236
	s_nop 0
	ds_bpermute_b32 v237, v235, v232
	s_waitcnt lgkmcnt(0)
	v_add_f32_e32 v232, v232, v237
	s_mov_b64 exec, s[0:1]
	global_atomic_add_f32 v[204:205], v232, off
	s_mov_b64 exec, -1
	s_mov_b64 vcc, 64
	v_lshl_add_u64 v[204:205], v[204:205], 0, vcc
	v_mov_b32_dpp v228, v24 row_ror:8 row_mask:0xf bank_mask:0xf
	v_mov_b32_dpp v229, v25 row_ror:8 row_mask:0xf bank_mask:0xf
	v_mov_b32_dpp v230, v26 row_ror:8 row_mask:0xf bank_mask:0xf
	v_mov_b32_dpp v231, v27 row_ror:8 row_mask:0xf bank_mask:0xf
	v_cndmask_b32_e64 v24, v228, v28, s[24:25]
	v_cndmask_b32_e64 v25, v229, v29, s[24:25]
	v_cndmask_b32_e64 v26, v230, v30, s[24:25]
	v_cndmask_b32_e64 v27, v231, v31, s[24:25]
	v_cndmask_b32_e64 v28, v28, v228, s[24:25]
	v_cndmask_b32_e64 v29, v29, v229, s[24:25]
	v_cndmask_b32_e64 v30, v30, v230, s[24:25]
	v_cndmask_b32_e64 v31, v31, v231, s[24:25]
	v_mov_b32_dpp v228, v16 row_ror:8 row_mask:0xf bank_mask:0xf
	v_mov_b32_dpp v229, v17 row_ror:8 row_mask:0xf bank_mask:0xf
	v_mov_b32_dpp v230, v18 row_ror:8 row_mask:0xf bank_mask:0xf
	v_mov_b32_dpp v231, v19 row_ror:8 row_mask:0xf bank_mask:0xf
	v_cndmask_b32_e64 v16, v228, v20, s[24:25]
	v_cndmask_b32_e64 v17, v229, v21, s[24:25]
	v_cndmask_b32_e64 v18, v230, v22, s[24:25]
	v_cndmask_b32_e64 v19, v231, v23, s[24:25]
	v_cndmask_b32_e64 v20, v20, v228, s[24:25]
	v_cndmask_b32_e64 v21, v21, v229, s[24:25]
	v_cndmask_b32_e64 v22, v22, v230, s[24:25]
	v_cndmask_b32_e64 v23, v23, v231, s[24:25]
	s_waitcnt vmcnt(10)
;     __device__ __forceinline__ void operator()(const f32x4 (&acc)[2][2][4][2], const Unit& u, int wr, int wc, int fr, int fq) const {
;     ...
;         for (int ai = 0; ai < 2; ++ai)
; #pragma unroll
;             for (int m = 0; m < 4; ++m) {
;                 const int row = row0 + ai * HALF + m * 16;
;                 const size_t off = (size_t)row * ldc + col0;
;                 float q = 0.f;
; #pragma unroll
;                 for (int bj = 0; bj < 2; ++bj)
; #pragma unroll
;                     for (int n = 0; n < 2; ++n) {
;                         const f32x4 rv = *(const f32x4*)(rbase + off + bj * HALF + n * 16);
;                         const f32x4 v = rv + acc[ai][bj][m][n] * scale;
;                         if (out) *(f32x4*)(out + off + bj * HALF + n * 16) = v;
;                         if (xn) { q += (v.x * v.x + v.y * v.y) + (v.z * v.z + v.w * v.w); const f32x4 o = v * wv[bj][n];
;                             u32x2 p; p.x = pk2(o.x, o.y); p.y = pk2(o.z, o.w); *(u32x2*)(xn + off + bj * HALF + n * 16) = p; }
;                     }
;                 if (xn) { q += __shfl_xor(q, 16); q += __shfl_xor(q, 32); if (fq == 0) (void)__hip_atomic_fetch_add(ss + row, q, __ATOMIC_RELAXED, __HIP_MEMORY_SCOPE_AGENT); }
;             }
	v_pk_fma_f32 v[26:27], v[26:27], 0.5, v[158:159] op_sel_hi:[1,0,1]
	v_pk_fma_f32 v[24:25], v[24:25], 0.5, v[156:157] op_sel_hi:[1,0,1]
	v_pk_mul_f32 v[216:217], v[72:73], v[24:25]
	v_pk_mul_f32 v[218:219], v[74:75], v[26:27]
	v_mul_f32_e32 v232, v24, v24
	v_add_u32_e32 v216, 0x8000, v216
	v_add_u32_e32 v217, 0x8000, v217
	v_add_u32_e32 v218, 0x8000, v218
	v_add_u32_e32 v219, 0x8000, v219
	v_fmac_f32_e32 v232, v25, v25
	v_fmac_f32_e32 v232, v26, v26
	v_fmac_f32_e32 v232, v27, v27
	v_perm_b32 v224, v217, v216, s50
	v_perm_b32 v225, v219, v218, s50
	global_store_dwordx2 v[200:201], v[224:225], off
	v_pk_fma_f32 v[18:19], v[18:19], 0.5, v[170:171] op_sel_hi:[1,0,1]
	v_pk_fma_f32 v[16:17], v[16:17], 0.5, v[168:169] op_sel_hi:[1,0,1]
	v_pk_mul_f32 v[220:221], v[84:85], v[16:17]
	v_pk_mul_f32 v[222:223], v[86:87], v[18:19]
	v_fmac_f32_e32 v232, v16, v16
	v_add_u32_e32 v220, 0x8000, v220
	v_add_u32_e32 v221, 0x8000, v221
	v_add_u32_e32 v222, 0x8000, v222
	v_add_u32_e32 v223, 0x8000, v223
	v_fmac_f32_e32 v232, v17, v17
	v_fmac_f32_e32 v232, v18, v18
	v_fmac_f32_e32 v232, v19, v19
	v_perm_b32 v226, v221, v220, s50
	v_perm_b32 v227, v223, v222, s50
	global_store_dwordx2 v[200:201], v[226:227], off offset:256
	v_pk_fma_f32 v[30:31], v[30:31], 0.5, v[174:175] op_sel_hi:[1,0,1]
	v_pk_fma_f32 v[28:29], v[28:29], 0.5, v[172:173] op_sel_hi:[1,0,1]
	v_pk_mul_f32 v[216:217], v[88:89], v[28:29]
	v_pk_mul_f32 v[218:219], v[90:91], v[30:31]
	v_mul_f32_e32 v233, v28, v28
	v_add_u32_e32 v216, 0x8000, v216
	v_add_u32_e32 v217, 0x8000, v217
	v_add_u32_e32 v218, 0x8000, v218
	v_add_u32_e32 v219, 0x8000, v219
	v_fmac_f32_e32 v233, v29, v29
	v_fmac_f32_e32 v233, v30, v30
	v_fmac_f32_e32 v233, v31, v31
	v_perm_b32 v224, v217, v216, s50
	v_perm_b32 v225, v219, v218, s50
	global_store_dwordx2 v[202:203], v[224:225], off
	v_pk_fma_f32 v[22:23], v[22:23], 0.5, v[178:179] op_sel_hi:[1,0,1]
	v_pk_fma_f32 v[20:21], v[20:21], 0.5, v[176:177] op_sel_hi:[1,0,1]
	v_pk_mul_f32 v[220:221], v[96:97], v[20:21]
	v_pk_mul_f32 v[222:223], v[98:99], v[22:23]
	v_fmac_f32_e32 v233, v20, v20
	v_add_u32_e32 v220, 0x8000, v220
	v_add_u32_e32 v221, 0x8000, v221
	v_add_u32_e32 v222, 0x8000, v222
	v_add_u32_e32 v223, 0x8000, v223
	v_fmac_f32_e32 v233, v21, v21
	v_fmac_f32_e32 v233, v22, v22
	v_fmac_f32_e32 v233, v23, v23
	v_perm_b32 v226, v221, v220, s50
	v_perm_b32 v227, v223, v222, s50
	global_store_dwordx2 v[202:203], v[226:227], off offset:256
	s_nop 1
	v_mov_b32_dpp v236, v232 row_ror:8 row_mask:0xf bank_mask:0xf
	v_mov_b32_dpp v237, v233 row_ror:8 row_mask:0xf bank_mask:0xf
	v_add_f32_e32 v232, v232, v236
	v_add_f32_e32 v233, v233, v237
	v_cndmask_b32_e64 v232, v233, v232, s[24:25]
	s_nop 0
	ds_bpermute_b32 v236, v234, v232
	s_mov_b64 vcc, 0x20000
	s_mov_b64 vcc, 0x10000
	v_lshl_add_u64 v[200:201], v[200:201], 0, vcc
	v_lshl_add_u64 v[202:203], v[202:203], 0, vcc
	s_waitcnt lgkmcnt(0)
	v_add_f32_e32 v232, v232, v236
	s_nop 0
	ds_bpermute_b32 v237, v235, v232
	s_waitcnt lgkmcnt(0)
	v_add_f32_e32 v232, v232, v237
	s_mov_b64 exec, s[0:1]
	global_atomic_add_f32 v[204:205], v232, off
	s_mov_b64 exec, -1
	s_mov_b64 vcc, 64
	v_lshl_add_u64 v[204:205], v[204:205], 0, vcc
	v_mov_b32_dpp v228, v8 row_ror:8 row_mask:0xf bank_mask:0xf
	v_mov_b32_dpp v229, v9 row_ror:8 row_mask:0xf bank_mask:0xf
	v_mov_b32_dpp v230, v10 row_ror:8 row_mask:0xf bank_mask:0xf
	v_mov_b32_dpp v231, v11 row_ror:8 row_mask:0xf bank_mask:0xf
	v_cndmask_b32_e64 v8, v228, v12, s[24:25]
	v_cndmask_b32_e64 v9, v229, v13, s[24:25]
	v_cndmask_b32_e64 v10, v230, v14, s[24:25]
	v_cndmask_b32_e64 v11, v231, v15, s[24:25]
	v_cndmask_b32_e64 v12, v12, v228, s[24:25]
	v_cndmask_b32_e64 v13, v13, v229, s[24:25]
	v_cndmask_b32_e64 v14, v14, v230, s[24:25]
	v_cndmask_b32_e64 v15, v15, v231, s[24:25]
	v_mov_b32_dpp v228, v0 row_ror:8 row_mask:0xf bank_mask:0xf
	v_mov_b32_dpp v229, v1 row_ror:8 row_mask:0xf bank_mask:0xf
	v_mov_b32_dpp v230, v2 row_ror:8 row_mask:0xf bank_mask:0xf
	v_mov_b32_dpp v231, v3 row_ror:8 row_mask:0xf bank_mask:0xf
	v_cndmask_b32_e64 v0, v228, v4, s[24:25]
	v_cndmask_b32_e64 v1, v229, v5, s[24:25]
	v_cndmask_b32_e64 v2, v230, v6, s[24:25]
	v_cndmask_b32_e64 v3, v231, v7, s[24:25]
	v_cndmask_b32_e64 v4, v4, v228, s[24:25]
	v_cndmask_b32_e64 v5, v5, v229, s[24:25]
	v_cndmask_b32_e64 v6, v6, v230, s[24:25]
	v_cndmask_b32_e64 v7, v7, v231, s[24:25]
	s_waitcnt vmcnt(6)
; #define PG8_BAR __builtin_amdgcn_s_barrier()
;     __device__ __forceinline__ void operator()(const f32x4 (&acc)[2][2][4][2], const Unit& u, int wr, int wc, int fr, int fq) const {
;     ...
;         for (int ai = 0; ai < 2; ++ai)
; #pragma unroll
;             for (int m = 0; m < 4; ++m) {
;                 const int row = row0 + ai * HALF + m * 16;
;                 const size_t off = (size_t)row * ldc + col0;
;                 float q = 0.f;
; #pragma unroll
;                 for (int bj = 0; bj < 2; ++bj)
; #pragma unroll
;                     for (int n = 0; n < 2; ++n) {
;                         const f32x4 rv = *(const f32x4*)(rbase + off + bj * HALF + n * 16);
;                         const f32x4 v = rv + acc[ai][bj][m][n] * scale;
;                         if (out) *(f32x4*)(out + off + bj * HALF + n * 16) = v;
;                         if (xn) { q += (v.x * v.x + v.y * v.y) + (v.z * v.z + v.w * v.w); const f32x4 o = v * wv[bj][n];
;                             u32x2 p; p.x = pk2(o.x, o.y); p.y = pk2(o.z, o.w); *(u32x2*)(xn + off + bj * HALF + n * 16) = p; }
;                     }
;                 if (xn) { q += __shfl_xor(q, 16); q += __shfl_xor(q, 32); if (fq == 0) (void)__hip_atomic_fetch_add(ss + row, q, __ATOMIC_RELAXED, __HIP_MEMORY_SCOPE_AGENT); }
;             }
; template <class Epi, bool ALIGN_EPI>
; __device__ __forceinline__ void gemm_phase(LAS unsigned char* lds, const Gemm g, const StaticOrder& S, const Epi& E) {
;     ...
;         if (!has_next) break;
; #pragma unroll
;         for (int a = 0; a < 2; ++a)
; #pragma unroll
;             for (int b = 0; b < 2; ++b)
; #pragma unroll
;                 for (int m = 0; m < 4; ++m)
; #pragma unroll
;                     for (int n = 0; n < 2; ++n) acc[a][b][m][n] = (f32x4){0.f, 0.f, 0.f, 0.f};
;         cur = nxt; cA = nA; cB = nB; ++ui;
;         if constexpr (ALIGN_EPI) { if (wr == 1) PG8_BAR; }
	v_pk_fma_f32 v[10:11], v[10:11], 0.5, v[182:183] op_sel_hi:[1,0,1]
	v_pk_fma_f32 v[8:9], v[8:9], 0.5, v[180:181] op_sel_hi:[1,0,1]
	v_pk_mul_f32 v[216:217], v[72:73], v[8:9]
	v_pk_mul_f32 v[218:219], v[74:75], v[10:11]
	v_mul_f32_e32 v232, v8, v8
	v_add_u32_e32 v216, 0x8000, v216
	v_add_u32_e32 v217, 0x8000, v217
	v_add_u32_e32 v218, 0x8000, v218
	v_add_u32_e32 v219, 0x8000, v219
	v_fmac_f32_e32 v232, v9, v9
	v_fmac_f32_e32 v232, v10, v10
	v_fmac_f32_e32 v232, v11, v11
	v_perm_b32 v224, v217, v216, s50
	v_perm_b32 v225, v219, v218, s50
	global_store_dwordx2 v[200:201], v[224:225], off
	v_pk_fma_f32 v[2:3], v[2:3], 0.5, v[186:187] op_sel_hi:[1,0,1]
	v_pk_fma_f32 v[0:1], v[0:1], 0.5, v[184:185] op_sel_hi:[1,0,1]
	v_pk_mul_f32 v[220:221], v[84:85], v[0:1]
	v_pk_mul_f32 v[222:223], v[86:87], v[2:3]
	v_fmac_f32_e32 v232, v0, v0
	v_add_u32_e32 v220, 0x8000, v220
	v_add_u32_e32 v221, 0x8000, v221
	v_add_u32_e32 v222, 0x8000, v222
	v_add_u32_e32 v223, 0x8000, v223
	v_fmac_f32_e32 v232, v1, v1
	v_fmac_f32_e32 v232, v2, v2
	v_fmac_f32_e32 v232, v3, v3
	v_perm_b32 v226, v221, v220, s50
	v_perm_b32 v227, v223, v222, s50
	global_store_dwordx2 v[200:201], v[226:227], off offset:256
	v_pk_fma_f32 v[14:15], v[14:15], 0.5, v[190:191] op_sel_hi:[1,0,1]
	v_pk_fma_f32 v[12:13], v[12:13], 0.5, v[188:189] op_sel_hi:[1,0,1]
	v_pk_mul_f32 v[216:217], v[88:89], v[12:13]
	v_pk_mul_f32 v[218:219], v[90:91], v[14:15]
	v_mul_f32_e32 v233, v12, v12
	v_add_u32_e32 v216, 0x8000, v216
	v_add_u32_e32 v217, 0x8000, v217
	v_add_u32_e32 v218, 0x8000, v218
	v_add_u32_e32 v219, 0x8000, v219
	v_fmac_f32_e32 v233, v13, v13
	v_fmac_f32_e32 v233, v14, v14
	v_fmac_f32_e32 v233, v15, v15
	v_perm_b32 v224, v217, v216, s50
	v_perm_b32 v225, v219, v218, s50
	global_store_dwordx2 v[202:203], v[224:225], off
	v_pk_fma_f32 v[6:7], v[6:7], 0.5, v[194:195] op_sel_hi:[1,0,1]
	v_pk_fma_f32 v[4:5], v[4:5], 0.5, v[192:193] op_sel_hi:[1,0,1]
	v_pk_mul_f32 v[220:221], v[96:97], v[4:5]
	v_pk_mul_f32 v[222:223], v[98:99], v[6:7]
	v_fmac_f32_e32 v233, v4, v4
	v_add_u32_e32 v220, 0x8000, v220
	v_add_u32_e32 v221, 0x8000, v221
	v_add_u32_e32 v222, 0x8000, v222
	v_add_u32_e32 v223, 0x8000, v223
	v_fmac_f32_e32 v233, v5, v5
	v_fmac_f32_e32 v233, v6, v6
	v_fmac_f32_e32 v233, v7, v7
	v_perm_b32 v226, v221, v220, s50
	v_perm_b32 v227, v223, v222, s50
	global_store_dwordx2 v[202:203], v[226:227], off offset:256
	s_nop 1
	v_mov_b32_dpp v236, v232 row_ror:8 row_mask:0xf bank_mask:0xf
	v_mov_b32_dpp v237, v233 row_ror:8 row_mask:0xf bank_mask:0xf
	v_add_f32_e32 v232, v232, v236
	v_add_f32_e32 v233, v233, v237
	v_cndmask_b32_e64 v232, v233, v232, s[24:25]
	s_nop 0
	ds_bpermute_b32 v236, v234, v232
	s_waitcnt lgkmcnt(0)
	v_add_f32_e32 v232, v232, v236
	s_nop 0
	ds_bpermute_b32 v237, v235, v232
	s_waitcnt lgkmcnt(0)
	v_add_f32_e32 v232, v232, v237
	s_mov_b64 exec, s[0:1]
	global_atomic_add_f32 v[204:205], v232, off
	s_mov_b64 exec, -1
	s_and_b64 vcc, exec, s[6:7]
	s_mov_b64 s[6:7], -1
	s_cbranch_vccnz .LBB0_1371
	s_andn2_b64 vcc, exec, s[12:13]
	s_cbranch_vccnz .LBB0_1370
	s_barrier
	s_branch .LBB0_1370
